# de-serialized GEMM epilogues: hoisted ss loads (Epi0/Epi2), software-pipelined residual epilogues
# speedup vs baseline: 1.0263x; 1.0263x over previous
.LBB0_147:
	ds_read_b128 v[144:147], v165
	v_xor_b32_e32 v177, 64, v165
	ds_read_b128 v[148:151], v177
	ds_read_b128 v[170:173], v165 offset:2048
	ds_read_b128 v[174:177], v177 offset:2048
	s_add_u32 s18, s16, 0xfff80080
	s_addc_u32 s19, s17, -1
	s_cmp_eq_u32 s47, 28
	s_cselect_b32 s21, s11, s19
	s_cselect_b32 s20, s41, s18
	s_cselect_b32 s19, s9, s46
	s_cselect_b32 s18, s44, s45
	v_lshl_add_u64 v[210:211], s[16:17], 0, v[136:137]
	s_add_i32 m0, s1, 0xc000
	ds_read_b128 v[178:181], v166
	v_xor_b32_e32 v209, 64, v166
	ds_read_b128 v[182:185], v209
	ds_read_b128 v[186:189], v166 offset:2048
	ds_read_b128 v[190:193], v209 offset:2048
	ds_read_b128 v[194:197], v166 offset:4096
	ds_read_b128 v[198:201], v209 offset:4096
	ds_read_b128 v[202:205], v166 offset:6144
	ds_read_b128 v[206:209], v209 offset:6144
	global_load_lds_dwordx4 v[210:211], off
	v_lshl_add_u64 v[210:211], s[16:17], 0, v[138:139]
	s_add_i32 m0, s1, 0xe000
	s_nop 0
	global_load_lds_dwordx4 v[210:211], off
	s_waitcnt lgkmcnt(8)
	s_barrier
	s_waitcnt lgkmcnt(0)
	s_setprio 1
	s_waitcnt lgkmcnt(0)
	v_mfma_f32_16x16x32_bf16 v[124:127], v[144:147], v[178:181], v[124:127]
	v_mfma_f32_16x16x32_bf16 v[120:123], v[170:173], v[178:181], v[120:123]
	v_mfma_f32_16x16x32_bf16 v[108:111], v[144:147], v[186:189], v[108:111]
	v_mfma_f32_16x16x32_bf16 v[104:107], v[170:173], v[186:189], v[104:107]
	v_mfma_f32_16x16x32_bf16 v[92:95], v[144:147], v[194:197], v[92:95]
	v_mfma_f32_16x16x32_bf16 v[88:91], v[170:173], v[194:197], v[88:91]
	v_mfma_f32_16x16x32_bf16 v[76:79], v[144:147], v[202:205], v[76:79]
	v_mfma_f32_16x16x32_bf16 v[72:75], v[170:173], v[202:205], v[72:75]
	v_mfma_f32_16x16x32_bf16 v[124:127], v[148:151], v[182:185], v[124:127]
	v_mfma_f32_16x16x32_bf16 v[120:123], v[174:177], v[182:185], v[120:123]
	v_mfma_f32_16x16x32_bf16 v[108:111], v[148:151], v[190:193], v[108:111]
	v_mfma_f32_16x16x32_bf16 v[104:107], v[174:177], v[190:193], v[104:107]
	v_mfma_f32_16x16x32_bf16 v[92:95], v[148:151], v[198:201], v[92:95]
	v_mfma_f32_16x16x32_bf16 v[88:91], v[174:177], v[198:201], v[88:91]
	v_mfma_f32_16x16x32_bf16 v[76:79], v[148:151], v[206:209], v[76:79]
	v_mfma_f32_16x16x32_bf16 v[72:75], v[174:177], v[206:209], v[72:75]
	s_setprio 0
	s_barrier
	s_add_i32 s48, s35, s24
	v_lshl_add_u64 v[220:221], s[18:19], 0, v[132:133]
	s_mov_b32 m0, s48
	ds_read_b128 v[210:213], v167
	v_xor_b32_e32 v233, 64, v167
	ds_read_b128 v[214:217], v233
	ds_read_b128 v[226:229], v167 offset:2048
	ds_read_b128 v[230:233], v233 offset:2048
	global_load_lds_dwordx4 v[220:221], off
	v_lshl_add_u64 v[234:235], s[18:19], 0, v[128:129]
	s_add_i32 m0, s48, 0x2000
	s_nop 0
	global_load_lds_dwordx4 v[234:235], off
	s_barrier
	s_waitcnt lgkmcnt(0)
	s_setprio 1
	s_waitcnt lgkmcnt(0)
	v_mfma_f32_16x16x32_bf16 v[116:119], v[210:213], v[178:181], v[116:119]
	v_mfma_f32_16x16x32_bf16 v[112:115], v[226:229], v[178:181], v[112:115]
	v_mfma_f32_16x16x32_bf16 v[100:103], v[210:213], v[186:189], v[100:103]
	v_mfma_f32_16x16x32_bf16 v[96:99], v[226:229], v[186:189], v[96:99]
	v_mfma_f32_16x16x32_bf16 v[84:87], v[210:213], v[194:197], v[84:87]
	v_mfma_f32_16x16x32_bf16 v[80:83], v[226:229], v[194:197], v[80:83]
	v_mfma_f32_16x16x32_bf16 v[68:71], v[210:213], v[202:205], v[68:71]
	v_mfma_f32_16x16x32_bf16 v[64:67], v[226:229], v[202:205], v[64:67]
	v_mfma_f32_16x16x32_bf16 v[116:119], v[214:217], v[182:185], v[116:119]
	v_mfma_f32_16x16x32_bf16 v[112:115], v[230:233], v[182:185], v[112:115]
	v_mfma_f32_16x16x32_bf16 v[100:103], v[214:217], v[190:193], v[100:103]
	v_mfma_f32_16x16x32_bf16 v[96:99], v[230:233], v[190:193], v[96:99]
	v_mfma_f32_16x16x32_bf16 v[84:87], v[214:217], v[198:201], v[84:87]
	v_mfma_f32_16x16x32_bf16 v[80:83], v[230:233], v[198:201], v[80:83]
	v_mfma_f32_16x16x32_bf16 v[68:71], v[214:217], v[206:209], v[68:71]
	v_mfma_f32_16x16x32_bf16 v[64:67], v[230:233], v[206:209], v[64:67]
	s_setprio 0
	s_mov_b32 m0, s1
	v_lshl_add_u64 v[236:237], s[20:21], 0, v[134:135]
	s_barrier
	ds_read_b128 v[178:181], v166 offset:16384
	v_xor_b32_e32 v209, 64, v166
	ds_read_b128 v[182:185], v209 offset:16384
	ds_read_b128 v[186:189], v166 offset:18432
	ds_read_b128 v[190:193], v209 offset:18432
	ds_read_b128 v[194:197], v166 offset:20480
	ds_read_b128 v[198:201], v209 offset:20480
	ds_read_b128 v[202:205], v166 offset:22528
	ds_read_b128 v[206:209], v209 offset:22528
	global_load_lds_dwordx4 v[236:237], off
	v_lshl_add_u64 v[240:241], s[20:21], 0, v[130:131]
	s_mov_b32 m0, s26
	s_nop 0
	global_load_lds_dwordx4 v[240:241], off
	s_barrier
	s_waitcnt lgkmcnt(0)
	s_setprio 1
	s_waitcnt lgkmcnt(0)
	v_mfma_f32_16x16x32_bf16 v[60:63], v[144:147], v[178:181], v[60:63]
	v_mfma_f32_16x16x32_bf16 v[56:59], v[170:173], v[178:181], v[56:59]
	v_mfma_f32_16x16x32_bf16 v[44:47], v[144:147], v[186:189], v[44:47]
	v_mfma_f32_16x16x32_bf16 v[40:43], v[170:173], v[186:189], v[40:43]
	v_mfma_f32_16x16x32_bf16 v[28:31], v[144:147], v[194:197], v[28:31]
	v_mfma_f32_16x16x32_bf16 v[24:27], v[170:173], v[194:197], v[24:27]
	v_mfma_f32_16x16x32_bf16 v[12:15], v[144:147], v[202:205], v[12:15]
	v_mfma_f32_16x16x32_bf16 v[8:11], v[170:173], v[202:205], v[8:11]
	v_mfma_f32_16x16x32_bf16 v[60:63], v[148:151], v[182:185], v[60:63]
	v_mfma_f32_16x16x32_bf16 v[56:59], v[174:177], v[182:185], v[56:59]
	v_mfma_f32_16x16x32_bf16 v[44:47], v[148:151], v[190:193], v[44:47]
	v_mfma_f32_16x16x32_bf16 v[40:43], v[174:177], v[190:193], v[40:43]
	v_mfma_f32_16x16x32_bf16 v[28:31], v[148:151], v[198:201], v[28:31]
	v_mfma_f32_16x16x32_bf16 v[24:27], v[174:177], v[198:201], v[24:27]
	v_mfma_f32_16x16x32_bf16 v[12:15], v[148:151], v[206:209], v[12:15]
	v_mfma_f32_16x16x32_bf16 v[8:11], v[174:177], v[206:209], v[8:11]
	s_setprio 0
	s_barrier
	s_add_u32 s48, s18, 0x80000
	s_addc_u32 s49, s19, 0
	s_add_i32 s52, s38, s24
	v_lshl_add_u64 v[144:145], s[48:49], 0, v[132:133]
	s_mov_b32 m0, s52
	s_nop 0
	global_load_lds_dwordx4 v[144:145], off
	v_lshl_add_u64 v[144:145], s[48:49], 0, v[128:129]
	s_add_i32 m0, s52, 0x2000
	s_nop 0
	global_load_lds_dwordx4 v[144:145], off
	s_waitcnt vmcnt(6)
	s_barrier
	s_setprio 1
	v_mfma_f32_16x16x32_bf16 v[52:55], v[210:213], v[178:181], v[52:55]
	v_mfma_f32_16x16x32_bf16 v[48:51], v[226:229], v[178:181], v[48:51]
	v_mfma_f32_16x16x32_bf16 v[36:39], v[210:213], v[186:189], v[36:39]
	v_mfma_f32_16x16x32_bf16 v[32:35], v[226:229], v[186:189], v[32:35]
	v_mfma_f32_16x16x32_bf16 v[20:23], v[210:213], v[194:197], v[20:23]
	v_mfma_f32_16x16x32_bf16 v[16:19], v[226:229], v[194:197], v[16:19]
	v_mfma_f32_16x16x32_bf16 v[4:7], v[210:213], v[202:205], v[4:7]
	v_mfma_f32_16x16x32_bf16 v[0:3], v[226:229], v[202:205], v[0:3]
	v_mfma_f32_16x16x32_bf16 v[52:55], v[214:217], v[182:185], v[52:55]
	v_mfma_f32_16x16x32_bf16 v[48:51], v[230:233], v[182:185], v[48:51]
	v_mfma_f32_16x16x32_bf16 v[36:39], v[214:217], v[190:193], v[36:39]
	v_mfma_f32_16x16x32_bf16 v[32:35], v[230:233], v[190:193], v[32:35]
	v_mfma_f32_16x16x32_bf16 v[20:23], v[214:217], v[198:201], v[20:23]
	v_mfma_f32_16x16x32_bf16 v[16:19], v[230:233], v[198:201], v[16:19]
	v_mfma_f32_16x16x32_bf16 v[4:7], v[214:217], v[206:209], v[4:7]
	v_mfma_f32_16x16x32_bf16 v[0:3], v[230:233], v[206:209], v[0:3]
	s_setprio 0
	s_add_i32 s48, 0, 0x18000
	v_add_u32_e32 v169, s48, v161
	s_barrier
	ds_read_b128 v[144:147], v169
	v_xor_b32_e32 v177, 64, v169
	ds_read_b128 v[148:151], v177
	ds_read_b128 v[170:173], v169 offset:2048
	ds_read_b128 v[174:177], v177 offset:2048
	s_add_u32 s20, s20, 0x80000
	s_addc_u32 s21, s21, 0
	s_mov_b32 m0, s27
	v_lshl_add_u64 v[210:211], s[20:21], 0, v[134:135]
	ds_read_b128 v[178:181], v166 offset:32768
	v_xor_b32_e32 v209, 64, v166
	ds_read_b128 v[182:185], v209 offset:32768
	ds_read_b128 v[186:189], v166 offset:34816
	ds_read_b128 v[190:193], v209 offset:34816
	ds_read_b128 v[194:197], v166 offset:36864
	ds_read_b128 v[198:201], v209 offset:36864
	ds_read_b128 v[202:205], v166 offset:38912
	ds_read_b128 v[206:209], v209 offset:38912
	global_load_lds_dwordx4 v[210:211], off
	v_lshl_add_u64 v[210:211], s[20:21], 0, v[130:131]
	s_mov_b32 m0, s28
	s_nop 0
	global_load_lds_dwordx4 v[210:211], off
	s_waitcnt lgkmcnt(8)
	s_barrier
	s_waitcnt lgkmcnt(0)
	s_setprio 1
	s_waitcnt lgkmcnt(0)
	v_mfma_f32_16x16x32_bf16 v[124:127], v[144:147], v[178:181], v[124:127]
	v_mfma_f32_16x16x32_bf16 v[120:123], v[170:173], v[178:181], v[120:123]
	v_mfma_f32_16x16x32_bf16 v[108:111], v[144:147], v[186:189], v[108:111]
	v_mfma_f32_16x16x32_bf16 v[104:107], v[170:173], v[186:189], v[104:107]
	v_mfma_f32_16x16x32_bf16 v[92:95], v[144:147], v[194:197], v[92:95]
	v_mfma_f32_16x16x32_bf16 v[88:91], v[170:173], v[194:197], v[88:91]
	v_mfma_f32_16x16x32_bf16 v[76:79], v[144:147], v[202:205], v[76:79]
	v_mfma_f32_16x16x32_bf16 v[72:75], v[170:173], v[202:205], v[72:75]
	v_mfma_f32_16x16x32_bf16 v[124:127], v[148:151], v[182:185], v[124:127]
	v_mfma_f32_16x16x32_bf16 v[120:123], v[174:177], v[182:185], v[120:123]
	v_mfma_f32_16x16x32_bf16 v[108:111], v[148:151], v[190:193], v[108:111]
	v_mfma_f32_16x16x32_bf16 v[104:107], v[174:177], v[190:193], v[104:107]
	v_mfma_f32_16x16x32_bf16 v[92:95], v[148:151], v[198:201], v[92:95]
	v_mfma_f32_16x16x32_bf16 v[88:91], v[174:177], v[198:201], v[88:91]
	v_mfma_f32_16x16x32_bf16 v[76:79], v[148:151], v[206:209], v[76:79]
	v_mfma_f32_16x16x32_bf16 v[72:75], v[174:177], v[206:209], v[72:75]
	s_setprio 0
	s_barrier
	s_add_i32 s20, 0, 0x1c000
	s_add_i32 s21, s48, s24
	v_add_u32_e32 v169, s20, v161
	v_lshl_add_u64 v[220:221], v[220:221], 0, s[6:7]
	s_mov_b32 m0, s21
	ds_read_b128 v[210:213], v169
	v_xor_b32_e32 v233, 64, v169
	ds_read_b128 v[214:217], v233
	ds_read_b128 v[226:229], v169 offset:2048
	ds_read_b128 v[230:233], v233 offset:2048
	global_load_lds_dwordx4 v[220:221], off
	v_lshl_add_u64 v[220:221], v[234:235], 0, s[6:7]
	s_add_i32 m0, s21, 0x2000
	s_nop 0
	global_load_lds_dwordx4 v[220:221], off
	s_barrier
	s_waitcnt lgkmcnt(0)
	s_setprio 1
	s_waitcnt lgkmcnt(0)
	v_mfma_f32_16x16x32_bf16 v[116:119], v[210:213], v[178:181], v[116:119]
	v_mfma_f32_16x16x32_bf16 v[112:115], v[226:229], v[178:181], v[112:115]
	v_mfma_f32_16x16x32_bf16 v[100:103], v[210:213], v[186:189], v[100:103]
	v_mfma_f32_16x16x32_bf16 v[96:99], v[226:229], v[186:189], v[96:99]
	v_mfma_f32_16x16x32_bf16 v[84:87], v[210:213], v[194:197], v[84:87]
	v_mfma_f32_16x16x32_bf16 v[80:83], v[226:229], v[194:197], v[80:83]
	v_mfma_f32_16x16x32_bf16 v[68:71], v[210:213], v[202:205], v[68:71]
	v_mfma_f32_16x16x32_bf16 v[64:67], v[226:229], v[202:205], v[64:67]
	v_mfma_f32_16x16x32_bf16 v[116:119], v[214:217], v[182:185], v[116:119]
	v_mfma_f32_16x16x32_bf16 v[112:115], v[230:233], v[182:185], v[112:115]
	v_mfma_f32_16x16x32_bf16 v[100:103], v[214:217], v[190:193], v[100:103]
	v_mfma_f32_16x16x32_bf16 v[96:99], v[230:233], v[190:193], v[96:99]
	v_mfma_f32_16x16x32_bf16 v[84:87], v[214:217], v[198:201], v[84:87]
	v_mfma_f32_16x16x32_bf16 v[80:83], v[230:233], v[198:201], v[80:83]
	v_mfma_f32_16x16x32_bf16 v[68:71], v[214:217], v[206:209], v[68:71]
	v_mfma_f32_16x16x32_bf16 v[64:67], v[230:233], v[206:209], v[64:67]
	s_setprio 0
	s_mov_b32 m0, s30
	v_lshl_add_u64 v[220:221], v[236:237], 0, s[6:7]
	s_barrier
	ds_read_b128 v[178:181], v166 offset:49152
	v_xor_b32_e32 v209, 64, v166
	ds_read_b128 v[182:185], v209 offset:49152
	ds_read_b128 v[186:189], v166 offset:51200
	ds_read_b128 v[190:193], v209 offset:51200
	ds_read_b128 v[194:197], v166 offset:53248
	ds_read_b128 v[198:201], v209 offset:53248
	ds_read_b128 v[202:205], v166 offset:55296
	ds_read_b128 v[206:209], v209 offset:55296
	global_load_lds_dwordx4 v[220:221], off
	v_lshl_add_u64 v[220:221], v[240:241], 0, s[6:7]
	s_mov_b32 m0, s31
	s_nop 0
	global_load_lds_dwordx4 v[220:221], off
	s_barrier
	s_waitcnt lgkmcnt(0)
	s_setprio 1
	s_waitcnt lgkmcnt(0)
	v_mfma_f32_16x16x32_bf16 v[60:63], v[144:147], v[178:181], v[60:63]
	v_mfma_f32_16x16x32_bf16 v[56:59], v[170:173], v[178:181], v[56:59]
	v_mfma_f32_16x16x32_bf16 v[44:47], v[144:147], v[186:189], v[44:47]
	v_mfma_f32_16x16x32_bf16 v[40:43], v[170:173], v[186:189], v[40:43]
	v_mfma_f32_16x16x32_bf16 v[28:31], v[144:147], v[194:197], v[28:31]
	v_mfma_f32_16x16x32_bf16 v[24:27], v[170:173], v[194:197], v[24:27]
	v_mfma_f32_16x16x32_bf16 v[12:15], v[144:147], v[202:205], v[12:15]
	v_mfma_f32_16x16x32_bf16 v[8:11], v[170:173], v[202:205], v[8:11]
	v_mfma_f32_16x16x32_bf16 v[60:63], v[148:151], v[182:185], v[60:63]
	v_mfma_f32_16x16x32_bf16 v[56:59], v[174:177], v[182:185], v[56:59]
	v_mfma_f32_16x16x32_bf16 v[44:47], v[148:151], v[190:193], v[44:47]
	v_mfma_f32_16x16x32_bf16 v[40:43], v[174:177], v[190:193], v[40:43]
	v_mfma_f32_16x16x32_bf16 v[28:31], v[148:151], v[198:201], v[28:31]
	v_mfma_f32_16x16x32_bf16 v[24:27], v[174:177], v[198:201], v[24:27]
	v_mfma_f32_16x16x32_bf16 v[12:15], v[148:151], v[206:209], v[12:15]
	v_mfma_f32_16x16x32_bf16 v[8:11], v[174:177], v[206:209], v[8:11]
	s_setprio 0
	s_barrier
	s_add_u32 s18, s18, 0x80080
	s_addc_u32 s19, s19, 0
	s_add_i32 s20, s20, s24
	v_lshl_add_u64 v[144:145], s[18:19], 0, v[132:133]
	s_mov_b32 m0, s20
	s_nop 0
	global_load_lds_dwordx4 v[144:145], off
	v_lshl_add_u64 v[144:145], s[18:19], 0, v[128:129]
	s_add_i32 m0, s20, 0x2000
	s_nop 0
	global_load_lds_dwordx4 v[144:145], off
	s_waitcnt vmcnt(6)
	s_barrier
	s_setprio 1
	v_mfma_f32_16x16x32_bf16 v[52:55], v[210:213], v[178:181], v[52:55]
	v_mfma_f32_16x16x32_bf16 v[48:51], v[226:229], v[178:181], v[48:51]
	v_mfma_f32_16x16x32_bf16 v[36:39], v[210:213], v[186:189], v[36:39]
	v_mfma_f32_16x16x32_bf16 v[32:35], v[226:229], v[186:189], v[32:35]
	v_mfma_f32_16x16x32_bf16 v[20:23], v[210:213], v[194:197], v[20:23]
	v_mfma_f32_16x16x32_bf16 v[16:19], v[226:229], v[194:197], v[16:19]
	v_mfma_f32_16x16x32_bf16 v[4:7], v[210:213], v[202:205], v[4:7]
	v_mfma_f32_16x16x32_bf16 v[0:3], v[226:229], v[202:205], v[0:3]
	v_mfma_f32_16x16x32_bf16 v[52:55], v[214:217], v[182:185], v[52:55]
	v_mfma_f32_16x16x32_bf16 v[48:51], v[230:233], v[182:185], v[48:51]
	v_mfma_f32_16x16x32_bf16 v[36:39], v[214:217], v[190:193], v[36:39]
	v_mfma_f32_16x16x32_bf16 v[32:35], v[230:233], v[190:193], v[32:35]
	v_mfma_f32_16x16x32_bf16 v[20:23], v[214:217], v[198:201], v[20:23]
	v_mfma_f32_16x16x32_bf16 v[16:19], v[230:233], v[198:201], v[16:19]
	v_mfma_f32_16x16x32_bf16 v[4:7], v[214:217], v[206:209], v[4:7]
	v_mfma_f32_16x16x32_bf16 v[0:3], v[230:233], v[206:209], v[0:3]
	s_setprio 0
	s_add_i32 s47, s47, 2
	s_add_u32 s16, s16, 0x100
	s_addc_u32 s17, s17, 0
	s_add_u32 s45, s45, 0x100
	s_addc_u32 s46, s46, 0
	s_cmp_gt_u32 s47, 29
	s_barrier
	s_cbranch_scc0 .LBB0_147
	v_lshl_add_u32 v144, s0, 8, v160
	v_ashrrev_i32_e32 v145, 31, v144
	v_lshl_add_u64 v[150:151], v[144:145], 2, s[92:93]
	global_load_dword v176, v[150:151], off
	global_load_dword v177, v[150:151], off offset:64
	global_load_dword v178, v[150:151], off offset:128
	global_load_dword v179, v[150:151], off offset:192
	global_load_dword v180, v[150:151], off offset:512
	global_load_dword v181, v[150:151], off offset:576
	global_load_dword v182, v[150:151], off offset:640
	global_load_dword v183, v[150:151], off offset:704
	v_lshl_or_b32 v148, s40, 8, v164
	v_mov_b64_e32 v[146:147], s[96:97]
	v_ashrrev_i32_e32 v149, 31, v148
	v_mad_i64_i32 v[172:173], s[16:17], v144, s39, v[146:147]
	v_lshlrev_b64 v[148:149], 1, v[148:149]
	v_lshl_add_u64 v[172:173], v[172:173], 0, v[148:149]
	s_and_b64 vcc, exec, s[4:5]
	s_mov_b32 s40, s8
	s_mov_b32 s0, s10
	s_mov_b64 s[18:19], s[14:15]
	s_waitcnt vmcnt(0)
	v_fmamk_f32 v145, v176, 0x3a000000, v168
	v_rsq_f32_e32 v170, v145
	s_nop 0
	v_pk_mul_f32 v[126:127], v[126:127], v[170:171] op_sel_hi:[1,0]
	v_pk_mul_f32 v[124:125], v[124:125], v[170:171] op_sel_hi:[1,0]
	v_pk_mul_f32 v[122:123], v[122:123], v[170:171] op_sel_hi:[1,0]
	v_pk_mul_f32 v[120:121], v[120:121], v[170:171] op_sel_hi:[1,0]
	v_pk_mul_f32 v[118:119], v[118:119], v[170:171] op_sel_hi:[1,0]
	v_pk_mul_f32 v[116:117], v[116:117], v[170:171] op_sel_hi:[1,0]
	v_pk_mul_f32 v[174:175], v[114:115], v[170:171] op_sel_hi:[1,0]
	v_pk_mul_f32 v[170:171], v[112:113], v[170:171] op_sel_hi:[1,0]
	v_cvt_pk_bf16_f32 v112, v124, v125
	v_cvt_pk_bf16_f32 v113, v126, v127
	v_cvt_pk_bf16_f32 v114, v120, v121
	v_cvt_pk_bf16_f32 v115, v122, v123
	global_store_dwordx4 v[172:173], v[112:115], off
	s_nop 1
	v_cvt_pk_bf16_f32 v112, v116, v117
	v_cvt_pk_bf16_f32 v113, v118, v119
	v_cvt_pk_bf16_f32 v114, v170, v171
	v_cvt_pk_bf16_f32 v115, v174, v175
	global_store_dwordx4 v[172:173], v[112:115], off offset:256
	s_nop 0
	s_nop 0
	v_or_b32_e32 v113, 16, v144
	v_mad_i64_i32 v[114:115], s[16:17], v113, s39, v[146:147]
	v_lshl_add_u64 v[114:115], v[114:115], 0, v[148:149]
	s_nop 0
	v_fmamk_f32 v112, v177, 0x3a000000, v168
	v_rsq_f32_e32 v112, v112
	s_nop 0
	v_pk_mul_f32 v[110:111], v[110:111], v[112:113] op_sel_hi:[1,0]
	v_pk_mul_f32 v[108:109], v[108:109], v[112:113] op_sel_hi:[1,0]
	v_pk_mul_f32 v[106:107], v[106:107], v[112:113] op_sel_hi:[1,0]
	v_pk_mul_f32 v[104:105], v[104:105], v[112:113] op_sel_hi:[1,0]
	v_pk_mul_f32 v[102:103], v[102:103], v[112:113] op_sel_hi:[1,0]
	v_pk_mul_f32 v[100:101], v[100:101], v[112:113] op_sel_hi:[1,0]
	v_pk_mul_f32 v[116:117], v[98:99], v[112:113] op_sel_hi:[1,0]
	v_pk_mul_f32 v[112:113], v[96:97], v[112:113] op_sel_hi:[1,0]
	v_cvt_pk_bf16_f32 v96, v108, v109
	v_cvt_pk_bf16_f32 v97, v110, v111
	v_cvt_pk_bf16_f32 v98, v104, v105
	v_cvt_pk_bf16_f32 v99, v106, v107
	global_store_dwordx4 v[114:115], v[96:99], off
	s_nop 1
	v_cvt_pk_bf16_f32 v96, v100, v101
	v_cvt_pk_bf16_f32 v97, v102, v103
	v_cvt_pk_bf16_f32 v98, v112, v113
	v_cvt_pk_bf16_f32 v99, v116, v117
	global_store_dwordx4 v[114:115], v[96:99], off offset:256
	s_nop 0
	s_nop 0
	v_or_b32_e32 v97, 32, v144
	v_mad_i64_i32 v[98:99], s[16:17], v97, s39, v[146:147]
	v_lshl_add_u64 v[98:99], v[98:99], 0, v[148:149]
	s_nop 0
	v_fmamk_f32 v96, v178, 0x3a000000, v168
	v_rsq_f32_e32 v96, v96
	s_nop 0
	v_pk_mul_f32 v[94:95], v[94:95], v[96:97] op_sel_hi:[1,0]
	v_pk_mul_f32 v[92:93], v[92:93], v[96:97] op_sel_hi:[1,0]
	v_pk_mul_f32 v[90:91], v[90:91], v[96:97] op_sel_hi:[1,0]
	v_pk_mul_f32 v[88:89], v[88:89], v[96:97] op_sel_hi:[1,0]
	v_pk_mul_f32 v[86:87], v[86:87], v[96:97] op_sel_hi:[1,0]
	v_pk_mul_f32 v[84:85], v[84:85], v[96:97] op_sel_hi:[1,0]
	v_pk_mul_f32 v[100:101], v[82:83], v[96:97] op_sel_hi:[1,0]
	v_pk_mul_f32 v[96:97], v[80:81], v[96:97] op_sel_hi:[1,0]
	v_cvt_pk_bf16_f32 v80, v92, v93
	v_cvt_pk_bf16_f32 v81, v94, v95
	v_cvt_pk_bf16_f32 v82, v88, v89
	v_cvt_pk_bf16_f32 v83, v90, v91
	global_store_dwordx4 v[98:99], v[80:83], off
	s_nop 1
	v_cvt_pk_bf16_f32 v80, v84, v85
	v_cvt_pk_bf16_f32 v81, v86, v87
	v_cvt_pk_bf16_f32 v82, v96, v97
	v_cvt_pk_bf16_f32 v83, v100, v101
	global_store_dwordx4 v[98:99], v[80:83], off offset:256
	s_nop 0
	s_nop 0
	v_or_b32_e32 v81, 48, v144
	v_mad_i64_i32 v[82:83], s[16:17], v81, s39, v[146:147]
	v_lshl_add_u64 v[82:83], v[82:83], 0, v[148:149]
	s_nop 0
	v_fmamk_f32 v80, v179, 0x3a000000, v168
	v_rsq_f32_e32 v80, v80
	s_nop 0
	v_pk_mul_f32 v[78:79], v[78:79], v[80:81] op_sel_hi:[1,0]
	v_pk_mul_f32 v[76:77], v[76:77], v[80:81] op_sel_hi:[1,0]
	v_pk_mul_f32 v[74:75], v[74:75], v[80:81] op_sel_hi:[1,0]
	v_pk_mul_f32 v[72:73], v[72:73], v[80:81] op_sel_hi:[1,0]
	v_pk_mul_f32 v[70:71], v[70:71], v[80:81] op_sel_hi:[1,0]
	v_pk_mul_f32 v[68:69], v[68:69], v[80:81] op_sel_hi:[1,0]
	v_pk_mul_f32 v[84:85], v[66:67], v[80:81] op_sel_hi:[1,0]
	v_pk_mul_f32 v[80:81], v[64:65], v[80:81] op_sel_hi:[1,0]
	v_cvt_pk_bf16_f32 v64, v76, v77
	v_cvt_pk_bf16_f32 v65, v78, v79
	v_cvt_pk_bf16_f32 v66, v72, v73
	v_cvt_pk_bf16_f32 v67, v74, v75
	global_store_dwordx4 v[82:83], v[64:67], off
	s_nop 1
	v_cvt_pk_bf16_f32 v64, v68, v69
	v_cvt_pk_bf16_f32 v65, v70, v71
	v_cvt_pk_bf16_f32 v66, v80, v81
	v_cvt_pk_bf16_f32 v67, v84, v85
	global_store_dwordx4 v[82:83], v[64:67], off offset:256
	s_nop 0
	s_nop 0
	v_add_u32_e32 v65, 0x80, v144
	v_mad_i64_i32 v[66:67], s[16:17], v65, s39, v[146:147]
	v_lshl_add_u64 v[66:67], v[66:67], 0, v[148:149]
	s_nop 0
	v_fmamk_f32 v64, v180, 0x3a000000, v168
	v_rsq_f32_e32 v64, v64
	s_nop 0
	v_pk_mul_f32 v[62:63], v[62:63], v[64:65] op_sel_hi:[1,0]
	v_pk_mul_f32 v[60:61], v[60:61], v[64:65] op_sel_hi:[1,0]
	v_pk_mul_f32 v[58:59], v[58:59], v[64:65] op_sel_hi:[1,0]
	v_pk_mul_f32 v[56:57], v[56:57], v[64:65] op_sel_hi:[1,0]
	v_pk_mul_f32 v[54:55], v[54:55], v[64:65] op_sel_hi:[1,0]
	v_pk_mul_f32 v[52:53], v[52:53], v[64:65] op_sel_hi:[1,0]
	v_pk_mul_f32 v[68:69], v[50:51], v[64:65] op_sel_hi:[1,0]
	v_pk_mul_f32 v[64:65], v[48:49], v[64:65] op_sel_hi:[1,0]
	v_cvt_pk_bf16_f32 v48, v60, v61
	v_cvt_pk_bf16_f32 v49, v62, v63
	v_cvt_pk_bf16_f32 v50, v56, v57
	v_cvt_pk_bf16_f32 v51, v58, v59
	global_store_dwordx4 v[66:67], v[48:51], off
	s_nop 1
	v_cvt_pk_bf16_f32 v48, v52, v53
	v_cvt_pk_bf16_f32 v49, v54, v55
	v_cvt_pk_bf16_f32 v50, v64, v65
	v_cvt_pk_bf16_f32 v51, v68, v69
	global_store_dwordx4 v[66:67], v[48:51], off offset:256
	s_nop 0
	s_nop 0
	v_add_u32_e32 v49, 0x90, v144
	v_mad_i64_i32 v[50:51], s[16:17], v49, s39, v[146:147]
	v_lshl_add_u64 v[50:51], v[50:51], 0, v[148:149]
	s_nop 0
	v_fmamk_f32 v48, v181, 0x3a000000, v168
	v_rsq_f32_e32 v48, v48
	s_nop 0
	v_pk_mul_f32 v[46:47], v[46:47], v[48:49] op_sel_hi:[1,0]
	v_pk_mul_f32 v[44:45], v[44:45], v[48:49] op_sel_hi:[1,0]
	v_pk_mul_f32 v[42:43], v[42:43], v[48:49] op_sel_hi:[1,0]
	v_pk_mul_f32 v[40:41], v[40:41], v[48:49] op_sel_hi:[1,0]
	v_pk_mul_f32 v[38:39], v[38:39], v[48:49] op_sel_hi:[1,0]
	v_pk_mul_f32 v[36:37], v[36:37], v[48:49] op_sel_hi:[1,0]
	v_pk_mul_f32 v[52:53], v[34:35], v[48:49] op_sel_hi:[1,0]
	v_pk_mul_f32 v[48:49], v[32:33], v[48:49] op_sel_hi:[1,0]
	v_cvt_pk_bf16_f32 v32, v44, v45
	v_cvt_pk_bf16_f32 v33, v46, v47
	v_cvt_pk_bf16_f32 v34, v40, v41
	v_cvt_pk_bf16_f32 v35, v42, v43
	global_store_dwordx4 v[50:51], v[32:35], off
	s_nop 1
	v_cvt_pk_bf16_f32 v32, v36, v37
	v_cvt_pk_bf16_f32 v33, v38, v39
	v_cvt_pk_bf16_f32 v34, v48, v49
	v_cvt_pk_bf16_f32 v35, v52, v53
	global_store_dwordx4 v[50:51], v[32:35], off offset:256
	s_nop 0
	s_nop 0
	v_add_u32_e32 v33, 0xa0, v144
	v_mad_i64_i32 v[34:35], s[16:17], v33, s39, v[146:147]
	v_lshl_add_u64 v[34:35], v[34:35], 0, v[148:149]
	s_mov_b64 s[16:17], s[12:13]
	s_nop 0
	v_fmamk_f32 v32, v182, 0x3a000000, v168
	v_rsq_f32_e32 v32, v32
	s_nop 0
	v_pk_mul_f32 v[30:31], v[30:31], v[32:33] op_sel_hi:[1,0]
	v_pk_mul_f32 v[28:29], v[28:29], v[32:33] op_sel_hi:[1,0]
	v_pk_mul_f32 v[26:27], v[26:27], v[32:33] op_sel_hi:[1,0]
	v_pk_mul_f32 v[24:25], v[24:25], v[32:33] op_sel_hi:[1,0]
	v_pk_mul_f32 v[22:23], v[22:23], v[32:33] op_sel_hi:[1,0]
	v_pk_mul_f32 v[20:21], v[20:21], v[32:33] op_sel_hi:[1,0]
	v_pk_mul_f32 v[36:37], v[18:19], v[32:33] op_sel_hi:[1,0]
	v_pk_mul_f32 v[32:33], v[16:17], v[32:33] op_sel_hi:[1,0]
	v_cvt_pk_bf16_f32 v16, v28, v29
	v_cvt_pk_bf16_f32 v17, v30, v31
	v_cvt_pk_bf16_f32 v18, v24, v25
	v_cvt_pk_bf16_f32 v19, v26, v27
	global_store_dwordx4 v[34:35], v[16:19], off
	s_nop 1
	v_cvt_pk_bf16_f32 v16, v20, v21
	v_cvt_pk_bf16_f32 v17, v22, v23
	v_cvt_pk_bf16_f32 v18, v32, v33
	v_cvt_pk_bf16_f32 v19, v36, v37
	global_store_dwordx4 v[34:35], v[16:19], off offset:256
	s_nop 0
	s_nop 0
	v_add_u32_e32 v17, 0xb0, v144
	v_mad_i64_i32 v[18:19], s[4:5], v17, s39, v[146:147]
	v_lshl_add_u64 v[18:19], v[18:19], 0, v[148:149]
	s_nop 0
	v_fmamk_f32 v16, v183, 0x3a000000, v168
	v_rsq_f32_e32 v16, v16
	s_nop 0
	v_pk_mul_f32 v[14:15], v[14:15], v[16:17] op_sel_hi:[1,0]
	v_pk_mul_f32 v[12:13], v[12:13], v[16:17] op_sel_hi:[1,0]
	v_pk_mul_f32 v[10:11], v[10:11], v[16:17] op_sel_hi:[1,0]
	v_pk_mul_f32 v[8:9], v[8:9], v[16:17] op_sel_hi:[1,0]
	v_pk_mul_f32 v[6:7], v[6:7], v[16:17] op_sel_hi:[1,0]
	v_pk_mul_f32 v[4:5], v[4:5], v[16:17] op_sel_hi:[1,0]
	v_pk_mul_f32 v[20:21], v[2:3], v[16:17] op_sel_hi:[1,0]
	v_pk_mul_f32 v[16:17], v[0:1], v[16:17] op_sel_hi:[1,0]
	v_cvt_pk_bf16_f32 v0, v12, v13
	v_cvt_pk_bf16_f32 v1, v14, v15
	v_cvt_pk_bf16_f32 v2, v8, v9
	v_cvt_pk_bf16_f32 v3, v10, v11
	global_store_dwordx4 v[18:19], v[0:3], off
	s_nop 1
	v_cvt_pk_bf16_f32 v0, v4, v5
	v_cvt_pk_bf16_f32 v1, v6, v7
	v_cvt_pk_bf16_f32 v2, v16, v17
	v_cvt_pk_bf16_f32 v3, v20, v21
	global_store_dwordx4 v[18:19], v[0:3], off offset:256
	s_cbranch_vccz .LBB0_144
	s_waitcnt vmcnt(0)
	s_cmpk_gt_u32 s3, 0xff
	s_cbranch_scc1 .LBB0_151
	s_barrier

.LBB0_283:
	ds_read_b128 v[140:143], v146
	v_xor_b32_e32 v171, 64, v146
	ds_read_b128 v[154:157], v171
	ds_read_b128 v[158:161], v146 offset:2048
	ds_read_b128 v[168:171], v171 offset:2048
	s_add_u32 s18, s6, 0xffe80080
	s_addc_u32 s19, s7, -1
	s_cmp_eq_u32 s45, 28
	s_cselect_b32 s21, s15, s19
	s_cselect_b32 s20, s14, s18
	s_cselect_b32 s19, s1, s44
	s_cselect_b32 s18, s11, s43
	v_lshl_add_u64 v[150:151], s[6:7], 0, v[132:133]
	s_add_i32 m0, s25, 0xc000
	ds_read_b128 v[172:175], v147
	v_xor_b32_e32 v203, 64, v147
	ds_read_b128 v[176:179], v203
	ds_read_b128 v[180:183], v147 offset:2048
	ds_read_b128 v[184:187], v203 offset:2048
	ds_read_b128 v[188:191], v147 offset:4096
	ds_read_b128 v[192:195], v203 offset:4096
	ds_read_b128 v[196:199], v147 offset:6144
	ds_read_b128 v[200:203], v203 offset:6144
	global_load_lds_dwordx4 v[150:151], off
	v_lshl_add_u64 v[150:151], s[6:7], 0, v[134:135]
	s_add_i32 m0, s25, 0xe000
	s_nop 0
	global_load_lds_dwordx4 v[150:151], off
	s_waitcnt lgkmcnt(8)
	s_barrier
	s_waitcnt lgkmcnt(0)
	s_setprio 1
	s_waitcnt lgkmcnt(0)
	v_mfma_f32_16x16x32_bf16 v[124:127], v[140:143], v[172:175], v[124:127]
	v_mfma_f32_16x16x32_bf16 v[120:123], v[158:161], v[172:175], v[120:123]
	v_mfma_f32_16x16x32_bf16 v[108:111], v[140:143], v[180:183], v[108:111]
	v_mfma_f32_16x16x32_bf16 v[104:107], v[158:161], v[180:183], v[104:107]
	v_mfma_f32_16x16x32_bf16 v[92:95], v[140:143], v[188:191], v[92:95]
	v_mfma_f32_16x16x32_bf16 v[88:91], v[158:161], v[188:191], v[88:91]
	v_mfma_f32_16x16x32_bf16 v[76:79], v[140:143], v[196:199], v[76:79]
	v_mfma_f32_16x16x32_bf16 v[72:75], v[158:161], v[196:199], v[72:75]
	v_mfma_f32_16x16x32_bf16 v[124:127], v[154:157], v[176:179], v[124:127]
	v_mfma_f32_16x16x32_bf16 v[120:123], v[168:171], v[176:179], v[120:123]
	v_mfma_f32_16x16x32_bf16 v[108:111], v[154:157], v[184:187], v[108:111]
	v_mfma_f32_16x16x32_bf16 v[104:107], v[168:171], v[184:187], v[104:107]
	v_mfma_f32_16x16x32_bf16 v[92:95], v[154:157], v[192:195], v[92:95]
	v_mfma_f32_16x16x32_bf16 v[88:91], v[168:171], v[192:195], v[88:91]
	v_mfma_f32_16x16x32_bf16 v[76:79], v[154:157], v[200:203], v[76:79]
	v_mfma_f32_16x16x32_bf16 v[72:75], v[168:171], v[200:203], v[72:75]
	s_setprio 0
	s_barrier
	s_add_i32 s46, s39, s24
	v_lshl_add_u64 v[150:151], s[18:19], 0, v[164:165]
	s_mov_b32 m0, s46
	ds_read_b128 v[204:207], v148
	v_xor_b32_e32 v245, 64, v148
	ds_read_b128 v[208:211], v245
	ds_read_b128 v[212:215], v148 offset:2048
	ds_read_b128 v[242:245], v245 offset:2048
	global_load_lds_dwordx4 v[150:151], off
	v_lshl_add_u64 v[216:217], s[18:19], 0, v[166:167]
	s_add_i32 m0, s46, 0x2000
	s_nop 0
	global_load_lds_dwordx4 v[216:217], off
	s_barrier
	s_waitcnt lgkmcnt(0)
	s_setprio 1
	s_waitcnt lgkmcnt(0)
	v_mfma_f32_16x16x32_bf16 v[116:119], v[204:207], v[172:175], v[116:119]
	v_mfma_f32_16x16x32_bf16 v[112:115], v[212:215], v[172:175], v[112:115]
	v_mfma_f32_16x16x32_bf16 v[100:103], v[204:207], v[180:183], v[100:103]
	v_mfma_f32_16x16x32_bf16 v[96:99], v[212:215], v[180:183], v[96:99]
	v_mfma_f32_16x16x32_bf16 v[84:87], v[204:207], v[188:191], v[84:87]
	v_mfma_f32_16x16x32_bf16 v[80:83], v[212:215], v[188:191], v[80:83]
	v_mfma_f32_16x16x32_bf16 v[68:71], v[204:207], v[196:199], v[68:71]
	v_mfma_f32_16x16x32_bf16 v[64:67], v[212:215], v[196:199], v[64:67]
	v_mfma_f32_16x16x32_bf16 v[116:119], v[208:211], v[176:179], v[116:119]
	v_mfma_f32_16x16x32_bf16 v[112:115], v[242:245], v[176:179], v[112:115]
	v_mfma_f32_16x16x32_bf16 v[100:103], v[208:211], v[184:187], v[100:103]
	v_mfma_f32_16x16x32_bf16 v[96:99], v[242:245], v[184:187], v[96:99]
	v_mfma_f32_16x16x32_bf16 v[84:87], v[208:211], v[192:195], v[84:87]
	v_mfma_f32_16x16x32_bf16 v[80:83], v[242:245], v[192:195], v[80:83]
	v_mfma_f32_16x16x32_bf16 v[68:71], v[208:211], v[200:203], v[68:71]
	v_mfma_f32_16x16x32_bf16 v[64:67], v[242:245], v[200:203], v[64:67]
	s_setprio 0
	s_mov_b32 m0, s25
	v_lshl_add_u64 v[220:221], s[20:21], 0, v[128:129]
	s_barrier
	ds_read_b128 v[172:175], v147 offset:16384
	v_xor_b32_e32 v203, 64, v147
	ds_read_b128 v[176:179], v203 offset:16384
	ds_read_b128 v[180:183], v147 offset:18432
	ds_read_b128 v[184:187], v203 offset:18432
	ds_read_b128 v[188:191], v147 offset:20480
	ds_read_b128 v[192:195], v203 offset:20480
	ds_read_b128 v[196:199], v147 offset:22528
	ds_read_b128 v[200:203], v203 offset:22528
	global_load_lds_dwordx4 v[220:221], off
	v_lshl_add_u64 v[230:231], s[20:21], 0, v[130:131]
	s_mov_b32 m0, s26
	s_nop 0
	global_load_lds_dwordx4 v[230:231], off
	s_barrier
	s_waitcnt lgkmcnt(0)
	s_setprio 1
	s_waitcnt lgkmcnt(0)
	v_mfma_f32_16x16x32_bf16 v[60:63], v[140:143], v[172:175], v[60:63]
	v_mfma_f32_16x16x32_bf16 v[56:59], v[158:161], v[172:175], v[56:59]
	v_mfma_f32_16x16x32_bf16 v[44:47], v[140:143], v[180:183], v[44:47]
	v_mfma_f32_16x16x32_bf16 v[40:43], v[158:161], v[180:183], v[40:43]
	v_mfma_f32_16x16x32_bf16 v[28:31], v[140:143], v[188:191], v[28:31]
	v_mfma_f32_16x16x32_bf16 v[24:27], v[158:161], v[188:191], v[24:27]
	v_mfma_f32_16x16x32_bf16 v[12:15], v[140:143], v[196:199], v[12:15]
	v_mfma_f32_16x16x32_bf16 v[8:11], v[158:161], v[196:199], v[8:11]
	v_mfma_f32_16x16x32_bf16 v[60:63], v[154:157], v[176:179], v[60:63]
	v_mfma_f32_16x16x32_bf16 v[56:59], v[168:171], v[176:179], v[56:59]
	v_mfma_f32_16x16x32_bf16 v[44:47], v[154:157], v[184:187], v[44:47]
	v_mfma_f32_16x16x32_bf16 v[40:43], v[168:171], v[184:187], v[40:43]
	v_mfma_f32_16x16x32_bf16 v[28:31], v[154:157], v[192:195], v[28:31]
	v_mfma_f32_16x16x32_bf16 v[24:27], v[168:171], v[192:195], v[24:27]
	v_mfma_f32_16x16x32_bf16 v[12:15], v[154:157], v[200:203], v[12:15]
	v_mfma_f32_16x16x32_bf16 v[8:11], v[168:171], v[200:203], v[8:11]
	s_setprio 0
	s_barrier
	s_add_u32 s46, s18, 0x80000
	s_addc_u32 s47, s19, 0
	s_add_i32 s48, s40, s24
	v_lshl_add_u64 v[140:141], s[46:47], 0, v[164:165]
	s_mov_b32 m0, s48
	s_nop 0
	global_load_lds_dwordx4 v[140:141], off
	v_lshl_add_u64 v[140:141], s[46:47], 0, v[166:167]
	s_add_i32 m0, s48, 0x2000
	s_nop 0
	global_load_lds_dwordx4 v[140:141], off
	s_waitcnt vmcnt(6)
	s_barrier
	s_setprio 1
	v_mfma_f32_16x16x32_bf16 v[52:55], v[204:207], v[172:175], v[52:55]
	v_mfma_f32_16x16x32_bf16 v[48:51], v[212:215], v[172:175], v[48:51]
	v_mfma_f32_16x16x32_bf16 v[36:39], v[204:207], v[180:183], v[36:39]
	v_mfma_f32_16x16x32_bf16 v[32:35], v[212:215], v[180:183], v[32:35]
	v_mfma_f32_16x16x32_bf16 v[20:23], v[204:207], v[188:191], v[20:23]
	v_mfma_f32_16x16x32_bf16 v[16:19], v[212:215], v[188:191], v[16:19]
	v_mfma_f32_16x16x32_bf16 v[4:7], v[204:207], v[196:199], v[4:7]
	v_mfma_f32_16x16x32_bf16 v[0:3], v[212:215], v[196:199], v[0:3]
	v_mfma_f32_16x16x32_bf16 v[52:55], v[208:211], v[176:179], v[52:55]
	v_mfma_f32_16x16x32_bf16 v[48:51], v[242:245], v[176:179], v[48:51]
	v_mfma_f32_16x16x32_bf16 v[36:39], v[208:211], v[184:187], v[36:39]
	v_mfma_f32_16x16x32_bf16 v[32:35], v[242:245], v[184:187], v[32:35]
	v_mfma_f32_16x16x32_bf16 v[20:23], v[208:211], v[192:195], v[20:23]
	v_mfma_f32_16x16x32_bf16 v[16:19], v[242:245], v[192:195], v[16:19]
	v_mfma_f32_16x16x32_bf16 v[4:7], v[208:211], v[200:203], v[4:7]
	v_mfma_f32_16x16x32_bf16 v[0:3], v[242:245], v[200:203], v[0:3]
	s_setprio 0
	s_add_i32 s46, 0, 0x18000
	v_add_u32_e32 v168, s46, v145
	s_barrier
	ds_read_b128 v[140:143], v168
	v_xor_b32_e32 v171, 64, v168
	ds_read_b128 v[154:157], v171
	ds_read_b128 v[158:161], v168 offset:2048
	ds_read_b128 v[168:171], v171 offset:2048
	s_add_u32 s20, s20, 0x180000
	s_addc_u32 s21, s21, 0
	s_mov_b32 m0, s27
	v_lshl_add_u64 v[204:205], s[20:21], 0, v[128:129]
	ds_read_b128 v[172:175], v147 offset:32768
	v_xor_b32_e32 v203, 64, v147
	ds_read_b128 v[176:179], v203 offset:32768
	ds_read_b128 v[180:183], v147 offset:34816
	ds_read_b128 v[184:187], v203 offset:34816
	ds_read_b128 v[188:191], v147 offset:36864
	ds_read_b128 v[192:195], v203 offset:36864
	ds_read_b128 v[196:199], v147 offset:38912
	ds_read_b128 v[200:203], v203 offset:38912
	global_load_lds_dwordx4 v[204:205], off
	v_lshl_add_u64 v[204:205], s[20:21], 0, v[130:131]
	s_mov_b32 m0, s28
	s_nop 0
	global_load_lds_dwordx4 v[204:205], off
	s_waitcnt lgkmcnt(8)
	s_barrier
	s_waitcnt lgkmcnt(0)
	s_setprio 1
	s_waitcnt lgkmcnt(0)
	v_mfma_f32_16x16x32_bf16 v[124:127], v[140:143], v[172:175], v[124:127]
	v_mfma_f32_16x16x32_bf16 v[120:123], v[158:161], v[172:175], v[120:123]
	v_mfma_f32_16x16x32_bf16 v[108:111], v[140:143], v[180:183], v[108:111]
	v_mfma_f32_16x16x32_bf16 v[104:107], v[158:161], v[180:183], v[104:107]
	v_mfma_f32_16x16x32_bf16 v[92:95], v[140:143], v[188:191], v[92:95]
	v_mfma_f32_16x16x32_bf16 v[88:91], v[158:161], v[188:191], v[88:91]
	v_mfma_f32_16x16x32_bf16 v[76:79], v[140:143], v[196:199], v[76:79]
	v_mfma_f32_16x16x32_bf16 v[72:75], v[158:161], v[196:199], v[72:75]
	v_mfma_f32_16x16x32_bf16 v[124:127], v[154:157], v[176:179], v[124:127]
	v_mfma_f32_16x16x32_bf16 v[120:123], v[168:171], v[176:179], v[120:123]
	v_mfma_f32_16x16x32_bf16 v[108:111], v[154:157], v[184:187], v[108:111]
	v_mfma_f32_16x16x32_bf16 v[104:107], v[168:171], v[184:187], v[104:107]
	v_mfma_f32_16x16x32_bf16 v[92:95], v[154:157], v[192:195], v[92:95]
	v_mfma_f32_16x16x32_bf16 v[88:91], v[168:171], v[192:195], v[88:91]
	v_mfma_f32_16x16x32_bf16 v[76:79], v[154:157], v[200:203], v[76:79]
	v_mfma_f32_16x16x32_bf16 v[72:75], v[168:171], v[200:203], v[72:75]
	s_setprio 0
	s_barrier
	s_add_i32 s20, 0, 0x1c000
	s_add_i32 s21, s46, s24
	v_add_u32_e32 v223, s20, v145
	v_lshl_add_u64 v[150:151], v[150:151], 0, s[8:9]
	s_mov_b32 m0, s21
	ds_read_b128 v[204:207], v223
	v_xor_b32_e32 v245, 64, v223
	ds_read_b128 v[208:211], v245
	ds_read_b128 v[212:215], v223 offset:2048
	ds_read_b128 v[242:245], v245 offset:2048
	global_load_lds_dwordx4 v[150:151], off
	v_lshl_add_u64 v[150:151], v[216:217], 0, s[8:9]
	s_add_i32 m0, s21, 0x2000
	s_nop 0
	global_load_lds_dwordx4 v[150:151], off
	s_barrier
	s_waitcnt lgkmcnt(0)
	s_setprio 1
	s_waitcnt lgkmcnt(0)
	v_mfma_f32_16x16x32_bf16 v[116:119], v[204:207], v[172:175], v[116:119]
	v_mfma_f32_16x16x32_bf16 v[112:115], v[212:215], v[172:175], v[112:115]
	v_mfma_f32_16x16x32_bf16 v[100:103], v[204:207], v[180:183], v[100:103]
	v_mfma_f32_16x16x32_bf16 v[96:99], v[212:215], v[180:183], v[96:99]
	v_mfma_f32_16x16x32_bf16 v[84:87], v[204:207], v[188:191], v[84:87]
	v_mfma_f32_16x16x32_bf16 v[80:83], v[212:215], v[188:191], v[80:83]
	v_mfma_f32_16x16x32_bf16 v[68:71], v[204:207], v[196:199], v[68:71]
	v_mfma_f32_16x16x32_bf16 v[64:67], v[212:215], v[196:199], v[64:67]
	v_mfma_f32_16x16x32_bf16 v[116:119], v[208:211], v[176:179], v[116:119]
	v_mfma_f32_16x16x32_bf16 v[112:115], v[242:245], v[176:179], v[112:115]
	v_mfma_f32_16x16x32_bf16 v[100:103], v[208:211], v[184:187], v[100:103]
	v_mfma_f32_16x16x32_bf16 v[96:99], v[242:245], v[184:187], v[96:99]
	v_mfma_f32_16x16x32_bf16 v[84:87], v[208:211], v[192:195], v[84:87]
	v_mfma_f32_16x16x32_bf16 v[80:83], v[242:245], v[192:195], v[80:83]
	v_mfma_f32_16x16x32_bf16 v[68:71], v[208:211], v[200:203], v[68:71]
	v_mfma_f32_16x16x32_bf16 v[64:67], v[242:245], v[200:203], v[64:67]
	s_setprio 0
	s_mov_b32 m0, s33
	v_lshl_add_u64 v[150:151], v[220:221], 0, s[8:9]
	s_barrier
	ds_read_b128 v[172:175], v147 offset:49152
	v_xor_b32_e32 v203, 64, v147
	ds_read_b128 v[176:179], v203 offset:49152
	ds_read_b128 v[180:183], v147 offset:51200
	ds_read_b128 v[184:187], v203 offset:51200
	ds_read_b128 v[188:191], v147 offset:53248
	ds_read_b128 v[192:195], v203 offset:53248
	ds_read_b128 v[196:199], v147 offset:55296
	ds_read_b128 v[200:203], v203 offset:55296
	global_load_lds_dwordx4 v[150:151], off
	v_lshl_add_u64 v[150:151], v[230:231], 0, s[8:9]
	s_mov_b32 m0, s34
	s_nop 0
	global_load_lds_dwordx4 v[150:151], off
	s_barrier
	s_waitcnt lgkmcnt(0)
	s_setprio 1
	s_waitcnt lgkmcnt(0)
	v_mfma_f32_16x16x32_bf16 v[60:63], v[140:143], v[172:175], v[60:63]
	v_mfma_f32_16x16x32_bf16 v[56:59], v[158:161], v[172:175], v[56:59]
	v_mfma_f32_16x16x32_bf16 v[44:47], v[140:143], v[180:183], v[44:47]
	v_mfma_f32_16x16x32_bf16 v[40:43], v[158:161], v[180:183], v[40:43]
	v_mfma_f32_16x16x32_bf16 v[28:31], v[140:143], v[188:191], v[28:31]
	v_mfma_f32_16x16x32_bf16 v[24:27], v[158:161], v[188:191], v[24:27]
	v_mfma_f32_16x16x32_bf16 v[12:15], v[140:143], v[196:199], v[12:15]
	v_mfma_f32_16x16x32_bf16 v[8:11], v[158:161], v[196:199], v[8:11]
	v_mfma_f32_16x16x32_bf16 v[60:63], v[154:157], v[176:179], v[60:63]
	v_mfma_f32_16x16x32_bf16 v[56:59], v[168:171], v[176:179], v[56:59]
	v_mfma_f32_16x16x32_bf16 v[44:47], v[154:157], v[184:187], v[44:47]
	v_mfma_f32_16x16x32_bf16 v[40:43], v[168:171], v[184:187], v[40:43]
	v_mfma_f32_16x16x32_bf16 v[28:31], v[154:157], v[192:195], v[28:31]
	v_mfma_f32_16x16x32_bf16 v[24:27], v[168:171], v[192:195], v[24:27]
	v_mfma_f32_16x16x32_bf16 v[12:15], v[154:157], v[200:203], v[12:15]
	v_mfma_f32_16x16x32_bf16 v[8:11], v[168:171], v[200:203], v[8:11]
	s_setprio 0
	s_barrier
	s_add_u32 s18, s18, 0x80080
	s_addc_u32 s19, s19, 0
	s_add_i32 s20, s20, s24
	v_lshl_add_u64 v[140:141], s[18:19], 0, v[164:165]
	s_mov_b32 m0, s20
	s_nop 0
	global_load_lds_dwordx4 v[140:141], off
	v_lshl_add_u64 v[140:141], s[18:19], 0, v[166:167]
	s_add_i32 m0, s20, 0x2000
	s_nop 0
	global_load_lds_dwordx4 v[140:141], off
	s_waitcnt vmcnt(6)
	s_barrier
	s_setprio 1
	v_mfma_f32_16x16x32_bf16 v[52:55], v[204:207], v[172:175], v[52:55]
	v_mfma_f32_16x16x32_bf16 v[48:51], v[212:215], v[172:175], v[48:51]
	v_mfma_f32_16x16x32_bf16 v[36:39], v[204:207], v[180:183], v[36:39]
	v_mfma_f32_16x16x32_bf16 v[32:35], v[212:215], v[180:183], v[32:35]
	v_mfma_f32_16x16x32_bf16 v[20:23], v[204:207], v[188:191], v[20:23]
	v_mfma_f32_16x16x32_bf16 v[16:19], v[212:215], v[188:191], v[16:19]
	v_mfma_f32_16x16x32_bf16 v[4:7], v[204:207], v[196:199], v[4:7]
	v_mfma_f32_16x16x32_bf16 v[0:3], v[212:215], v[196:199], v[0:3]
	v_mfma_f32_16x16x32_bf16 v[52:55], v[208:211], v[176:179], v[52:55]
	v_mfma_f32_16x16x32_bf16 v[48:51], v[242:245], v[176:179], v[48:51]
	v_mfma_f32_16x16x32_bf16 v[36:39], v[208:211], v[184:187], v[36:39]
	v_mfma_f32_16x16x32_bf16 v[32:35], v[242:245], v[184:187], v[32:35]
	v_mfma_f32_16x16x32_bf16 v[20:23], v[208:211], v[192:195], v[20:23]
	v_mfma_f32_16x16x32_bf16 v[16:19], v[242:245], v[192:195], v[16:19]
	v_mfma_f32_16x16x32_bf16 v[4:7], v[208:211], v[200:203], v[4:7]
	v_mfma_f32_16x16x32_bf16 v[0:3], v[242:245], v[200:203], v[0:3]
	s_setprio 0
	s_add_i32 s45, s45, 2
	s_add_u32 s6, s6, 0x100
	s_addc_u32 s7, s7, 0
	s_add_u32 s43, s43, 0x100
	s_addc_u32 s44, s44, 0
	s_cmp_gt_u32 s45, 29
	s_barrier
	s_cbranch_scc0 .LBB0_283
	v_lshl_add_u32 v217, s42, 8, v163
	v_add_u32_e32 v217, s30, v217
	v_lshlrev_b32_e32 v208, 2, v217
	v_lshl_add_u32 v214, v225, 3, s31
	v_lshl_add_u32 v214, s0, 8, v214
	v_lshl_add_u32 v209, v217, 11, v214
	v_lshlrev_b32_e32 v209, 1, v209
	v_lshlrev_b32_e32 v210, 1, v209
	v_lshl_add_u32 v217, v225, 4, v163
	v_xor_b32_e32 v215, 16, v217
	v_lshlrev_b32_e32 v215, 2, v215
	v_xor_b32_e32 v216, 32, v217
	v_lshlrev_b32_e32 v216, 2, v216
	v_add_u32_e32 v212, 0x0, v210
	global_load_dwordx4 v[176:179], v212, s[36:37]
	global_load_dwordx4 v[180:183], v212, s[36:37] offset:16
	global_load_dwordx4 v[184:187], v212, s[36:37] offset:512
	global_load_dwordx4 v[188:191], v212, s[36:37] offset:528
	v_add_u32_e32 v212, 0x20000, v210
	global_load_dwordx4 v[192:195], v212, s[36:37]
	global_load_dwordx4 v[196:199], v212, s[36:37] offset:16
	global_load_dwordx4 v[200:203], v212, s[36:37] offset:512
	global_load_dwordx4 v[204:207], v212, s[36:37] offset:528
	s_waitcnt vmcnt(4)
	v_pk_add_f32 v[124:125], v[124:125], v[176:177]
	v_pk_add_f32 v[126:127], v[126:127], v[178:179]
	v_pk_add_f32 v[120:121], v[120:121], v[180:181]
	v_pk_add_f32 v[122:123], v[122:123], v[182:183]
	v_mul_f32_e32 v213, v124, v124
	v_fmac_f32_e32 v213, v125, v125
	v_fmac_f32_e32 v213, v126, v126
	v_fmac_f32_e32 v213, v127, v127
	v_fmac_f32_e32 v213, v120, v120
	v_fmac_f32_e32 v213, v121, v121
	v_fmac_f32_e32 v213, v122, v122
	v_fmac_f32_e32 v213, v123, v123
	v_cvt_pk_bf16_f32 v176, v124, v125
	v_cvt_pk_bf16_f32 v177, v126, v127
	v_cvt_pk_bf16_f32 v178, v120, v121
	v_cvt_pk_bf16_f32 v179, v122, v123
	v_add_u32_e32 v217, 0x0, v209
	global_store_dwordx4 v217, v[176:179], s[80:81]
	v_pk_add_f32 v[116:117], v[116:117], v[184:185]
	v_pk_add_f32 v[118:119], v[118:119], v[186:187]
	v_pk_add_f32 v[112:113], v[112:113], v[188:189]
	v_pk_add_f32 v[114:115], v[114:115], v[190:191]
	v_fmac_f32_e32 v213, v116, v116
	v_fmac_f32_e32 v213, v117, v117
	v_fmac_f32_e32 v213, v118, v118
	v_fmac_f32_e32 v213, v119, v119
	v_fmac_f32_e32 v213, v112, v112
	v_fmac_f32_e32 v213, v113, v113
	v_fmac_f32_e32 v213, v114, v114
	v_fmac_f32_e32 v213, v115, v115
	v_cvt_pk_bf16_f32 v184, v116, v117
	v_cvt_pk_bf16_f32 v185, v118, v119
	v_cvt_pk_bf16_f32 v186, v112, v113
	v_cvt_pk_bf16_f32 v187, v114, v115
	global_store_dwordx4 v217, v[184:187], s[80:81] offset:256
	ds_bpermute_b32 v214, v215, v213
	s_waitcnt lgkmcnt(0)
	v_add_f32_e32 v213, v213, v214
	ds_bpermute_b32 v214, v216, v213
	s_waitcnt lgkmcnt(0)
	v_add_f32_e32 v213, v213, v214
	s_mov_b64 exec, 0xffff
	global_atomic_add_f32 v208, v213, s[12:13]
	s_mov_b64 exec, -1
	v_add_u32_e32 v212, 0x40000, v210
	global_load_dwordx4 v[176:179], v212, s[36:37]
	global_load_dwordx4 v[180:183], v212, s[36:37] offset:16
	global_load_dwordx4 v[184:187], v212, s[36:37] offset:512
	global_load_dwordx4 v[188:191], v212, s[36:37] offset:528
	s_waitcnt vmcnt(7)
	v_pk_add_f32 v[108:109], v[108:109], v[192:193]
	v_pk_add_f32 v[110:111], v[110:111], v[194:195]
	v_pk_add_f32 v[104:105], v[104:105], v[196:197]
	v_pk_add_f32 v[106:107], v[106:107], v[198:199]
	v_mul_f32_e32 v213, v108, v108
	v_fmac_f32_e32 v213, v109, v109
	v_fmac_f32_e32 v213, v110, v110
	v_fmac_f32_e32 v213, v111, v111
	v_fmac_f32_e32 v213, v104, v104
	v_fmac_f32_e32 v213, v105, v105
	v_fmac_f32_e32 v213, v106, v106
	v_fmac_f32_e32 v213, v107, v107
	v_cvt_pk_bf16_f32 v192, v108, v109
	v_cvt_pk_bf16_f32 v193, v110, v111
	v_cvt_pk_bf16_f32 v194, v104, v105
	v_cvt_pk_bf16_f32 v195, v106, v107
	v_add_u32_e32 v217, 0x10000, v209
	global_store_dwordx4 v217, v[192:195], s[80:81]
	v_pk_add_f32 v[100:101], v[100:101], v[200:201]
	v_pk_add_f32 v[102:103], v[102:103], v[202:203]
	v_pk_add_f32 v[96:97], v[96:97], v[204:205]
	v_pk_add_f32 v[98:99], v[98:99], v[206:207]
	v_fmac_f32_e32 v213, v100, v100
	v_fmac_f32_e32 v213, v101, v101
	v_fmac_f32_e32 v213, v102, v102
	v_fmac_f32_e32 v213, v103, v103
	v_fmac_f32_e32 v213, v96, v96
	v_fmac_f32_e32 v213, v97, v97
	v_fmac_f32_e32 v213, v98, v98
	v_fmac_f32_e32 v213, v99, v99
	v_cvt_pk_bf16_f32 v200, v100, v101
	v_cvt_pk_bf16_f32 v201, v102, v103
	v_cvt_pk_bf16_f32 v202, v96, v97
	v_cvt_pk_bf16_f32 v203, v98, v99
	global_store_dwordx4 v217, v[200:203], s[80:81] offset:256
	ds_bpermute_b32 v214, v215, v213
	s_waitcnt lgkmcnt(0)
	v_add_f32_e32 v213, v213, v214
	ds_bpermute_b32 v214, v216, v213
	s_waitcnt lgkmcnt(0)
	v_add_f32_e32 v213, v213, v214
	s_mov_b64 exec, 0xffff
	global_atomic_add_f32 v208, v213, s[12:13] offset:64
	s_mov_b64 exec, -1
	v_add_u32_e32 v212, 0x60000, v210
	global_load_dwordx4 v[192:195], v212, s[36:37]
	global_load_dwordx4 v[196:199], v212, s[36:37] offset:16
	global_load_dwordx4 v[200:203], v212, s[36:37] offset:512
	global_load_dwordx4 v[204:207], v212, s[36:37] offset:528
	s_waitcnt vmcnt(7)
	v_pk_add_f32 v[92:93], v[92:93], v[176:177]
	v_pk_add_f32 v[94:95], v[94:95], v[178:179]
	v_pk_add_f32 v[88:89], v[88:89], v[180:181]
	v_pk_add_f32 v[90:91], v[90:91], v[182:183]
	v_mul_f32_e32 v213, v92, v92
	v_fmac_f32_e32 v213, v93, v93
	v_fmac_f32_e32 v213, v94, v94
	v_fmac_f32_e32 v213, v95, v95
	v_fmac_f32_e32 v213, v88, v88
	v_fmac_f32_e32 v213, v89, v89
	v_fmac_f32_e32 v213, v90, v90
	v_fmac_f32_e32 v213, v91, v91
	v_cvt_pk_bf16_f32 v176, v92, v93
	v_cvt_pk_bf16_f32 v177, v94, v95
	v_cvt_pk_bf16_f32 v178, v88, v89
	v_cvt_pk_bf16_f32 v179, v90, v91
	v_add_u32_e32 v217, 0x20000, v209
	global_store_dwordx4 v217, v[176:179], s[80:81]
	v_pk_add_f32 v[84:85], v[84:85], v[184:185]
	v_pk_add_f32 v[86:87], v[86:87], v[186:187]
	v_pk_add_f32 v[80:81], v[80:81], v[188:189]
	v_pk_add_f32 v[82:83], v[82:83], v[190:191]
	v_fmac_f32_e32 v213, v84, v84
	v_fmac_f32_e32 v213, v85, v85
	v_fmac_f32_e32 v213, v86, v86
	v_fmac_f32_e32 v213, v87, v87
	v_fmac_f32_e32 v213, v80, v80
	v_fmac_f32_e32 v213, v81, v81
	v_fmac_f32_e32 v213, v82, v82
	v_fmac_f32_e32 v213, v83, v83
	v_cvt_pk_bf16_f32 v184, v84, v85
	v_cvt_pk_bf16_f32 v185, v86, v87
	v_cvt_pk_bf16_f32 v186, v80, v81
	v_cvt_pk_bf16_f32 v187, v82, v83
	global_store_dwordx4 v217, v[184:187], s[80:81] offset:256
	ds_bpermute_b32 v214, v215, v213
	s_waitcnt lgkmcnt(0)
	v_add_f32_e32 v213, v213, v214
	ds_bpermute_b32 v214, v216, v213
	s_waitcnt lgkmcnt(0)
	v_add_f32_e32 v213, v213, v214
	s_mov_b64 exec, 0xffff
	global_atomic_add_f32 v208, v213, s[12:13] offset:128
	s_mov_b64 exec, -1
	v_add_u32_e32 v212, 0x100000, v210
	global_load_dwordx4 v[176:179], v212, s[36:37]
	global_load_dwordx4 v[180:183], v212, s[36:37] offset:16
	global_load_dwordx4 v[184:187], v212, s[36:37] offset:512
	global_load_dwordx4 v[188:191], v212, s[36:37] offset:528
	s_waitcnt vmcnt(7)
	v_pk_add_f32 v[76:77], v[76:77], v[192:193]
	v_pk_add_f32 v[78:79], v[78:79], v[194:195]
	v_pk_add_f32 v[72:73], v[72:73], v[196:197]
	v_pk_add_f32 v[74:75], v[74:75], v[198:199]
	v_mul_f32_e32 v213, v76, v76
	v_fmac_f32_e32 v213, v77, v77
	v_fmac_f32_e32 v213, v78, v78
	v_fmac_f32_e32 v213, v79, v79
	v_fmac_f32_e32 v213, v72, v72
	v_fmac_f32_e32 v213, v73, v73
	v_fmac_f32_e32 v213, v74, v74
	v_fmac_f32_e32 v213, v75, v75
	v_cvt_pk_bf16_f32 v192, v76, v77
	v_cvt_pk_bf16_f32 v193, v78, v79
	v_cvt_pk_bf16_f32 v194, v72, v73
	v_cvt_pk_bf16_f32 v195, v74, v75
	v_add_u32_e32 v217, 0x30000, v209
	global_store_dwordx4 v217, v[192:195], s[80:81]
	v_pk_add_f32 v[68:69], v[68:69], v[200:201]
	v_pk_add_f32 v[70:71], v[70:71], v[202:203]
	v_pk_add_f32 v[64:65], v[64:65], v[204:205]
	v_pk_add_f32 v[66:67], v[66:67], v[206:207]
	v_fmac_f32_e32 v213, v68, v68
	v_fmac_f32_e32 v213, v69, v69
	v_fmac_f32_e32 v213, v70, v70
	v_fmac_f32_e32 v213, v71, v71
	v_fmac_f32_e32 v213, v64, v64
	v_fmac_f32_e32 v213, v65, v65
	v_fmac_f32_e32 v213, v66, v66
	v_fmac_f32_e32 v213, v67, v67
	v_cvt_pk_bf16_f32 v200, v68, v69
	v_cvt_pk_bf16_f32 v201, v70, v71
	v_cvt_pk_bf16_f32 v202, v64, v65
	v_cvt_pk_bf16_f32 v203, v66, v67
	global_store_dwordx4 v217, v[200:203], s[80:81] offset:256
	ds_bpermute_b32 v214, v215, v213
	s_waitcnt lgkmcnt(0)
	v_add_f32_e32 v213, v213, v214
	ds_bpermute_b32 v214, v216, v213
	s_waitcnt lgkmcnt(0)
	v_add_f32_e32 v213, v213, v214
	s_mov_b64 exec, 0xffff
	global_atomic_add_f32 v208, v213, s[12:13] offset:192
	s_mov_b64 exec, -1
	v_add_u32_e32 v212, 0x120000, v210
	global_load_dwordx4 v[192:195], v212, s[36:37]
	global_load_dwordx4 v[196:199], v212, s[36:37] offset:16
	global_load_dwordx4 v[200:203], v212, s[36:37] offset:512
	global_load_dwordx4 v[204:207], v212, s[36:37] offset:528
	s_waitcnt vmcnt(7)
	v_pk_add_f32 v[60:61], v[60:61], v[176:177]
	v_pk_add_f32 v[62:63], v[62:63], v[178:179]
	v_pk_add_f32 v[56:57], v[56:57], v[180:181]
	v_pk_add_f32 v[58:59], v[58:59], v[182:183]
	v_mul_f32_e32 v213, v60, v60
	v_fmac_f32_e32 v213, v61, v61
	v_fmac_f32_e32 v213, v62, v62
	v_fmac_f32_e32 v213, v63, v63
	v_fmac_f32_e32 v213, v56, v56
	v_fmac_f32_e32 v213, v57, v57
	v_fmac_f32_e32 v213, v58, v58
	v_fmac_f32_e32 v213, v59, v59
	v_cvt_pk_bf16_f32 v176, v60, v61
	v_cvt_pk_bf16_f32 v177, v62, v63
	v_cvt_pk_bf16_f32 v178, v56, v57
	v_cvt_pk_bf16_f32 v179, v58, v59
	v_add_u32_e32 v217, 0x80000, v209
	global_store_dwordx4 v217, v[176:179], s[80:81]
	v_pk_add_f32 v[52:53], v[52:53], v[184:185]
	v_pk_add_f32 v[54:55], v[54:55], v[186:187]
	v_pk_add_f32 v[48:49], v[48:49], v[188:189]
	v_pk_add_f32 v[50:51], v[50:51], v[190:191]
	v_fmac_f32_e32 v213, v52, v52
	v_fmac_f32_e32 v213, v53, v53
	v_fmac_f32_e32 v213, v54, v54
	v_fmac_f32_e32 v213, v55, v55
	v_fmac_f32_e32 v213, v48, v48
	v_fmac_f32_e32 v213, v49, v49
	v_fmac_f32_e32 v213, v50, v50
	v_fmac_f32_e32 v213, v51, v51
	v_cvt_pk_bf16_f32 v184, v52, v53
	v_cvt_pk_bf16_f32 v185, v54, v55
	v_cvt_pk_bf16_f32 v186, v48, v49
	v_cvt_pk_bf16_f32 v187, v50, v51
	global_store_dwordx4 v217, v[184:187], s[80:81] offset:256
	ds_bpermute_b32 v214, v215, v213
	s_waitcnt lgkmcnt(0)
	v_add_f32_e32 v213, v213, v214
	ds_bpermute_b32 v214, v216, v213
	s_waitcnt lgkmcnt(0)
	v_add_f32_e32 v213, v213, v214
	s_mov_b64 exec, 0xffff
	global_atomic_add_f32 v208, v213, s[12:13] offset:512
	s_mov_b64 exec, -1
	v_add_u32_e32 v212, 0x140000, v210
	global_load_dwordx4 v[176:179], v212, s[36:37]
	global_load_dwordx4 v[180:183], v212, s[36:37] offset:16
	global_load_dwordx4 v[184:187], v212, s[36:37] offset:512
	global_load_dwordx4 v[188:191], v212, s[36:37] offset:528
	s_waitcnt vmcnt(7)
	v_pk_add_f32 v[44:45], v[44:45], v[192:193]
	v_pk_add_f32 v[46:47], v[46:47], v[194:195]
	v_pk_add_f32 v[40:41], v[40:41], v[196:197]
	v_pk_add_f32 v[42:43], v[42:43], v[198:199]
	v_mul_f32_e32 v213, v44, v44
	v_fmac_f32_e32 v213, v45, v45
	v_fmac_f32_e32 v213, v46, v46
	v_fmac_f32_e32 v213, v47, v47
	v_fmac_f32_e32 v213, v40, v40
	v_fmac_f32_e32 v213, v41, v41
	v_fmac_f32_e32 v213, v42, v42
	v_fmac_f32_e32 v213, v43, v43
	v_cvt_pk_bf16_f32 v192, v44, v45
	v_cvt_pk_bf16_f32 v193, v46, v47
	v_cvt_pk_bf16_f32 v194, v40, v41
	v_cvt_pk_bf16_f32 v195, v42, v43
	v_add_u32_e32 v217, 0x90000, v209
	global_store_dwordx4 v217, v[192:195], s[80:81]
	v_pk_add_f32 v[36:37], v[36:37], v[200:201]
	v_pk_add_f32 v[38:39], v[38:39], v[202:203]
	v_pk_add_f32 v[32:33], v[32:33], v[204:205]
	v_pk_add_f32 v[34:35], v[34:35], v[206:207]
	v_fmac_f32_e32 v213, v36, v36
	v_fmac_f32_e32 v213, v37, v37
	v_fmac_f32_e32 v213, v38, v38
	v_fmac_f32_e32 v213, v39, v39
	v_fmac_f32_e32 v213, v32, v32
	v_fmac_f32_e32 v213, v33, v33
	v_fmac_f32_e32 v213, v34, v34
	v_fmac_f32_e32 v213, v35, v35
	v_cvt_pk_bf16_f32 v200, v36, v37
	v_cvt_pk_bf16_f32 v201, v38, v39
	v_cvt_pk_bf16_f32 v202, v32, v33
	v_cvt_pk_bf16_f32 v203, v34, v35
	global_store_dwordx4 v217, v[200:203], s[80:81] offset:256
	ds_bpermute_b32 v214, v215, v213
	s_waitcnt lgkmcnt(0)
	v_add_f32_e32 v213, v213, v214
	ds_bpermute_b32 v214, v216, v213
	s_waitcnt lgkmcnt(0)
	v_add_f32_e32 v213, v213, v214
	s_mov_b64 exec, 0xffff
	global_atomic_add_f32 v208, v213, s[12:13] offset:576
	s_mov_b64 exec, -1
	v_add_u32_e32 v212, 0x160000, v210
	global_load_dwordx4 v[192:195], v212, s[36:37]
	global_load_dwordx4 v[196:199], v212, s[36:37] offset:16
	global_load_dwordx4 v[200:203], v212, s[36:37] offset:512
	global_load_dwordx4 v[204:207], v212, s[36:37] offset:528
	s_waitcnt vmcnt(7)
	v_pk_add_f32 v[28:29], v[28:29], v[176:177]
	v_pk_add_f32 v[30:31], v[30:31], v[178:179]
	v_pk_add_f32 v[24:25], v[24:25], v[180:181]
	v_pk_add_f32 v[26:27], v[26:27], v[182:183]
	v_mul_f32_e32 v213, v28, v28
	v_fmac_f32_e32 v213, v29, v29
	v_fmac_f32_e32 v213, v30, v30
	v_fmac_f32_e32 v213, v31, v31
	v_fmac_f32_e32 v213, v24, v24
	v_fmac_f32_e32 v213, v25, v25
	v_fmac_f32_e32 v213, v26, v26
	v_fmac_f32_e32 v213, v27, v27
	v_cvt_pk_bf16_f32 v176, v28, v29
	v_cvt_pk_bf16_f32 v177, v30, v31
	v_cvt_pk_bf16_f32 v178, v24, v25
	v_cvt_pk_bf16_f32 v179, v26, v27
	v_add_u32_e32 v217, 0xa0000, v209
	global_store_dwordx4 v217, v[176:179], s[80:81]
	v_pk_add_f32 v[20:21], v[20:21], v[184:185]
	v_pk_add_f32 v[22:23], v[22:23], v[186:187]
	v_pk_add_f32 v[16:17], v[16:17], v[188:189]
	v_pk_add_f32 v[18:19], v[18:19], v[190:191]
	v_fmac_f32_e32 v213, v20, v20
	v_fmac_f32_e32 v213, v21, v21
	v_fmac_f32_e32 v213, v22, v22
	v_fmac_f32_e32 v213, v23, v23
	v_fmac_f32_e32 v213, v16, v16
	v_fmac_f32_e32 v213, v17, v17
	v_fmac_f32_e32 v213, v18, v18
	v_fmac_f32_e32 v213, v19, v19
	v_cvt_pk_bf16_f32 v184, v20, v21
	v_cvt_pk_bf16_f32 v185, v22, v23
	v_cvt_pk_bf16_f32 v186, v16, v17
	v_cvt_pk_bf16_f32 v187, v18, v19
	global_store_dwordx4 v217, v[184:187], s[80:81] offset:256
	ds_bpermute_b32 v214, v215, v213
	s_waitcnt lgkmcnt(0)
	v_add_f32_e32 v213, v213, v214
	ds_bpermute_b32 v214, v216, v213
	s_waitcnt lgkmcnt(0)
	v_add_f32_e32 v213, v213, v214
	s_mov_b64 exec, 0xffff
	global_atomic_add_f32 v208, v213, s[12:13] offset:640
	s_mov_b64 exec, -1
	s_waitcnt vmcnt(3)
	v_pk_add_f32 v[12:13], v[12:13], v[192:193]
	v_pk_add_f32 v[14:15], v[14:15], v[194:195]
	v_pk_add_f32 v[8:9], v[8:9], v[196:197]
	v_pk_add_f32 v[10:11], v[10:11], v[198:199]
	v_mul_f32_e32 v213, v12, v12
	v_fmac_f32_e32 v213, v13, v13
	v_fmac_f32_e32 v213, v14, v14
	v_fmac_f32_e32 v213, v15, v15
	v_fmac_f32_e32 v213, v8, v8
	v_fmac_f32_e32 v213, v9, v9
	v_fmac_f32_e32 v213, v10, v10
	v_fmac_f32_e32 v213, v11, v11
	v_cvt_pk_bf16_f32 v192, v12, v13
	v_cvt_pk_bf16_f32 v193, v14, v15
	v_cvt_pk_bf16_f32 v194, v8, v9
	v_cvt_pk_bf16_f32 v195, v10, v11
	v_add_u32_e32 v217, 0xb0000, v209
	global_store_dwordx4 v217, v[192:195], s[80:81]
	v_pk_add_f32 v[4:5], v[4:5], v[200:201]
	v_pk_add_f32 v[6:7], v[6:7], v[202:203]
	v_pk_add_f32 v[0:1], v[0:1], v[204:205]
	v_pk_add_f32 v[2:3], v[2:3], v[206:207]
	v_fmac_f32_e32 v213, v4, v4
	v_fmac_f32_e32 v213, v5, v5
	v_fmac_f32_e32 v213, v6, v6
	v_fmac_f32_e32 v213, v7, v7
	v_fmac_f32_e32 v213, v0, v0
	v_fmac_f32_e32 v213, v1, v1
	v_fmac_f32_e32 v213, v2, v2
	v_fmac_f32_e32 v213, v3, v3
	v_cvt_pk_bf16_f32 v200, v4, v5
	v_cvt_pk_bf16_f32 v201, v6, v7
	v_cvt_pk_bf16_f32 v202, v0, v1
	v_cvt_pk_bf16_f32 v203, v2, v3
	global_store_dwordx4 v217, v[200:203], s[80:81] offset:256
	ds_bpermute_b32 v214, v215, v213
	s_waitcnt lgkmcnt(0)
	v_add_f32_e32 v213, v213, v214
	ds_bpermute_b32 v214, v216, v213
	s_waitcnt lgkmcnt(0)
	v_add_f32_e32 v213, v213, v214
	s_mov_b64 exec, 0xffff
	global_atomic_add_f32 v208, v213, s[12:13] offset:704
	s_mov_b64 exec, -1
	s_branch .LBB0_273

.LBB0_508:
	ds_read_b128 v[136:139], v141
	v_xor_b32_e32 v157, 64, v141
	ds_read_b128 v[146:149], v157
	ds_read_b128 v[150:153], v141 offset:2048
	ds_read_b128 v[154:157], v157 offset:2048
	s_add_u32 s8, s0, 0xffea0080
	s_addc_u32 s9, s1, -1
	s_cmpk_eq_i32 s41, 0x54
	s_cselect_b32 s17, s13, s9
	s_cselect_b32 s16, s12, s8
	s_cselect_b32 s9, s11, s40
	s_cselect_b32 s8, s10, s39
	v_lshl_add_u64 v[204:205], s[0:1], 0, v[128:129]
	s_add_i32 m0, s21, 0xc000
	ds_read_b128 v[158:161], v142
	v_xor_b32_e32 v203, 64, v142
	ds_read_b128 v[176:179], v203
	ds_read_b128 v[180:183], v142 offset:2048
	ds_read_b128 v[184:187], v203 offset:2048
	ds_read_b128 v[188:191], v142 offset:4096
	ds_read_b128 v[192:195], v203 offset:4096
	ds_read_b128 v[196:199], v142 offset:6144
	ds_read_b128 v[200:203], v203 offset:6144
	global_load_lds_dwordx4 v[204:205], off
	v_lshl_add_u64 v[204:205], s[0:1], 0, v[130:131]
	s_add_i32 m0, s21, 0xe000
	s_nop 0
	global_load_lds_dwordx4 v[204:205], off
	s_waitcnt lgkmcnt(8)
	s_barrier
	s_waitcnt lgkmcnt(0)
	s_setprio 1
	s_waitcnt lgkmcnt(0)
	v_mfma_f32_16x16x32_bf16 v[124:127], v[136:139], v[158:161], v[124:127]
	v_mfma_f32_16x16x32_bf16 v[120:123], v[150:153], v[158:161], v[120:123]
	v_mfma_f32_16x16x32_bf16 v[108:111], v[136:139], v[180:183], v[108:111]
	v_mfma_f32_16x16x32_bf16 v[104:107], v[150:153], v[180:183], v[104:107]
	v_mfma_f32_16x16x32_bf16 v[92:95], v[136:139], v[188:191], v[92:95]
	v_mfma_f32_16x16x32_bf16 v[88:91], v[150:153], v[188:191], v[88:91]
	v_mfma_f32_16x16x32_bf16 v[76:79], v[136:139], v[196:199], v[76:79]
	v_mfma_f32_16x16x32_bf16 v[72:75], v[150:153], v[196:199], v[72:75]
	v_mfma_f32_16x16x32_bf16 v[124:127], v[146:149], v[176:179], v[124:127]
	v_mfma_f32_16x16x32_bf16 v[120:123], v[154:157], v[176:179], v[120:123]
	v_mfma_f32_16x16x32_bf16 v[108:111], v[146:149], v[184:187], v[108:111]
	v_mfma_f32_16x16x32_bf16 v[104:107], v[154:157], v[184:187], v[104:107]
	v_mfma_f32_16x16x32_bf16 v[92:95], v[146:149], v[192:195], v[92:95]
	v_mfma_f32_16x16x32_bf16 v[88:91], v[154:157], v[192:195], v[88:91]
	v_mfma_f32_16x16x32_bf16 v[76:79], v[146:149], v[200:203], v[76:79]
	v_mfma_f32_16x16x32_bf16 v[72:75], v[154:157], v[200:203], v[72:75]
	s_setprio 0
	s_barrier
	s_add_i32 s42, s33, s20
	v_lshl_add_u64 v[216:217], s[8:9], 0, v[170:171]
	s_mov_b32 m0, s42
	ds_read_b128 v[204:207], v143
	v_xor_b32_e32 v243, 64, v143
	ds_read_b128 v[208:211], v243
	ds_read_b128 v[212:215], v143 offset:2048
	ds_read_b128 v[240:243], v243 offset:2048
	global_load_lds_dwordx4 v[216:217], off
	v_lshl_add_u64 v[244:245], s[8:9], 0, v[174:175]
	s_add_i32 m0, s42, 0x2000
	s_nop 0
	global_load_lds_dwordx4 v[244:245], off
	s_barrier
	s_waitcnt lgkmcnt(0)
	s_setprio 1
	s_waitcnt lgkmcnt(0)
	v_mfma_f32_16x16x32_bf16 v[116:119], v[204:207], v[158:161], v[116:119]
	v_mfma_f32_16x16x32_bf16 v[112:115], v[212:215], v[158:161], v[112:115]
	v_mfma_f32_16x16x32_bf16 v[100:103], v[204:207], v[180:183], v[100:103]
	v_mfma_f32_16x16x32_bf16 v[96:99], v[212:215], v[180:183], v[96:99]
	v_mfma_f32_16x16x32_bf16 v[84:87], v[204:207], v[188:191], v[84:87]
	v_mfma_f32_16x16x32_bf16 v[80:83], v[212:215], v[188:191], v[80:83]
	v_mfma_f32_16x16x32_bf16 v[68:71], v[204:207], v[196:199], v[68:71]
	v_mfma_f32_16x16x32_bf16 v[64:67], v[212:215], v[196:199], v[64:67]
	v_mfma_f32_16x16x32_bf16 v[116:119], v[208:211], v[176:179], v[116:119]
	v_mfma_f32_16x16x32_bf16 v[112:115], v[240:243], v[176:179], v[112:115]
	v_mfma_f32_16x16x32_bf16 v[100:103], v[208:211], v[184:187], v[100:103]
	v_mfma_f32_16x16x32_bf16 v[96:99], v[240:243], v[184:187], v[96:99]
	v_mfma_f32_16x16x32_bf16 v[84:87], v[208:211], v[192:195], v[84:87]
	v_mfma_f32_16x16x32_bf16 v[80:83], v[240:243], v[192:195], v[80:83]
	v_mfma_f32_16x16x32_bf16 v[68:71], v[208:211], v[200:203], v[68:71]
	v_mfma_f32_16x16x32_bf16 v[64:67], v[240:243], v[200:203], v[64:67]
	s_setprio 0
	s_mov_b32 m0, s21
	v_lshl_add_u64 v[246:247], s[16:17], 0, v[168:169]
	s_barrier
	ds_read_b128 v[158:161], v142 offset:16384
	v_xor_b32_e32 v203, 64, v142
	ds_read_b128 v[176:179], v203 offset:16384
	ds_read_b128 v[180:183], v142 offset:18432
	ds_read_b128 v[184:187], v203 offset:18432
	ds_read_b128 v[188:191], v142 offset:20480
	ds_read_b128 v[192:195], v203 offset:20480
	ds_read_b128 v[196:199], v142 offset:22528
	ds_read_b128 v[200:203], v203 offset:22528
	global_load_lds_dwordx4 v[246:247], off
	v_lshl_add_u64 v[248:249], s[16:17], 0, v[172:173]
	s_mov_b32 m0, s22
	s_nop 0
	global_load_lds_dwordx4 v[248:249], off
	s_barrier
	s_waitcnt lgkmcnt(0)
	s_setprio 1
	s_waitcnt lgkmcnt(0)
	v_mfma_f32_16x16x32_bf16 v[60:63], v[136:139], v[158:161], v[60:63]
	v_mfma_f32_16x16x32_bf16 v[56:59], v[150:153], v[158:161], v[56:59]
	v_mfma_f32_16x16x32_bf16 v[44:47], v[136:139], v[180:183], v[44:47]
	v_mfma_f32_16x16x32_bf16 v[40:43], v[150:153], v[180:183], v[40:43]
	v_mfma_f32_16x16x32_bf16 v[28:31], v[136:139], v[188:191], v[28:31]
	v_mfma_f32_16x16x32_bf16 v[24:27], v[150:153], v[188:191], v[24:27]
	v_mfma_f32_16x16x32_bf16 v[12:15], v[136:139], v[196:199], v[12:15]
	v_mfma_f32_16x16x32_bf16 v[8:11], v[150:153], v[196:199], v[8:11]
	v_mfma_f32_16x16x32_bf16 v[60:63], v[146:149], v[176:179], v[60:63]
	v_mfma_f32_16x16x32_bf16 v[56:59], v[154:157], v[176:179], v[56:59]
	v_mfma_f32_16x16x32_bf16 v[44:47], v[146:149], v[184:187], v[44:47]
	v_mfma_f32_16x16x32_bf16 v[40:43], v[154:157], v[184:187], v[40:43]
	v_mfma_f32_16x16x32_bf16 v[28:31], v[146:149], v[192:195], v[28:31]
	v_mfma_f32_16x16x32_bf16 v[24:27], v[154:157], v[192:195], v[24:27]
	v_mfma_f32_16x16x32_bf16 v[12:15], v[146:149], v[200:203], v[12:15]
	v_mfma_f32_16x16x32_bf16 v[8:11], v[154:157], v[200:203], v[8:11]
	s_setprio 0
	s_barrier
	s_add_u32 s42, s8, 0x160000
	s_addc_u32 s43, s9, 0
	s_add_i32 s44, s34, s20
	v_lshl_add_u64 v[136:137], s[42:43], 0, v[170:171]
	s_mov_b32 m0, s44
	s_nop 0
	global_load_lds_dwordx4 v[136:137], off
	v_lshl_add_u64 v[136:137], s[42:43], 0, v[174:175]
	s_add_i32 m0, s44, 0x2000
	s_nop 0
	global_load_lds_dwordx4 v[136:137], off
	s_waitcnt vmcnt(6)
	s_barrier
	s_setprio 1
	v_mfma_f32_16x16x32_bf16 v[52:55], v[204:207], v[158:161], v[52:55]
	v_mfma_f32_16x16x32_bf16 v[48:51], v[212:215], v[158:161], v[48:51]
	v_mfma_f32_16x16x32_bf16 v[36:39], v[204:207], v[180:183], v[36:39]
	v_mfma_f32_16x16x32_bf16 v[32:35], v[212:215], v[180:183], v[32:35]
	v_mfma_f32_16x16x32_bf16 v[20:23], v[204:207], v[188:191], v[20:23]
	v_mfma_f32_16x16x32_bf16 v[16:19], v[212:215], v[188:191], v[16:19]
	v_mfma_f32_16x16x32_bf16 v[4:7], v[204:207], v[196:199], v[4:7]
	v_mfma_f32_16x16x32_bf16 v[0:3], v[212:215], v[196:199], v[0:3]
	v_mfma_f32_16x16x32_bf16 v[52:55], v[208:211], v[176:179], v[52:55]
	v_mfma_f32_16x16x32_bf16 v[48:51], v[240:243], v[176:179], v[48:51]
	v_mfma_f32_16x16x32_bf16 v[36:39], v[208:211], v[184:187], v[36:39]
	v_mfma_f32_16x16x32_bf16 v[32:35], v[240:243], v[184:187], v[32:35]
	v_mfma_f32_16x16x32_bf16 v[20:23], v[208:211], v[192:195], v[20:23]
	v_mfma_f32_16x16x32_bf16 v[16:19], v[240:243], v[192:195], v[16:19]
	v_mfma_f32_16x16x32_bf16 v[4:7], v[208:211], v[200:203], v[4:7]
	v_mfma_f32_16x16x32_bf16 v[0:3], v[240:243], v[200:203], v[0:3]
	s_setprio 0
	s_add_i32 s42, 0, 0x18000
	v_add_u32_e32 v145, s42, v140
	s_barrier
	ds_read_b128 v[136:139], v145
	v_xor_b32_e32 v157, 64, v145
	ds_read_b128 v[146:149], v157
	ds_read_b128 v[150:153], v145 offset:2048
	ds_read_b128 v[154:157], v157 offset:2048
	s_add_u32 s16, s16, 0x160000
	s_addc_u32 s17, s17, 0
	s_mov_b32 m0, s23
	v_lshl_add_u64 v[204:205], s[16:17], 0, v[168:169]
	ds_read_b128 v[158:161], v142 offset:32768
	v_xor_b32_e32 v203, 64, v142
	ds_read_b128 v[176:179], v203 offset:32768
	ds_read_b128 v[180:183], v142 offset:34816
	ds_read_b128 v[184:187], v203 offset:34816
	ds_read_b128 v[188:191], v142 offset:36864
	ds_read_b128 v[192:195], v203 offset:36864
	ds_read_b128 v[196:199], v142 offset:38912
	ds_read_b128 v[200:203], v203 offset:38912
	global_load_lds_dwordx4 v[204:205], off
	v_lshl_add_u64 v[204:205], s[16:17], 0, v[172:173]
	s_mov_b32 m0, s24
	s_nop 0
	global_load_lds_dwordx4 v[204:205], off
	s_waitcnt lgkmcnt(8)
	s_barrier
	s_waitcnt lgkmcnt(0)
	s_setprio 1
	s_waitcnt lgkmcnt(0)
	v_mfma_f32_16x16x32_bf16 v[124:127], v[136:139], v[158:161], v[124:127]
	v_mfma_f32_16x16x32_bf16 v[120:123], v[150:153], v[158:161], v[120:123]
	v_mfma_f32_16x16x32_bf16 v[108:111], v[136:139], v[180:183], v[108:111]
	v_mfma_f32_16x16x32_bf16 v[104:107], v[150:153], v[180:183], v[104:107]
	v_mfma_f32_16x16x32_bf16 v[92:95], v[136:139], v[188:191], v[92:95]
	v_mfma_f32_16x16x32_bf16 v[88:91], v[150:153], v[188:191], v[88:91]
	v_mfma_f32_16x16x32_bf16 v[76:79], v[136:139], v[196:199], v[76:79]
	v_mfma_f32_16x16x32_bf16 v[72:75], v[150:153], v[196:199], v[72:75]
	v_mfma_f32_16x16x32_bf16 v[124:127], v[146:149], v[176:179], v[124:127]
	v_mfma_f32_16x16x32_bf16 v[120:123], v[154:157], v[176:179], v[120:123]
	v_mfma_f32_16x16x32_bf16 v[108:111], v[146:149], v[184:187], v[108:111]
	v_mfma_f32_16x16x32_bf16 v[104:107], v[154:157], v[184:187], v[104:107]
	v_mfma_f32_16x16x32_bf16 v[92:95], v[146:149], v[192:195], v[92:95]
	v_mfma_f32_16x16x32_bf16 v[88:91], v[154:157], v[192:195], v[88:91]
	v_mfma_f32_16x16x32_bf16 v[76:79], v[146:149], v[200:203], v[76:79]
	v_mfma_f32_16x16x32_bf16 v[72:75], v[154:157], v[200:203], v[72:75]
	s_setprio 0
	s_barrier
	s_add_i32 s16, 0, 0x1c000
	s_add_i32 s17, s42, s20
	v_add_u32_e32 v145, s16, v140
	v_lshl_add_u64 v[216:217], v[216:217], 0, s[4:5]
	s_mov_b32 m0, s17
	ds_read_b128 v[204:207], v145
	v_xor_b32_e32 v243, 64, v145
	ds_read_b128 v[208:211], v243
	ds_read_b128 v[212:215], v145 offset:2048
	ds_read_b128 v[240:243], v243 offset:2048
	global_load_lds_dwordx4 v[216:217], off
	v_lshl_add_u64 v[216:217], v[244:245], 0, s[4:5]
	s_add_i32 m0, s17, 0x2000
	s_nop 0
	global_load_lds_dwordx4 v[216:217], off
	s_barrier
	s_waitcnt lgkmcnt(0)
	s_setprio 1
	s_waitcnt lgkmcnt(0)
	v_mfma_f32_16x16x32_bf16 v[116:119], v[204:207], v[158:161], v[116:119]
	v_mfma_f32_16x16x32_bf16 v[112:115], v[212:215], v[158:161], v[112:115]
	v_mfma_f32_16x16x32_bf16 v[100:103], v[204:207], v[180:183], v[100:103]
	v_mfma_f32_16x16x32_bf16 v[96:99], v[212:215], v[180:183], v[96:99]
	v_mfma_f32_16x16x32_bf16 v[84:87], v[204:207], v[188:191], v[84:87]
	v_mfma_f32_16x16x32_bf16 v[80:83], v[212:215], v[188:191], v[80:83]
	v_mfma_f32_16x16x32_bf16 v[68:71], v[204:207], v[196:199], v[68:71]
	v_mfma_f32_16x16x32_bf16 v[64:67], v[212:215], v[196:199], v[64:67]
	v_mfma_f32_16x16x32_bf16 v[116:119], v[208:211], v[176:179], v[116:119]
	v_mfma_f32_16x16x32_bf16 v[112:115], v[240:243], v[176:179], v[112:115]
	v_mfma_f32_16x16x32_bf16 v[100:103], v[208:211], v[184:187], v[100:103]
	v_mfma_f32_16x16x32_bf16 v[96:99], v[240:243], v[184:187], v[96:99]
	v_mfma_f32_16x16x32_bf16 v[84:87], v[208:211], v[192:195], v[84:87]
	v_mfma_f32_16x16x32_bf16 v[80:83], v[240:243], v[192:195], v[80:83]
	v_mfma_f32_16x16x32_bf16 v[68:71], v[208:211], v[200:203], v[68:71]
	v_mfma_f32_16x16x32_bf16 v[64:67], v[240:243], v[200:203], v[64:67]
	s_setprio 0
	s_mov_b32 m0, s28
	v_lshl_add_u64 v[216:217], v[246:247], 0, s[4:5]
	s_barrier
	ds_read_b128 v[158:161], v142 offset:49152
	v_xor_b32_e32 v203, 64, v142
	ds_read_b128 v[176:179], v203 offset:49152
	ds_read_b128 v[180:183], v142 offset:51200
	ds_read_b128 v[184:187], v203 offset:51200
	ds_read_b128 v[188:191], v142 offset:53248
	ds_read_b128 v[192:195], v203 offset:53248
	ds_read_b128 v[196:199], v142 offset:55296
	ds_read_b128 v[200:203], v203 offset:55296
	global_load_lds_dwordx4 v[216:217], off
	v_lshl_add_u64 v[216:217], v[248:249], 0, s[4:5]
	s_mov_b32 m0, s29
	s_nop 0
	global_load_lds_dwordx4 v[216:217], off
	s_barrier
	s_waitcnt lgkmcnt(0)
	s_setprio 1
	s_waitcnt lgkmcnt(0)
	v_mfma_f32_16x16x32_bf16 v[60:63], v[136:139], v[158:161], v[60:63]
	v_mfma_f32_16x16x32_bf16 v[56:59], v[150:153], v[158:161], v[56:59]
	v_mfma_f32_16x16x32_bf16 v[44:47], v[136:139], v[180:183], v[44:47]
	v_mfma_f32_16x16x32_bf16 v[40:43], v[150:153], v[180:183], v[40:43]
	v_mfma_f32_16x16x32_bf16 v[28:31], v[136:139], v[188:191], v[28:31]
	v_mfma_f32_16x16x32_bf16 v[24:27], v[150:153], v[188:191], v[24:27]
	v_mfma_f32_16x16x32_bf16 v[12:15], v[136:139], v[196:199], v[12:15]
	v_mfma_f32_16x16x32_bf16 v[8:11], v[150:153], v[196:199], v[8:11]
	v_mfma_f32_16x16x32_bf16 v[60:63], v[146:149], v[176:179], v[60:63]
	v_mfma_f32_16x16x32_bf16 v[56:59], v[154:157], v[176:179], v[56:59]
	v_mfma_f32_16x16x32_bf16 v[44:47], v[146:149], v[184:187], v[44:47]
	v_mfma_f32_16x16x32_bf16 v[40:43], v[154:157], v[184:187], v[40:43]
	v_mfma_f32_16x16x32_bf16 v[28:31], v[146:149], v[192:195], v[28:31]
	v_mfma_f32_16x16x32_bf16 v[24:27], v[154:157], v[192:195], v[24:27]
	v_mfma_f32_16x16x32_bf16 v[12:15], v[146:149], v[200:203], v[12:15]
	v_mfma_f32_16x16x32_bf16 v[8:11], v[154:157], v[200:203], v[8:11]
	s_setprio 0
	s_barrier
	s_add_u32 s8, s8, 0x160080
	s_addc_u32 s9, s9, 0
	s_add_i32 s16, s16, s20
	v_lshl_add_u64 v[136:137], s[8:9], 0, v[170:171]
	s_mov_b32 m0, s16
	s_nop 0
	global_load_lds_dwordx4 v[136:137], off
	v_lshl_add_u64 v[136:137], s[8:9], 0, v[174:175]
	s_add_i32 m0, s16, 0x2000
	s_nop 0
	global_load_lds_dwordx4 v[136:137], off
	s_waitcnt vmcnt(6)
	s_barrier
	s_setprio 1
	v_mfma_f32_16x16x32_bf16 v[52:55], v[204:207], v[158:161], v[52:55]
	v_mfma_f32_16x16x32_bf16 v[48:51], v[212:215], v[158:161], v[48:51]
	v_mfma_f32_16x16x32_bf16 v[36:39], v[204:207], v[180:183], v[36:39]
	v_mfma_f32_16x16x32_bf16 v[32:35], v[212:215], v[180:183], v[32:35]
	v_mfma_f32_16x16x32_bf16 v[20:23], v[204:207], v[188:191], v[20:23]
	v_mfma_f32_16x16x32_bf16 v[16:19], v[212:215], v[188:191], v[16:19]
	v_mfma_f32_16x16x32_bf16 v[4:7], v[204:207], v[196:199], v[4:7]
	v_mfma_f32_16x16x32_bf16 v[0:3], v[212:215], v[196:199], v[0:3]
	v_mfma_f32_16x16x32_bf16 v[52:55], v[208:211], v[176:179], v[52:55]
	v_mfma_f32_16x16x32_bf16 v[48:51], v[240:243], v[176:179], v[48:51]
	v_mfma_f32_16x16x32_bf16 v[36:39], v[208:211], v[184:187], v[36:39]
	v_mfma_f32_16x16x32_bf16 v[32:35], v[240:243], v[184:187], v[32:35]
	v_mfma_f32_16x16x32_bf16 v[20:23], v[208:211], v[192:195], v[20:23]
	v_mfma_f32_16x16x32_bf16 v[16:19], v[240:243], v[192:195], v[16:19]
	v_mfma_f32_16x16x32_bf16 v[4:7], v[208:211], v[200:203], v[4:7]
	v_mfma_f32_16x16x32_bf16 v[0:3], v[240:243], v[200:203], v[0:3]
	s_setprio 0
	s_add_i32 s41, s41, 2
	s_add_u32 s0, s0, 0x100
	s_addc_u32 s1, s1, 0
	s_add_u32 s39, s39, 0x100
	s_addc_u32 s40, s40, 0
	s_cmpk_gt_u32 s41, 0x55
	s_barrier
	s_cbranch_scc0 .LBB0_508
	v_lshl_add_u32 v217, s38, 8, v163
	v_add_u32_e32 v217, s26, v217
	v_lshlrev_b32_e32 v208, 2, v217
	v_lshl_add_u32 v214, v225, 3, s27
	v_lshl_add_u32 v214, s37, 8, v214
	v_lshl_add_u32 v209, v217, 11, v214
	v_lshlrev_b32_e32 v209, 1, v209
	v_lshlrev_b32_e32 v210, 1, v209
	v_lshl_add_u32 v217, v225, 4, v163
	v_xor_b32_e32 v215, 16, v217
	v_lshlrev_b32_e32 v215, 2, v215
	v_xor_b32_e32 v216, 32, v217
	v_lshlrev_b32_e32 v216, 2, v216
	v_add_u32_e32 v211, 0x0, v209
	global_load_dwordx4 v[176:179], v211, s[80:81]
	global_load_dwordx4 v[180:183], v211, s[80:81] offset:256
	v_add_u32_e32 v211, 0x10000, v209
	global_load_dwordx4 v[192:195], v211, s[80:81]
	global_load_dwordx4 v[196:199], v211, s[80:81] offset:256
	s_waitcnt vmcnt(2)
	v_lshlrev_b32_e32 v184, 16, v176
	v_and_b32_e32 v185, 0xffff0000, v176
	v_lshlrev_b32_e32 v186, 16, v177
	v_and_b32_e32 v187, 0xffff0000, v177
	v_lshlrev_b32_e32 v188, 16, v178
	v_and_b32_e32 v189, 0xffff0000, v178
	v_lshlrev_b32_e32 v190, 16, v179
	v_and_b32_e32 v191, 0xffff0000, v179
	v_pk_add_f32 v[124:125], v[124:125], v[184:185]
	v_pk_add_f32 v[126:127], v[126:127], v[186:187]
	v_pk_add_f32 v[120:121], v[120:121], v[188:189]
	v_pk_add_f32 v[122:123], v[122:123], v[190:191]
	v_mul_f32_e32 v213, v124, v124
	v_fmac_f32_e32 v213, v125, v125
	v_fmac_f32_e32 v213, v126, v126
	v_fmac_f32_e32 v213, v127, v127
	v_fmac_f32_e32 v213, v120, v120
	v_fmac_f32_e32 v213, v121, v121
	v_fmac_f32_e32 v213, v122, v122
	v_fmac_f32_e32 v213, v123, v123
	v_cvt_pk_bf16_f32 v176, v124, v125
	v_cvt_pk_bf16_f32 v177, v126, v127
	v_cvt_pk_bf16_f32 v178, v120, v121
	v_cvt_pk_bf16_f32 v179, v122, v123
	v_add_u32_e32 v217, 0x0, v209
	global_store_dwordx4 v217, v[176:179], s[80:81]
	v_lshlrev_b32_e32 v184, 16, v180
	v_and_b32_e32 v185, 0xffff0000, v180
	v_lshlrev_b32_e32 v186, 16, v181
	v_and_b32_e32 v187, 0xffff0000, v181
	v_lshlrev_b32_e32 v188, 16, v182
	v_and_b32_e32 v189, 0xffff0000, v182
	v_lshlrev_b32_e32 v190, 16, v183
	v_and_b32_e32 v191, 0xffff0000, v183
	v_pk_add_f32 v[116:117], v[116:117], v[184:185]
	v_pk_add_f32 v[118:119], v[118:119], v[186:187]
	v_pk_add_f32 v[112:113], v[112:113], v[188:189]
	v_pk_add_f32 v[114:115], v[114:115], v[190:191]
	v_fmac_f32_e32 v213, v116, v116
	v_fmac_f32_e32 v213, v117, v117
	v_fmac_f32_e32 v213, v118, v118
	v_fmac_f32_e32 v213, v119, v119
	v_fmac_f32_e32 v213, v112, v112
	v_fmac_f32_e32 v213, v113, v113
	v_fmac_f32_e32 v213, v114, v114
	v_fmac_f32_e32 v213, v115, v115
	v_cvt_pk_bf16_f32 v180, v116, v117
	v_cvt_pk_bf16_f32 v181, v118, v119
	v_cvt_pk_bf16_f32 v182, v112, v113
	v_cvt_pk_bf16_f32 v183, v114, v115
	global_store_dwordx4 v217, v[180:183], s[80:81] offset:256
	ds_bpermute_b32 v214, v215, v213
	s_waitcnt lgkmcnt(0)
	v_add_f32_e32 v213, v213, v214
	ds_bpermute_b32 v214, v216, v213
	s_waitcnt lgkmcnt(0)
	v_add_f32_e32 v213, v213, v214
	s_mov_b64 exec, 0xffff
	global_atomic_add_f32 v208, v213, s[14:15]
	s_mov_b64 exec, -1
	v_add_u32_e32 v211, 0x20000, v209
	global_load_dwordx4 v[176:179], v211, s[80:81]
	global_load_dwordx4 v[180:183], v211, s[80:81] offset:256
	s_waitcnt vmcnt(5)
	v_lshlrev_b32_e32 v200, 16, v192
	v_and_b32_e32 v201, 0xffff0000, v192
	v_lshlrev_b32_e32 v202, 16, v193
	v_and_b32_e32 v203, 0xffff0000, v193
	v_lshlrev_b32_e32 v204, 16, v194
	v_and_b32_e32 v205, 0xffff0000, v194
	v_lshlrev_b32_e32 v206, 16, v195
	v_and_b32_e32 v207, 0xffff0000, v195
	v_pk_add_f32 v[108:109], v[108:109], v[200:201]
	v_pk_add_f32 v[110:111], v[110:111], v[202:203]
	v_pk_add_f32 v[104:105], v[104:105], v[204:205]
	v_pk_add_f32 v[106:107], v[106:107], v[206:207]
	v_mul_f32_e32 v213, v108, v108
	v_fmac_f32_e32 v213, v109, v109
	v_fmac_f32_e32 v213, v110, v110
	v_fmac_f32_e32 v213, v111, v111
	v_fmac_f32_e32 v213, v104, v104
	v_fmac_f32_e32 v213, v105, v105
	v_fmac_f32_e32 v213, v106, v106
	v_fmac_f32_e32 v213, v107, v107
	v_cvt_pk_bf16_f32 v192, v108, v109
	v_cvt_pk_bf16_f32 v193, v110, v111
	v_cvt_pk_bf16_f32 v194, v104, v105
	v_cvt_pk_bf16_f32 v195, v106, v107
	v_add_u32_e32 v217, 0x10000, v209
	global_store_dwordx4 v217, v[192:195], s[80:81]
	v_lshlrev_b32_e32 v200, 16, v196
	v_and_b32_e32 v201, 0xffff0000, v196
	v_lshlrev_b32_e32 v202, 16, v197
	v_and_b32_e32 v203, 0xffff0000, v197
	v_lshlrev_b32_e32 v204, 16, v198
	v_and_b32_e32 v205, 0xffff0000, v198
	v_lshlrev_b32_e32 v206, 16, v199
	v_and_b32_e32 v207, 0xffff0000, v199
	v_pk_add_f32 v[100:101], v[100:101], v[200:201]
	v_pk_add_f32 v[102:103], v[102:103], v[202:203]
	v_pk_add_f32 v[96:97], v[96:97], v[204:205]
	v_pk_add_f32 v[98:99], v[98:99], v[206:207]
	v_fmac_f32_e32 v213, v100, v100
	v_fmac_f32_e32 v213, v101, v101
	v_fmac_f32_e32 v213, v102, v102
	v_fmac_f32_e32 v213, v103, v103
	v_fmac_f32_e32 v213, v96, v96
	v_fmac_f32_e32 v213, v97, v97
	v_fmac_f32_e32 v213, v98, v98
	v_fmac_f32_e32 v213, v99, v99
	v_cvt_pk_bf16_f32 v196, v100, v101
	v_cvt_pk_bf16_f32 v197, v102, v103
	v_cvt_pk_bf16_f32 v198, v96, v97
	v_cvt_pk_bf16_f32 v199, v98, v99
	global_store_dwordx4 v217, v[196:199], s[80:81] offset:256
	ds_bpermute_b32 v214, v215, v213
	s_waitcnt lgkmcnt(0)
	v_add_f32_e32 v213, v213, v214
	ds_bpermute_b32 v214, v216, v213
	s_waitcnt lgkmcnt(0)
	v_add_f32_e32 v213, v213, v214
	s_mov_b64 exec, 0xffff
	global_atomic_add_f32 v208, v213, s[14:15] offset:64
	s_mov_b64 exec, -1
	v_add_u32_e32 v211, 0x30000, v209
	global_load_dwordx4 v[192:195], v211, s[80:81]
	global_load_dwordx4 v[196:199], v211, s[80:81] offset:256
	s_waitcnt vmcnt(5)
	v_lshlrev_b32_e32 v184, 16, v176
	v_and_b32_e32 v185, 0xffff0000, v176
	v_lshlrev_b32_e32 v186, 16, v177
	v_and_b32_e32 v187, 0xffff0000, v177
	v_lshlrev_b32_e32 v188, 16, v178
	v_and_b32_e32 v189, 0xffff0000, v178
	v_lshlrev_b32_e32 v190, 16, v179
	v_and_b32_e32 v191, 0xffff0000, v179
	v_pk_add_f32 v[92:93], v[92:93], v[184:185]
	v_pk_add_f32 v[94:95], v[94:95], v[186:187]
	v_pk_add_f32 v[88:89], v[88:89], v[188:189]
	v_pk_add_f32 v[90:91], v[90:91], v[190:191]
	v_mul_f32_e32 v213, v92, v92
	v_fmac_f32_e32 v213, v93, v93
	v_fmac_f32_e32 v213, v94, v94
	v_fmac_f32_e32 v213, v95, v95
	v_fmac_f32_e32 v213, v88, v88
	v_fmac_f32_e32 v213, v89, v89
	v_fmac_f32_e32 v213, v90, v90
	v_fmac_f32_e32 v213, v91, v91
	v_cvt_pk_bf16_f32 v176, v92, v93
	v_cvt_pk_bf16_f32 v177, v94, v95
	v_cvt_pk_bf16_f32 v178, v88, v89
	v_cvt_pk_bf16_f32 v179, v90, v91
	v_add_u32_e32 v217, 0x20000, v209
	global_store_dwordx4 v217, v[176:179], s[80:81]
	v_lshlrev_b32_e32 v184, 16, v180
	v_and_b32_e32 v185, 0xffff0000, v180
	v_lshlrev_b32_e32 v186, 16, v181
	v_and_b32_e32 v187, 0xffff0000, v181
	v_lshlrev_b32_e32 v188, 16, v182
	v_and_b32_e32 v189, 0xffff0000, v182
	v_lshlrev_b32_e32 v190, 16, v183
	v_and_b32_e32 v191, 0xffff0000, v183
	v_pk_add_f32 v[84:85], v[84:85], v[184:185]
	v_pk_add_f32 v[86:87], v[86:87], v[186:187]
	v_pk_add_f32 v[80:81], v[80:81], v[188:189]
	v_pk_add_f32 v[82:83], v[82:83], v[190:191]
	v_fmac_f32_e32 v213, v84, v84
	v_fmac_f32_e32 v213, v85, v85
	v_fmac_f32_e32 v213, v86, v86
	v_fmac_f32_e32 v213, v87, v87
	v_fmac_f32_e32 v213, v80, v80
	v_fmac_f32_e32 v213, v81, v81
	v_fmac_f32_e32 v213, v82, v82
	v_fmac_f32_e32 v213, v83, v83
	v_cvt_pk_bf16_f32 v180, v84, v85
	v_cvt_pk_bf16_f32 v181, v86, v87
	v_cvt_pk_bf16_f32 v182, v80, v81
	v_cvt_pk_bf16_f32 v183, v82, v83
	global_store_dwordx4 v217, v[180:183], s[80:81] offset:256
	ds_bpermute_b32 v214, v215, v213
	s_waitcnt lgkmcnt(0)
	v_add_f32_e32 v213, v213, v214
	ds_bpermute_b32 v214, v216, v213
	s_waitcnt lgkmcnt(0)
	v_add_f32_e32 v213, v213, v214
	s_mov_b64 exec, 0xffff
	global_atomic_add_f32 v208, v213, s[14:15] offset:128
	s_mov_b64 exec, -1
	v_add_u32_e32 v211, 0x80000, v209
	global_load_dwordx4 v[176:179], v211, s[80:81]
	global_load_dwordx4 v[180:183], v211, s[80:81] offset:256
	s_waitcnt vmcnt(5)
	v_lshlrev_b32_e32 v200, 16, v192
	v_and_b32_e32 v201, 0xffff0000, v192
	v_lshlrev_b32_e32 v202, 16, v193
	v_and_b32_e32 v203, 0xffff0000, v193
	v_lshlrev_b32_e32 v204, 16, v194
	v_and_b32_e32 v205, 0xffff0000, v194
	v_lshlrev_b32_e32 v206, 16, v195
	v_and_b32_e32 v207, 0xffff0000, v195
	v_pk_add_f32 v[76:77], v[76:77], v[200:201]
	v_pk_add_f32 v[78:79], v[78:79], v[202:203]
	v_pk_add_f32 v[72:73], v[72:73], v[204:205]
	v_pk_add_f32 v[74:75], v[74:75], v[206:207]
	v_mul_f32_e32 v213, v76, v76
	v_fmac_f32_e32 v213, v77, v77
	v_fmac_f32_e32 v213, v78, v78
	v_fmac_f32_e32 v213, v79, v79
	v_fmac_f32_e32 v213, v72, v72
	v_fmac_f32_e32 v213, v73, v73
	v_fmac_f32_e32 v213, v74, v74
	v_fmac_f32_e32 v213, v75, v75
	v_cvt_pk_bf16_f32 v192, v76, v77
	v_cvt_pk_bf16_f32 v193, v78, v79
	v_cvt_pk_bf16_f32 v194, v72, v73
	v_cvt_pk_bf16_f32 v195, v74, v75
	v_add_u32_e32 v217, 0x30000, v209
	global_store_dwordx4 v217, v[192:195], s[80:81]
	v_lshlrev_b32_e32 v200, 16, v196
	v_and_b32_e32 v201, 0xffff0000, v196
	v_lshlrev_b32_e32 v202, 16, v197
	v_and_b32_e32 v203, 0xffff0000, v197
	v_lshlrev_b32_e32 v204, 16, v198
	v_and_b32_e32 v205, 0xffff0000, v198
	v_lshlrev_b32_e32 v206, 16, v199
	v_and_b32_e32 v207, 0xffff0000, v199
	v_pk_add_f32 v[68:69], v[68:69], v[200:201]
	v_pk_add_f32 v[70:71], v[70:71], v[202:203]
	v_pk_add_f32 v[64:65], v[64:65], v[204:205]
	v_pk_add_f32 v[66:67], v[66:67], v[206:207]
	v_fmac_f32_e32 v213, v68, v68
	v_fmac_f32_e32 v213, v69, v69
	v_fmac_f32_e32 v213, v70, v70
	v_fmac_f32_e32 v213, v71, v71
	v_fmac_f32_e32 v213, v64, v64
	v_fmac_f32_e32 v213, v65, v65
	v_fmac_f32_e32 v213, v66, v66
	v_fmac_f32_e32 v213, v67, v67
	v_cvt_pk_bf16_f32 v196, v68, v69
	v_cvt_pk_bf16_f32 v197, v70, v71
	v_cvt_pk_bf16_f32 v198, v64, v65
	v_cvt_pk_bf16_f32 v199, v66, v67
	global_store_dwordx4 v217, v[196:199], s[80:81] offset:256
	ds_bpermute_b32 v214, v215, v213
	s_waitcnt lgkmcnt(0)
	v_add_f32_e32 v213, v213, v214
	ds_bpermute_b32 v214, v216, v213
	s_waitcnt lgkmcnt(0)
	v_add_f32_e32 v213, v213, v214
	s_mov_b64 exec, 0xffff
	global_atomic_add_f32 v208, v213, s[14:15] offset:192
	s_mov_b64 exec, -1
	v_add_u32_e32 v211, 0x90000, v209
	global_load_dwordx4 v[192:195], v211, s[80:81]
	global_load_dwordx4 v[196:199], v211, s[80:81] offset:256
	s_waitcnt vmcnt(5)
	v_lshlrev_b32_e32 v184, 16, v176
	v_and_b32_e32 v185, 0xffff0000, v176
	v_lshlrev_b32_e32 v186, 16, v177
	v_and_b32_e32 v187, 0xffff0000, v177
	v_lshlrev_b32_e32 v188, 16, v178
	v_and_b32_e32 v189, 0xffff0000, v178
	v_lshlrev_b32_e32 v190, 16, v179
	v_and_b32_e32 v191, 0xffff0000, v179
	v_pk_add_f32 v[60:61], v[60:61], v[184:185]
	v_pk_add_f32 v[62:63], v[62:63], v[186:187]
	v_pk_add_f32 v[56:57], v[56:57], v[188:189]
	v_pk_add_f32 v[58:59], v[58:59], v[190:191]
	v_mul_f32_e32 v213, v60, v60
	v_fmac_f32_e32 v213, v61, v61
	v_fmac_f32_e32 v213, v62, v62
	v_fmac_f32_e32 v213, v63, v63
	v_fmac_f32_e32 v213, v56, v56
	v_fmac_f32_e32 v213, v57, v57
	v_fmac_f32_e32 v213, v58, v58
	v_fmac_f32_e32 v213, v59, v59
	v_cvt_pk_bf16_f32 v176, v60, v61
	v_cvt_pk_bf16_f32 v177, v62, v63
	v_cvt_pk_bf16_f32 v178, v56, v57
	v_cvt_pk_bf16_f32 v179, v58, v59
	v_add_u32_e32 v217, 0x80000, v209
	global_store_dwordx4 v217, v[176:179], s[80:81]
	v_lshlrev_b32_e32 v184, 16, v180
	v_and_b32_e32 v185, 0xffff0000, v180
	v_lshlrev_b32_e32 v186, 16, v181
	v_and_b32_e32 v187, 0xffff0000, v181
	v_lshlrev_b32_e32 v188, 16, v182
	v_and_b32_e32 v189, 0xffff0000, v182
	v_lshlrev_b32_e32 v190, 16, v183
	v_and_b32_e32 v191, 0xffff0000, v183
	v_pk_add_f32 v[52:53], v[52:53], v[184:185]
	v_pk_add_f32 v[54:55], v[54:55], v[186:187]
	v_pk_add_f32 v[48:49], v[48:49], v[188:189]
	v_pk_add_f32 v[50:51], v[50:51], v[190:191]
	v_fmac_f32_e32 v213, v52, v52
	v_fmac_f32_e32 v213, v53, v53
	v_fmac_f32_e32 v213, v54, v54
	v_fmac_f32_e32 v213, v55, v55
	v_fmac_f32_e32 v213, v48, v48
	v_fmac_f32_e32 v213, v49, v49
	v_fmac_f32_e32 v213, v50, v50
	v_fmac_f32_e32 v213, v51, v51
	v_cvt_pk_bf16_f32 v180, v52, v53
	v_cvt_pk_bf16_f32 v181, v54, v55
	v_cvt_pk_bf16_f32 v182, v48, v49
	v_cvt_pk_bf16_f32 v183, v50, v51
	global_store_dwordx4 v217, v[180:183], s[80:81] offset:256
	ds_bpermute_b32 v214, v215, v213
	s_waitcnt lgkmcnt(0)
	v_add_f32_e32 v213, v213, v214
	ds_bpermute_b32 v214, v216, v213
	s_waitcnt lgkmcnt(0)
	v_add_f32_e32 v213, v213, v214
	s_mov_b64 exec, 0xffff
	global_atomic_add_f32 v208, v213, s[14:15] offset:512
	s_mov_b64 exec, -1
	v_add_u32_e32 v211, 0xa0000, v209
	global_load_dwordx4 v[176:179], v211, s[80:81]
	global_load_dwordx4 v[180:183], v211, s[80:81] offset:256
	s_waitcnt vmcnt(5)
	v_lshlrev_b32_e32 v200, 16, v192
	v_and_b32_e32 v201, 0xffff0000, v192
	v_lshlrev_b32_e32 v202, 16, v193
	v_and_b32_e32 v203, 0xffff0000, v193
	v_lshlrev_b32_e32 v204, 16, v194
	v_and_b32_e32 v205, 0xffff0000, v194
	v_lshlrev_b32_e32 v206, 16, v195
	v_and_b32_e32 v207, 0xffff0000, v195
	v_pk_add_f32 v[44:45], v[44:45], v[200:201]
	v_pk_add_f32 v[46:47], v[46:47], v[202:203]
	v_pk_add_f32 v[40:41], v[40:41], v[204:205]
	v_pk_add_f32 v[42:43], v[42:43], v[206:207]
	v_mul_f32_e32 v213, v44, v44
	v_fmac_f32_e32 v213, v45, v45
	v_fmac_f32_e32 v213, v46, v46
	v_fmac_f32_e32 v213, v47, v47
	v_fmac_f32_e32 v213, v40, v40
	v_fmac_f32_e32 v213, v41, v41
	v_fmac_f32_e32 v213, v42, v42
	v_fmac_f32_e32 v213, v43, v43
	v_cvt_pk_bf16_f32 v192, v44, v45
	v_cvt_pk_bf16_f32 v193, v46, v47
	v_cvt_pk_bf16_f32 v194, v40, v41
	v_cvt_pk_bf16_f32 v195, v42, v43
	v_add_u32_e32 v217, 0x90000, v209
	global_store_dwordx4 v217, v[192:195], s[80:81]
	v_lshlrev_b32_e32 v200, 16, v196
	v_and_b32_e32 v201, 0xffff0000, v196
	v_lshlrev_b32_e32 v202, 16, v197
	v_and_b32_e32 v203, 0xffff0000, v197
	v_lshlrev_b32_e32 v204, 16, v198
	v_and_b32_e32 v205, 0xffff0000, v198
	v_lshlrev_b32_e32 v206, 16, v199
	v_and_b32_e32 v207, 0xffff0000, v199
	v_pk_add_f32 v[36:37], v[36:37], v[200:201]
	v_pk_add_f32 v[38:39], v[38:39], v[202:203]
	v_pk_add_f32 v[32:33], v[32:33], v[204:205]
	v_pk_add_f32 v[34:35], v[34:35], v[206:207]
	v_fmac_f32_e32 v213, v36, v36
	v_fmac_f32_e32 v213, v37, v37
	v_fmac_f32_e32 v213, v38, v38
	v_fmac_f32_e32 v213, v39, v39
	v_fmac_f32_e32 v213, v32, v32
	v_fmac_f32_e32 v213, v33, v33
	v_fmac_f32_e32 v213, v34, v34
	v_fmac_f32_e32 v213, v35, v35
	v_cvt_pk_bf16_f32 v196, v36, v37
	v_cvt_pk_bf16_f32 v197, v38, v39
	v_cvt_pk_bf16_f32 v198, v32, v33
	v_cvt_pk_bf16_f32 v199, v34, v35
	global_store_dwordx4 v217, v[196:199], s[80:81] offset:256
	ds_bpermute_b32 v214, v215, v213
	s_waitcnt lgkmcnt(0)
	v_add_f32_e32 v213, v213, v214
	ds_bpermute_b32 v214, v216, v213
	s_waitcnt lgkmcnt(0)
	v_add_f32_e32 v213, v213, v214
	s_mov_b64 exec, 0xffff
	global_atomic_add_f32 v208, v213, s[14:15] offset:576
	s_mov_b64 exec, -1
	v_add_u32_e32 v211, 0xb0000, v209
	global_load_dwordx4 v[192:195], v211, s[80:81]
	global_load_dwordx4 v[196:199], v211, s[80:81] offset:256
	s_waitcnt vmcnt(5)
	v_lshlrev_b32_e32 v184, 16, v176
	v_and_b32_e32 v185, 0xffff0000, v176
	v_lshlrev_b32_e32 v186, 16, v177
	v_and_b32_e32 v187, 0xffff0000, v177
	v_lshlrev_b32_e32 v188, 16, v178
	v_and_b32_e32 v189, 0xffff0000, v178
	v_lshlrev_b32_e32 v190, 16, v179
	v_and_b32_e32 v191, 0xffff0000, v179
	v_pk_add_f32 v[28:29], v[28:29], v[184:185]
	v_pk_add_f32 v[30:31], v[30:31], v[186:187]
	v_pk_add_f32 v[24:25], v[24:25], v[188:189]
	v_pk_add_f32 v[26:27], v[26:27], v[190:191]
	v_mul_f32_e32 v213, v28, v28
	v_fmac_f32_e32 v213, v29, v29
	v_fmac_f32_e32 v213, v30, v30
	v_fmac_f32_e32 v213, v31, v31
	v_fmac_f32_e32 v213, v24, v24
	v_fmac_f32_e32 v213, v25, v25
	v_fmac_f32_e32 v213, v26, v26
	v_fmac_f32_e32 v213, v27, v27
	v_cvt_pk_bf16_f32 v176, v28, v29
	v_cvt_pk_bf16_f32 v177, v30, v31
	v_cvt_pk_bf16_f32 v178, v24, v25
	v_cvt_pk_bf16_f32 v179, v26, v27
	v_add_u32_e32 v217, 0xa0000, v209
	global_store_dwordx4 v217, v[176:179], s[80:81]
	v_lshlrev_b32_e32 v184, 16, v180
	v_and_b32_e32 v185, 0xffff0000, v180
	v_lshlrev_b32_e32 v186, 16, v181
	v_and_b32_e32 v187, 0xffff0000, v181
	v_lshlrev_b32_e32 v188, 16, v182
	v_and_b32_e32 v189, 0xffff0000, v182
	v_lshlrev_b32_e32 v190, 16, v183
	v_and_b32_e32 v191, 0xffff0000, v183
	v_pk_add_f32 v[20:21], v[20:21], v[184:185]
	v_pk_add_f32 v[22:23], v[22:23], v[186:187]
	v_pk_add_f32 v[16:17], v[16:17], v[188:189]
	v_pk_add_f32 v[18:19], v[18:19], v[190:191]
	v_fmac_f32_e32 v213, v20, v20
	v_fmac_f32_e32 v213, v21, v21
	v_fmac_f32_e32 v213, v22, v22
	v_fmac_f32_e32 v213, v23, v23
	v_fmac_f32_e32 v213, v16, v16
	v_fmac_f32_e32 v213, v17, v17
	v_fmac_f32_e32 v213, v18, v18
	v_fmac_f32_e32 v213, v19, v19
	v_cvt_pk_bf16_f32 v180, v20, v21
	v_cvt_pk_bf16_f32 v181, v22, v23
	v_cvt_pk_bf16_f32 v182, v16, v17
	v_cvt_pk_bf16_f32 v183, v18, v19
	global_store_dwordx4 v217, v[180:183], s[80:81] offset:256
	ds_bpermute_b32 v214, v215, v213
	s_waitcnt lgkmcnt(0)
	v_add_f32_e32 v213, v213, v214
	ds_bpermute_b32 v214, v216, v213
	s_waitcnt lgkmcnt(0)
	v_add_f32_e32 v213, v213, v214
	s_mov_b64 exec, 0xffff
	global_atomic_add_f32 v208, v213, s[14:15] offset:640
	s_mov_b64 exec, -1
	s_waitcnt vmcnt(3)
	v_lshlrev_b32_e32 v200, 16, v192
	v_and_b32_e32 v201, 0xffff0000, v192
	v_lshlrev_b32_e32 v202, 16, v193
	v_and_b32_e32 v203, 0xffff0000, v193
	v_lshlrev_b32_e32 v204, 16, v194
	v_and_b32_e32 v205, 0xffff0000, v194
	v_lshlrev_b32_e32 v206, 16, v195
	v_and_b32_e32 v207, 0xffff0000, v195
	v_pk_add_f32 v[12:13], v[12:13], v[200:201]
	v_pk_add_f32 v[14:15], v[14:15], v[202:203]
	v_pk_add_f32 v[8:9], v[8:9], v[204:205]
	v_pk_add_f32 v[10:11], v[10:11], v[206:207]
	v_mul_f32_e32 v213, v12, v12
	v_fmac_f32_e32 v213, v13, v13
	v_fmac_f32_e32 v213, v14, v14
	v_fmac_f32_e32 v213, v15, v15
	v_fmac_f32_e32 v213, v8, v8
	v_fmac_f32_e32 v213, v9, v9
	v_fmac_f32_e32 v213, v10, v10
	v_fmac_f32_e32 v213, v11, v11
	v_cvt_pk_bf16_f32 v192, v12, v13
	v_cvt_pk_bf16_f32 v193, v14, v15
	v_cvt_pk_bf16_f32 v194, v8, v9
	v_cvt_pk_bf16_f32 v195, v10, v11
	v_add_u32_e32 v217, 0xb0000, v209
	global_store_dwordx4 v217, v[192:195], s[80:81]
	v_lshlrev_b32_e32 v200, 16, v196
	v_and_b32_e32 v201, 0xffff0000, v196
	v_lshlrev_b32_e32 v202, 16, v197
	v_and_b32_e32 v203, 0xffff0000, v197
	v_lshlrev_b32_e32 v204, 16, v198
	v_and_b32_e32 v205, 0xffff0000, v198
	v_lshlrev_b32_e32 v206, 16, v199
	v_and_b32_e32 v207, 0xffff0000, v199
	v_pk_add_f32 v[4:5], v[4:5], v[200:201]
	v_pk_add_f32 v[6:7], v[6:7], v[202:203]
	v_pk_add_f32 v[0:1], v[0:1], v[204:205]
	v_pk_add_f32 v[2:3], v[2:3], v[206:207]
	v_fmac_f32_e32 v213, v4, v4
	v_fmac_f32_e32 v213, v5, v5
	v_fmac_f32_e32 v213, v6, v6
	v_fmac_f32_e32 v213, v7, v7
	v_fmac_f32_e32 v213, v0, v0
	v_fmac_f32_e32 v213, v1, v1
	v_fmac_f32_e32 v213, v2, v2
	v_fmac_f32_e32 v213, v3, v3
	v_cvt_pk_bf16_f32 v196, v4, v5
	v_cvt_pk_bf16_f32 v197, v6, v7
	v_cvt_pk_bf16_f32 v198, v0, v1
	v_cvt_pk_bf16_f32 v199, v2, v3
	global_store_dwordx4 v217, v[196:199], s[80:81] offset:256
	ds_bpermute_b32 v214, v215, v213
	s_waitcnt lgkmcnt(0)
	v_add_f32_e32 v213, v213, v214
	ds_bpermute_b32 v214, v216, v213
	s_waitcnt lgkmcnt(0)
	v_add_f32_e32 v213, v213, v214
	s_mov_b64 exec, 0xffff
	global_atomic_add_f32 v208, v213, s[14:15] offset:704
	s_mov_b64 exec, -1
	s_branch .LBB0_496

.LBB0_599:
	ds_read_b128 v[140:143], v149
	v_xor_b32_e32 v179, 64, v149
	ds_read_b128 v[154:157], v179
	ds_read_b128 v[158:161], v149 offset:2048
	ds_read_b128 v[176:179], v179 offset:2048
	s_add_u32 s28, s26, 0xfff80080
	s_addc_u32 s29, s27, -1
	s_cmp_eq_u32 s49, 28
	s_cselect_b32 s31, s1, s29
	s_cselect_b32 s30, s13, s28
	s_cselect_b32 s29, s19, s48
	s_cselect_b32 s28, s21, s33
	v_lshl_add_u64 v[144:145], s[26:27], 0, v[132:133]
	s_add_i32 m0, s37, 0xc000
	ds_read_b128 v[180:183], v150
	v_xor_b32_e32 v211, 64, v150
	ds_read_b128 v[184:187], v211
	ds_read_b128 v[188:191], v150 offset:2048
	ds_read_b128 v[192:195], v211 offset:2048
	ds_read_b128 v[196:199], v150 offset:4096
	ds_read_b128 v[200:203], v211 offset:4096
	ds_read_b128 v[204:207], v150 offset:6144
	ds_read_b128 v[208:211], v211 offset:6144
	global_load_lds_dwordx4 v[144:145], off
	v_lshl_add_u64 v[144:145], s[26:27], 0, v[134:135]
	s_add_i32 m0, s37, 0xe000
	s_nop 0
	global_load_lds_dwordx4 v[144:145], off
	s_waitcnt lgkmcnt(8)
	s_barrier
	s_waitcnt lgkmcnt(0)
	s_setprio 1
	s_waitcnt lgkmcnt(0)
	v_mfma_f32_16x16x32_bf16 v[124:127], v[140:143], v[180:183], v[124:127]
	v_mfma_f32_16x16x32_bf16 v[120:123], v[158:161], v[180:183], v[120:123]
	v_mfma_f32_16x16x32_bf16 v[108:111], v[140:143], v[188:191], v[108:111]
	v_mfma_f32_16x16x32_bf16 v[104:107], v[158:161], v[188:191], v[104:107]
	v_mfma_f32_16x16x32_bf16 v[92:95], v[140:143], v[196:199], v[92:95]
	v_mfma_f32_16x16x32_bf16 v[88:91], v[158:161], v[196:199], v[88:91]
	v_mfma_f32_16x16x32_bf16 v[76:79], v[140:143], v[204:207], v[76:79]
	v_mfma_f32_16x16x32_bf16 v[72:75], v[158:161], v[204:207], v[72:75]
	v_mfma_f32_16x16x32_bf16 v[124:127], v[154:157], v[184:187], v[124:127]
	v_mfma_f32_16x16x32_bf16 v[120:123], v[176:179], v[184:187], v[120:123]
	v_mfma_f32_16x16x32_bf16 v[108:111], v[154:157], v[192:195], v[108:111]
	v_mfma_f32_16x16x32_bf16 v[104:107], v[176:179], v[192:195], v[104:107]
	v_mfma_f32_16x16x32_bf16 v[92:95], v[154:157], v[200:203], v[92:95]
	v_mfma_f32_16x16x32_bf16 v[88:91], v[176:179], v[200:203], v[88:91]
	v_mfma_f32_16x16x32_bf16 v[76:79], v[154:157], v[208:211], v[76:79]
	v_mfma_f32_16x16x32_bf16 v[72:75], v[176:179], v[208:211], v[72:75]
	s_setprio 0
	s_barrier
	s_add_i32 s52, s46, s36
	v_lshl_add_u64 v[144:145], s[28:29], 0, v[164:165]
	s_mov_b32 m0, s52
	ds_read_b128 v[212:215], v151
	v_xor_b32_e32 v251, 64, v151
	ds_read_b128 v[240:243], v251
	ds_read_b128 v[244:247], v151 offset:2048
	ds_read_b128 v[248:251], v251 offset:2048
	global_load_lds_dwordx4 v[144:145], off
	v_lshl_add_u64 v[216:217], s[28:29], 0, v[166:167]
	s_add_i32 m0, s52, 0x2000
	s_nop 0
	global_load_lds_dwordx4 v[216:217], off
	s_barrier
	s_waitcnt lgkmcnt(0)
	s_setprio 1
	s_waitcnt lgkmcnt(0)
	v_mfma_f32_16x16x32_bf16 v[116:119], v[212:215], v[180:183], v[116:119]
	v_mfma_f32_16x16x32_bf16 v[112:115], v[244:247], v[180:183], v[112:115]
	v_mfma_f32_16x16x32_bf16 v[100:103], v[212:215], v[188:191], v[100:103]
	v_mfma_f32_16x16x32_bf16 v[96:99], v[244:247], v[188:191], v[96:99]
	v_mfma_f32_16x16x32_bf16 v[84:87], v[212:215], v[196:199], v[84:87]
	v_mfma_f32_16x16x32_bf16 v[80:83], v[244:247], v[196:199], v[80:83]
	v_mfma_f32_16x16x32_bf16 v[68:71], v[212:215], v[204:207], v[68:71]
	v_mfma_f32_16x16x32_bf16 v[64:67], v[244:247], v[204:207], v[64:67]
	v_mfma_f32_16x16x32_bf16 v[116:119], v[240:243], v[184:187], v[116:119]
	v_mfma_f32_16x16x32_bf16 v[112:115], v[248:251], v[184:187], v[112:115]
	v_mfma_f32_16x16x32_bf16 v[100:103], v[240:243], v[192:195], v[100:103]
	v_mfma_f32_16x16x32_bf16 v[96:99], v[248:251], v[192:195], v[96:99]
	v_mfma_f32_16x16x32_bf16 v[84:87], v[240:243], v[200:203], v[84:87]
	v_mfma_f32_16x16x32_bf16 v[80:83], v[248:251], v[200:203], v[80:83]
	v_mfma_f32_16x16x32_bf16 v[68:71], v[240:243], v[208:211], v[68:71]
	v_mfma_f32_16x16x32_bf16 v[64:67], v[248:251], v[208:211], v[64:67]
	s_setprio 0
	s_mov_b32 m0, s37
	v_lshl_add_u64 v[252:253], s[30:31], 0, v[128:129]
	s_barrier
	ds_read_b128 v[180:183], v150 offset:16384
	v_xor_b32_e32 v211, 64, v150
	ds_read_b128 v[184:187], v211 offset:16384
	ds_read_b128 v[188:191], v150 offset:18432
	ds_read_b128 v[192:195], v211 offset:18432
	ds_read_b128 v[196:199], v150 offset:20480
	ds_read_b128 v[200:203], v211 offset:20480
	ds_read_b128 v[204:207], v150 offset:22528
	ds_read_b128 v[208:211], v211 offset:22528
	global_load_lds_dwordx4 v[252:253], off
	v_lshl_add_u64 v[234:235], s[30:31], 0, v[130:131]
	s_mov_b32 m0, s38
	s_nop 0
	global_load_lds_dwordx4 v[234:235], off
	s_barrier
	s_waitcnt lgkmcnt(0)
	s_setprio 1
	s_waitcnt lgkmcnt(0)
	v_mfma_f32_16x16x32_bf16 v[60:63], v[140:143], v[180:183], v[60:63]
	v_mfma_f32_16x16x32_bf16 v[56:59], v[158:161], v[180:183], v[56:59]
	v_mfma_f32_16x16x32_bf16 v[44:47], v[140:143], v[188:191], v[44:47]
	v_mfma_f32_16x16x32_bf16 v[40:43], v[158:161], v[188:191], v[40:43]
	v_mfma_f32_16x16x32_bf16 v[28:31], v[140:143], v[196:199], v[28:31]
	v_mfma_f32_16x16x32_bf16 v[24:27], v[158:161], v[196:199], v[24:27]
	v_mfma_f32_16x16x32_bf16 v[12:15], v[140:143], v[204:207], v[12:15]
	v_mfma_f32_16x16x32_bf16 v[8:11], v[158:161], v[204:207], v[8:11]
	v_mfma_f32_16x16x32_bf16 v[60:63], v[154:157], v[184:187], v[60:63]
	v_mfma_f32_16x16x32_bf16 v[56:59], v[176:179], v[184:187], v[56:59]
	v_mfma_f32_16x16x32_bf16 v[44:47], v[154:157], v[192:195], v[44:47]
	v_mfma_f32_16x16x32_bf16 v[40:43], v[176:179], v[192:195], v[40:43]
	v_mfma_f32_16x16x32_bf16 v[28:31], v[154:157], v[200:203], v[28:31]
	v_mfma_f32_16x16x32_bf16 v[24:27], v[176:179], v[200:203], v[24:27]
	v_mfma_f32_16x16x32_bf16 v[12:15], v[154:157], v[208:211], v[12:15]
	v_mfma_f32_16x16x32_bf16 v[8:11], v[176:179], v[208:211], v[8:11]
	s_setprio 0
	s_barrier
	s_add_u32 s52, s28, 0x80000
	s_addc_u32 s53, s29, 0
	s_add_i32 s54, s47, s36
	v_lshl_add_u64 v[140:141], s[52:53], 0, v[164:165]
	s_mov_b32 m0, s54
	s_nop 0
	global_load_lds_dwordx4 v[140:141], off
	v_lshl_add_u64 v[140:141], s[52:53], 0, v[166:167]
	s_add_i32 m0, s54, 0x2000
	s_nop 0
	global_load_lds_dwordx4 v[140:141], off
	s_waitcnt vmcnt(6)
	s_barrier
	s_setprio 1
	v_mfma_f32_16x16x32_bf16 v[52:55], v[212:215], v[180:183], v[52:55]
	v_mfma_f32_16x16x32_bf16 v[48:51], v[244:247], v[180:183], v[48:51]
	v_mfma_f32_16x16x32_bf16 v[36:39], v[212:215], v[188:191], v[36:39]
	v_mfma_f32_16x16x32_bf16 v[32:35], v[244:247], v[188:191], v[32:35]
	v_mfma_f32_16x16x32_bf16 v[20:23], v[212:215], v[196:199], v[20:23]
	v_mfma_f32_16x16x32_bf16 v[16:19], v[244:247], v[196:199], v[16:19]
	v_mfma_f32_16x16x32_bf16 v[4:7], v[212:215], v[204:207], v[4:7]
	v_mfma_f32_16x16x32_bf16 v[0:3], v[244:247], v[204:207], v[0:3]
	v_mfma_f32_16x16x32_bf16 v[52:55], v[240:243], v[184:187], v[52:55]
	v_mfma_f32_16x16x32_bf16 v[48:51], v[248:251], v[184:187], v[48:51]
	v_mfma_f32_16x16x32_bf16 v[36:39], v[240:243], v[192:195], v[36:39]
	v_mfma_f32_16x16x32_bf16 v[32:35], v[248:251], v[192:195], v[32:35]
	v_mfma_f32_16x16x32_bf16 v[20:23], v[240:243], v[200:203], v[20:23]
	v_mfma_f32_16x16x32_bf16 v[16:19], v[248:251], v[200:203], v[16:19]
	v_mfma_f32_16x16x32_bf16 v[4:7], v[240:243], v[208:211], v[4:7]
	v_mfma_f32_16x16x32_bf16 v[0:3], v[248:251], v[208:211], v[0:3]
	s_setprio 0
	s_add_i32 s52, 0, 0x18000
	v_add_u32_e32 v169, s52, v147
	s_barrier
	ds_read_b128 v[140:143], v169
	v_xor_b32_e32 v179, 64, v169
	ds_read_b128 v[154:157], v179
	ds_read_b128 v[158:161], v169 offset:2048
	ds_read_b128 v[176:179], v179 offset:2048
	s_add_u32 s30, s30, 0x80000
	s_addc_u32 s31, s31, 0
	s_mov_b32 m0, s39
	v_lshl_add_u64 v[212:213], s[30:31], 0, v[128:129]
	ds_read_b128 v[180:183], v150 offset:32768
	v_xor_b32_e32 v211, 64, v150
	ds_read_b128 v[184:187], v211 offset:32768
	ds_read_b128 v[188:191], v150 offset:34816
	ds_read_b128 v[192:195], v211 offset:34816
	ds_read_b128 v[196:199], v150 offset:36864
	ds_read_b128 v[200:203], v211 offset:36864
	ds_read_b128 v[204:207], v150 offset:38912
	ds_read_b128 v[208:211], v211 offset:38912
	global_load_lds_dwordx4 v[212:213], off
	v_lshl_add_u64 v[212:213], s[30:31], 0, v[130:131]
	s_mov_b32 m0, s40
	s_nop 0
	global_load_lds_dwordx4 v[212:213], off
	s_waitcnt lgkmcnt(8)
	s_barrier
	s_waitcnt lgkmcnt(0)
	s_setprio 1
	s_waitcnt lgkmcnt(0)
	v_mfma_f32_16x16x32_bf16 v[124:127], v[140:143], v[180:183], v[124:127]
	v_mfma_f32_16x16x32_bf16 v[120:123], v[158:161], v[180:183], v[120:123]
	v_mfma_f32_16x16x32_bf16 v[108:111], v[140:143], v[188:191], v[108:111]
	v_mfma_f32_16x16x32_bf16 v[104:107], v[158:161], v[188:191], v[104:107]
	v_mfma_f32_16x16x32_bf16 v[92:95], v[140:143], v[196:199], v[92:95]
	v_mfma_f32_16x16x32_bf16 v[88:91], v[158:161], v[196:199], v[88:91]
	v_mfma_f32_16x16x32_bf16 v[76:79], v[140:143], v[204:207], v[76:79]
	v_mfma_f32_16x16x32_bf16 v[72:75], v[158:161], v[204:207], v[72:75]
	v_mfma_f32_16x16x32_bf16 v[124:127], v[154:157], v[184:187], v[124:127]
	v_mfma_f32_16x16x32_bf16 v[120:123], v[176:179], v[184:187], v[120:123]
	v_mfma_f32_16x16x32_bf16 v[108:111], v[154:157], v[192:195], v[108:111]
	v_mfma_f32_16x16x32_bf16 v[104:107], v[176:179], v[192:195], v[104:107]
	v_mfma_f32_16x16x32_bf16 v[92:95], v[154:157], v[200:203], v[92:95]
	v_mfma_f32_16x16x32_bf16 v[88:91], v[176:179], v[200:203], v[88:91]
	v_mfma_f32_16x16x32_bf16 v[76:79], v[154:157], v[208:211], v[76:79]
	v_mfma_f32_16x16x32_bf16 v[72:75], v[176:179], v[208:211], v[72:75]
	s_setprio 0
	s_barrier
	s_add_i32 s30, 0, 0x1c000
	s_add_i32 s31, s52, s36
	v_add_u32_e32 v169, s30, v147
	v_lshl_add_u64 v[144:145], v[144:145], 0, s[16:17]
	s_mov_b32 m0, s31
	ds_read_b128 v[212:215], v169
	v_xor_b32_e32 v251, 64, v169
	ds_read_b128 v[240:243], v251
	ds_read_b128 v[244:247], v169 offset:2048
	ds_read_b128 v[248:251], v251 offset:2048
	global_load_lds_dwordx4 v[144:145], off
	v_lshl_add_u64 v[144:145], v[216:217], 0, s[16:17]
	s_add_i32 m0, s31, 0x2000
	s_nop 0
	global_load_lds_dwordx4 v[144:145], off
	s_barrier
	s_waitcnt lgkmcnt(0)
	s_setprio 1
	s_waitcnt lgkmcnt(0)
	v_mfma_f32_16x16x32_bf16 v[116:119], v[212:215], v[180:183], v[116:119]
	v_mfma_f32_16x16x32_bf16 v[112:115], v[244:247], v[180:183], v[112:115]
	v_mfma_f32_16x16x32_bf16 v[100:103], v[212:215], v[188:191], v[100:103]
	v_mfma_f32_16x16x32_bf16 v[96:99], v[244:247], v[188:191], v[96:99]
	v_mfma_f32_16x16x32_bf16 v[84:87], v[212:215], v[196:199], v[84:87]
	v_mfma_f32_16x16x32_bf16 v[80:83], v[244:247], v[196:199], v[80:83]
	v_mfma_f32_16x16x32_bf16 v[68:71], v[212:215], v[204:207], v[68:71]
	v_mfma_f32_16x16x32_bf16 v[64:67], v[244:247], v[204:207], v[64:67]
	v_mfma_f32_16x16x32_bf16 v[116:119], v[240:243], v[184:187], v[116:119]
	v_mfma_f32_16x16x32_bf16 v[112:115], v[248:251], v[184:187], v[112:115]
	v_mfma_f32_16x16x32_bf16 v[100:103], v[240:243], v[192:195], v[100:103]
	v_mfma_f32_16x16x32_bf16 v[96:99], v[248:251], v[192:195], v[96:99]
	v_mfma_f32_16x16x32_bf16 v[84:87], v[240:243], v[200:203], v[84:87]
	v_mfma_f32_16x16x32_bf16 v[80:83], v[248:251], v[200:203], v[80:83]
	v_mfma_f32_16x16x32_bf16 v[68:71], v[240:243], v[208:211], v[68:71]
	v_mfma_f32_16x16x32_bf16 v[64:67], v[248:251], v[208:211], v[64:67]
	s_setprio 0
	s_mov_b32 m0, s42
	v_lshl_add_u64 v[144:145], v[252:253], 0, s[16:17]
	s_barrier
	ds_read_b128 v[180:183], v150 offset:49152
	v_xor_b32_e32 v211, 64, v150
	ds_read_b128 v[184:187], v211 offset:49152
	ds_read_b128 v[188:191], v150 offset:51200
	ds_read_b128 v[192:195], v211 offset:51200
	ds_read_b128 v[196:199], v150 offset:53248
	ds_read_b128 v[200:203], v211 offset:53248
	ds_read_b128 v[204:207], v150 offset:55296
	ds_read_b128 v[208:211], v211 offset:55296
	global_load_lds_dwordx4 v[144:145], off
	v_lshl_add_u64 v[144:145], v[234:235], 0, s[16:17]
	s_mov_b32 m0, s43
	s_nop 0
	global_load_lds_dwordx4 v[144:145], off
	s_barrier
	s_waitcnt lgkmcnt(0)
	s_setprio 1
	s_waitcnt lgkmcnt(0)
	v_mfma_f32_16x16x32_bf16 v[60:63], v[140:143], v[180:183], v[60:63]
	v_mfma_f32_16x16x32_bf16 v[56:59], v[158:161], v[180:183], v[56:59]
	v_mfma_f32_16x16x32_bf16 v[44:47], v[140:143], v[188:191], v[44:47]
	v_mfma_f32_16x16x32_bf16 v[40:43], v[158:161], v[188:191], v[40:43]
	v_mfma_f32_16x16x32_bf16 v[28:31], v[140:143], v[196:199], v[28:31]
	v_mfma_f32_16x16x32_bf16 v[24:27], v[158:161], v[196:199], v[24:27]
	v_mfma_f32_16x16x32_bf16 v[12:15], v[140:143], v[204:207], v[12:15]
	v_mfma_f32_16x16x32_bf16 v[8:11], v[158:161], v[204:207], v[8:11]
	v_mfma_f32_16x16x32_bf16 v[60:63], v[154:157], v[184:187], v[60:63]
	v_mfma_f32_16x16x32_bf16 v[56:59], v[176:179], v[184:187], v[56:59]
	v_mfma_f32_16x16x32_bf16 v[44:47], v[154:157], v[192:195], v[44:47]
	v_mfma_f32_16x16x32_bf16 v[40:43], v[176:179], v[192:195], v[40:43]
	v_mfma_f32_16x16x32_bf16 v[28:31], v[154:157], v[200:203], v[28:31]
	v_mfma_f32_16x16x32_bf16 v[24:27], v[176:179], v[200:203], v[24:27]
	v_mfma_f32_16x16x32_bf16 v[12:15], v[154:157], v[208:211], v[12:15]
	v_mfma_f32_16x16x32_bf16 v[8:11], v[176:179], v[208:211], v[8:11]
	s_setprio 0
	s_barrier
	s_add_u32 s28, s28, 0x80080
	s_addc_u32 s29, s29, 0
	s_add_i32 s30, s30, s36
	v_lshl_add_u64 v[140:141], s[28:29], 0, v[164:165]
	s_mov_b32 m0, s30
	s_nop 0
	global_load_lds_dwordx4 v[140:141], off
	v_lshl_add_u64 v[140:141], s[28:29], 0, v[166:167]
	s_add_i32 m0, s30, 0x2000
	s_nop 0
	global_load_lds_dwordx4 v[140:141], off
	s_waitcnt vmcnt(6)
	s_barrier
	s_setprio 1
	v_mfma_f32_16x16x32_bf16 v[52:55], v[212:215], v[180:183], v[52:55]
	v_mfma_f32_16x16x32_bf16 v[48:51], v[244:247], v[180:183], v[48:51]
	v_mfma_f32_16x16x32_bf16 v[36:39], v[212:215], v[188:191], v[36:39]
	v_mfma_f32_16x16x32_bf16 v[32:35], v[244:247], v[188:191], v[32:35]
	v_mfma_f32_16x16x32_bf16 v[20:23], v[212:215], v[196:199], v[20:23]
	v_mfma_f32_16x16x32_bf16 v[16:19], v[244:247], v[196:199], v[16:19]
	v_mfma_f32_16x16x32_bf16 v[4:7], v[212:215], v[204:207], v[4:7]
	v_mfma_f32_16x16x32_bf16 v[0:3], v[244:247], v[204:207], v[0:3]
	v_mfma_f32_16x16x32_bf16 v[52:55], v[240:243], v[184:187], v[52:55]
	v_mfma_f32_16x16x32_bf16 v[48:51], v[248:251], v[184:187], v[48:51]
	v_mfma_f32_16x16x32_bf16 v[36:39], v[240:243], v[192:195], v[36:39]
	v_mfma_f32_16x16x32_bf16 v[32:35], v[248:251], v[192:195], v[32:35]
	v_mfma_f32_16x16x32_bf16 v[20:23], v[240:243], v[200:203], v[20:23]
	v_mfma_f32_16x16x32_bf16 v[16:19], v[248:251], v[200:203], v[16:19]
	v_mfma_f32_16x16x32_bf16 v[4:7], v[240:243], v[208:211], v[4:7]
	v_mfma_f32_16x16x32_bf16 v[0:3], v[248:251], v[208:211], v[0:3]
	s_setprio 0
	s_add_i32 s49, s49, 2
	s_add_u32 s26, s26, 0x100
	s_addc_u32 s27, s27, 0
	s_add_u32 s33, s33, 0x100
	s_addc_u32 s48, s48, 0
	s_cmp_gt_u32 s49, 29
	s_barrier
	s_cbranch_scc0 .LBB0_599
	v_lshl_add_u32 v142, s12, 8, v146
	v_ashrrev_i32_e32 v143, 31, v142
	v_lshl_add_u64 v[144:145], v[142:143], 2, s[14:15]
	global_load_dword v179, v[144:145], off
	global_load_dword v180, v[144:145], off offset:64
	global_load_dword v181, v[144:145], off offset:128
	global_load_dword v182, v[144:145], off offset:192
	global_load_dword v183, v[144:145], off offset:512
	global_load_dword v184, v[144:145], off offset:576
	global_load_dword v185, v[144:145], off offset:640
	global_load_dword v186, v[144:145], off offset:704
	v_lshl_or_b32 v140, s0, 8, v148
	v_lshlrev_b64 v[156:157], 13, v[142:143]
	v_ashrrev_i32_e32 v141, 31, v140
	v_lshl_add_u64 v[156:157], s[96:97], 0, v[156:157]
	v_lshl_add_u64 v[158:159], v[140:141], 1, v[156:157]
	s_cmp_gt_i32 s0, 7
	s_cselect_b64 s[26:27], -1, 0
	s_cmp_lt_i32 s0, 8
	s_waitcnt vmcnt(0)
	v_fmamk_f32 v154, v179, 0x3a000000, v152
	v_rsq_f32_e32 v154, v154
	s_nop 0
	v_pk_mul_f32 v[126:127], v[126:127], v[154:155] op_sel_hi:[1,0]
	v_pk_mul_f32 v[124:125], v[124:125], v[154:155] op_sel_hi:[1,0]
	v_pk_mul_f32 v[120:121], v[120:121], v[154:155] op_sel_hi:[1,0]
	v_pk_mul_f32 v[122:123], v[122:123], v[154:155] op_sel_hi:[1,0]
	v_pk_mul_f32 v[156:157], v[118:119], v[154:155] op_sel_hi:[1,0]
	v_pk_mul_f32 v[160:161], v[116:117], v[154:155] op_sel_hi:[1,0]
	v_pk_mul_f32 v[176:177], v[114:115], v[154:155] op_sel_hi:[1,0]
	v_pk_mul_f32 v[154:155], v[112:113], v[154:155] op_sel_hi:[1,0]
	v_mul_f32_e32 v112, 0x3d372713, v124
	v_mul_f32_e32 v113, 0x3d372713, v120
	v_mul_f32_e32 v114, 0x3d372713, v125
	v_mul_f32_e32 v115, 0x3d372713, v121
	v_mul_f32_e32 v116, 0x3d372713, v126
	v_mul_f32_e32 v118, 0x3d372713, v127
	v_mul_f32_e32 v117, 0x3d372713, v122
	v_mul_f32_e32 v119, 0x3d372713, v123
	v_mul_f32_e32 v112, v124, v112
	v_mul_f32_e32 v113, v120, v113
	v_mul_f32_e32 v114, v125, v114
	v_mul_f32_e32 v115, v121, v115
	v_mul_f32_e32 v116, v126, v116
	v_mul_f32_e32 v118, v127, v118
	v_mul_f32_e32 v117, v122, v117
	v_mul_f32_e32 v119, v123, v119
	v_fma_f32 v112, v124, v112, v124
	v_fma_f32 v113, v120, v113, v120
	v_fma_f32 v114, v125, v114, v125
	v_fma_f32 v115, v121, v115, v121
	v_fma_f32 v116, v126, v116, v126
	v_fma_f32 v118, v127, v118, v127
	v_fma_f32 v117, v122, v117, v122
	v_fma_f32 v119, v123, v119, v123
	v_mul_f32_e32 v112, 0x3f4c422a, v112
	v_mul_f32_e32 v113, 0x3f4c422a, v113
	v_mul_f32_e32 v114, 0x3f4c422a, v114
	v_mul_f32_e32 v115, 0x3f4c422a, v115
	v_mul_f32_e32 v116, 0x3f4c422a, v116
	v_mul_f32_e32 v118, 0x3f4c422a, v118
	v_mul_f32_e32 v117, 0x3f4c422a, v117
	v_mul_f32_e32 v119, 0x3f4c422a, v119
	v_mul_f32_e32 v112, 0xc038aa3b, v112
	v_mul_f32_e32 v113, 0xc038aa3b, v113
	v_mul_f32_e32 v114, 0xc038aa3b, v114
	v_mul_f32_e32 v115, 0xc038aa3b, v115
	v_mul_f32_e32 v116, 0xc038aa3b, v116
	v_mul_f32_e32 v118, 0xc038aa3b, v118
	v_mul_f32_e32 v117, 0xc038aa3b, v117
	v_mul_f32_e32 v119, 0xc038aa3b, v119
	v_exp_f32_e32 v112, v112
	v_exp_f32_e32 v113, v113
	v_exp_f32_e32 v114, v114
	v_exp_f32_e32 v115, v115
	v_exp_f32_e32 v116, v116
	v_exp_f32_e32 v118, v118
	v_exp_f32_e32 v117, v117
	v_exp_f32_e32 v119, v119
	v_add_f32_e32 v112, 1.0, v112
	v_add_f32_e32 v113, 1.0, v113
	v_add_f32_e32 v114, 1.0, v114
	v_add_f32_e32 v115, 1.0, v115
	v_add_f32_e32 v116, 1.0, v116
	v_add_f32_e32 v118, 1.0, v118
	v_add_f32_e32 v117, 1.0, v117
	v_add_f32_e32 v119, 1.0, v119
	v_rcp_f32_e32 v112, v112
	v_rcp_f32_e32 v113, v113
	v_rcp_f32_e32 v114, v114
	v_rcp_f32_e32 v171, v115
	v_rcp_f32_e32 v173, v116
	v_rcp_f32_e32 v175, v118
	v_rcp_f32_e32 v117, v117
	v_rcp_f32_e32 v178, v119
	v_mul_f32_e32 v116, v124, v112
	v_mul_f32_e32 v119, v120, v113
	v_mul_f32_e32 v115, v125, v114
	v_mul_f32_e32 v118, v121, v171
	v_mul_f32_e32 v113, v126, v173
	v_mul_f32_e32 v112, v127, v175
	v_cvt_pk_bf16_f32 v120, v116, v115
	v_cvt_pk_bf16_f32 v121, v113, v112
	v_mul_f32_e32 v117, v122, v117
	v_mul_f32_e32 v114, v123, v178
	v_cvt_pk_bf16_f32 v122, v119, v118
	v_cvt_pk_bf16_f32 v123, v117, v114
	global_store_dwordx4 v[158:159], v[120:123], off
	v_mul_f32_e32 v169, 0x3d372713, v160
	v_mul_f32_e32 v169, v160, v169
	v_mul_f32_e32 v121, 0x3d372713, v161
	v_mul_f32_e32 v121, v161, v121
	v_fma_f32 v121, v161, v121, v161
	v_mul_f32_e32 v121, 0x3f4c422a, v121
	v_mul_f32_e32 v121, 0xc038aa3b, v121
	v_mul_f32_e32 v120, 0x3d372713, v154
	v_exp_f32_e32 v121, v121
	v_mul_f32_e32 v120, v154, v120
	v_fma_f32 v169, v160, v169, v160
	v_fma_f32 v120, v154, v120, v154
	v_mul_f32_e32 v169, 0x3f4c422a, v169
	v_mul_f32_e32 v120, 0x3f4c422a, v120
	v_mul_f32_e32 v169, 0xc038aa3b, v169
	v_mul_f32_e32 v120, 0xc038aa3b, v120
	v_add_f32_e32 v121, 1.0, v121
	v_exp_f32_e32 v169, v169
	v_exp_f32_e32 v120, v120
	v_rcp_f32_e32 v123, v121
	v_mul_f32_e32 v121, 0x3d372713, v155
	v_mul_f32_e32 v121, v155, v121
	v_fma_f32 v121, v155, v121, v155
	v_mul_f32_e32 v121, 0x3f4c422a, v121
	v_add_f32_e32 v169, 1.0, v169
	v_add_f32_e32 v120, 1.0, v120
	v_mul_f32_e32 v121, 0xc038aa3b, v121
	v_rcp_f32_e32 v122, v169
	v_rcp_f32_e32 v120, v120
	v_exp_f32_e32 v124, v121
	v_mul_f32_e32 v125, 0x3d372713, v176
	v_mul_f32_e32 v125, v176, v125
	v_mul_f32_e32 v126, 0x3d372713, v157
	v_mul_f32_e32 v121, v160, v122
	v_mul_f32_e32 v122, v154, v120
	v_mul_f32_e32 v120, v161, v123
	v_add_f32_e32 v123, 1.0, v124
	v_mul_f32_e32 v124, 0x3d372713, v156
	v_fma_f32 v125, v176, v125, v176
	v_mul_f32_e32 v126, v157, v126
	v_mul_f32_e32 v127, 0x3d372713, v177
	v_mul_f32_e32 v124, v156, v124
	v_mul_f32_e32 v125, 0x3f4c422a, v125
	v_fma_f32 v126, v157, v126, v157
	v_mul_f32_e32 v127, v177, v127
	v_fma_f32 v124, v156, v124, v156
	v_mul_f32_e32 v125, 0xc038aa3b, v125
	v_mul_f32_e32 v126, 0x3f4c422a, v126
	v_fma_f32 v127, v177, v127, v177
	v_mul_f32_e32 v124, 0x3f4c422a, v124
	v_exp_f32_e32 v125, v125
	v_mul_f32_e32 v126, 0xc038aa3b, v126
	v_mul_f32_e32 v127, 0x3f4c422a, v127
	v_mul_f32_e32 v124, 0xc038aa3b, v124
	v_exp_f32_e32 v126, v126
	v_mul_f32_e32 v127, 0xc038aa3b, v127
	v_exp_f32_e32 v124, v124
	v_exp_f32_e32 v127, v127
	v_rcp_f32_e32 v123, v123
	v_add_f32_e32 v125, 1.0, v125
	v_rcp_f32_e32 v154, v125
	v_add_f32_e32 v125, 1.0, v126
	v_add_f32_e32 v124, 1.0, v124
	v_rcp_f32_e32 v126, v125
	v_add_f32_e32 v125, 1.0, v127
	v_mul_f32_e32 v123, v155, v123
	v_rcp_f32_e32 v124, v124
	v_rcp_f32_e32 v155, v125
	v_mul_f32_e32 v127, v176, v154
	v_cvt_pk_bf16_f32 v154, v121, v120
	v_mul_f32_e32 v125, v156, v124
	v_mul_f32_e32 v124, v157, v126
	v_mul_f32_e32 v126, v177, v155
	v_cvt_pk_bf16_f32 v155, v125, v124
	v_cvt_pk_bf16_f32 v156, v122, v123
	v_cvt_pk_bf16_f32 v157, v127, v126
	global_store_dwordx4 v[158:159], v[154:157], off offset:256
	s_cbranch_scc1 .LBB0_604
	v_mul_f32_e32 v119, v119, v119
	v_fmac_f32_e32 v119, v116, v116
	v_mul_f32_e32 v116, v118, v118
	v_fmac_f32_e32 v116, v115, v115
	v_add_f32_e32 v115, v119, v116
	v_mul_f32_e32 v116, v117, v117
	v_fmac_f32_e32 v116, v113, v113
	v_mul_f32_e32 v114, v114, v114
	v_add_f32_e32 v113, v116, v115
	v_fmac_f32_e32 v114, v112, v112
	v_add_f32_e32 v112, v114, v113
	v_mul_f32_e32 v113, v122, v122
	v_fmac_f32_e32 v113, v121, v121
	v_add_f32_e32 v112, v113, v112
	v_mul_f32_e32 v113, v123, v123
	v_fmac_f32_e32 v113, v120, v120
	v_add_f32_e32 v112, v113, v112
	v_mul_f32_e32 v113, v127, v127
	v_fmac_f32_e32 v113, v125, v125
	v_add_f32_e32 v112, v113, v112
	v_mul_f32_e32 v113, v126, v126
	v_fmac_f32_e32 v113, v124, v124
	v_and_b32_e32 v114, 64, v153
	v_add_f32_e32 v112, v113, v112
	v_xor_b32_e32 v113, 16, v153
	v_add_u32_e32 v114, 64, v114
	v_cmp_lt_i32_e32 vcc, v113, v114
	s_nop 1
	v_cndmask_b32_e32 v113, v153, v113, vcc
	v_lshlrev_b32_e32 v113, 2, v113
	ds_bpermute_b32 v113, v113, v112
	s_waitcnt lgkmcnt(0)
	v_add_f32_e32 v112, v112, v113
	v_xor_b32_e32 v113, 32, v153
	v_cmp_lt_i32_e32 vcc, v113, v114
	s_nop 1
	v_cndmask_b32_e32 v113, v153, v113, vcc
	v_lshlrev_b32_e32 v113, 2, v113
	ds_bpermute_b32 v113, v113, v112
	s_and_saveexec_b64 s[0:1], s[8:9]
	s_cbranch_execz .LBB0_603
	v_lshl_add_u64 v[114:115], v[142:143], 2, s[4:5]
	s_waitcnt lgkmcnt(0)
	v_add_f32_e32 v112, v112, v113
	global_atomic_add_f32 v[114:115], v112, off

.LBB0_604:
	v_or_b32_e32 v112, 16, v142
	s_waitcnt lgkmcnt(0)
	v_ashrrev_i32_e32 v113, 31, v112
	v_lshl_add_u64 v[114:115], v[112:113], 2, s[14:15]
	s_nop 0
	v_lshlrev_b64 v[116:117], 13, v[112:113]
	v_lshl_add_u64 v[116:117], s[96:97], 0, v[116:117]
	v_lshl_add_u64 v[118:119], v[140:141], 1, v[116:117]
	s_andn2_b64 vcc, exec, s[26:27]
	s_nop 0
	v_fmamk_f32 v114, v180, 0x3a000000, v152
	v_rsq_f32_e32 v114, v114
	s_nop 0
	v_pk_mul_f32 v[110:111], v[110:111], v[114:115] op_sel_hi:[1,0]
	v_pk_mul_f32 v[108:109], v[108:109], v[114:115] op_sel_hi:[1,0]
	v_pk_mul_f32 v[104:105], v[104:105], v[114:115] op_sel_hi:[1,0]
	v_pk_mul_f32 v[106:107], v[106:107], v[114:115] op_sel_hi:[1,0]
	v_pk_mul_f32 v[116:117], v[102:103], v[114:115] op_sel_hi:[1,0]
	v_pk_mul_f32 v[120:121], v[100:101], v[114:115] op_sel_hi:[1,0]
	v_pk_mul_f32 v[122:123], v[98:99], v[114:115] op_sel_hi:[1,0]
	v_pk_mul_f32 v[114:115], v[96:97], v[114:115] op_sel_hi:[1,0]
	v_mul_f32_e32 v96, 0x3d372713, v108
	v_mul_f32_e32 v97, 0x3d372713, v104
	v_mul_f32_e32 v98, 0x3d372713, v109
	v_mul_f32_e32 v99, 0x3d372713, v105
	v_mul_f32_e32 v100, 0x3d372713, v110
	v_mul_f32_e32 v102, 0x3d372713, v111
	v_mul_f32_e32 v101, 0x3d372713, v106
	v_mul_f32_e32 v103, 0x3d372713, v107
	v_mul_f32_e32 v96, v108, v96
	v_mul_f32_e32 v97, v104, v97
	v_mul_f32_e32 v98, v109, v98
	v_mul_f32_e32 v99, v105, v99
	v_mul_f32_e32 v100, v110, v100
	v_mul_f32_e32 v102, v111, v102
	v_mul_f32_e32 v101, v106, v101
	v_mul_f32_e32 v103, v107, v103
	v_fma_f32 v96, v108, v96, v108
	v_fma_f32 v97, v104, v97, v104
	v_fma_f32 v98, v109, v98, v109
	v_fma_f32 v99, v105, v99, v105
	v_fma_f32 v100, v110, v100, v110
	v_fma_f32 v102, v111, v102, v111
	v_fma_f32 v101, v106, v101, v106
	v_fma_f32 v103, v107, v103, v107
	v_mul_f32_e32 v96, 0x3f4c422a, v96
	v_mul_f32_e32 v97, 0x3f4c422a, v97
	v_mul_f32_e32 v98, 0x3f4c422a, v98
	v_mul_f32_e32 v99, 0x3f4c422a, v99
	v_mul_f32_e32 v100, 0x3f4c422a, v100
	v_mul_f32_e32 v102, 0x3f4c422a, v102
	v_mul_f32_e32 v101, 0x3f4c422a, v101
	v_mul_f32_e32 v103, 0x3f4c422a, v103
	v_mul_f32_e32 v96, 0xc038aa3b, v96
	v_mul_f32_e32 v97, 0xc038aa3b, v97
	v_mul_f32_e32 v98, 0xc038aa3b, v98
	v_mul_f32_e32 v99, 0xc038aa3b, v99
	v_mul_f32_e32 v100, 0xc038aa3b, v100
	v_mul_f32_e32 v102, 0xc038aa3b, v102
	v_mul_f32_e32 v101, 0xc038aa3b, v101
	v_mul_f32_e32 v103, 0xc038aa3b, v103
	v_exp_f32_e32 v96, v96
	v_exp_f32_e32 v97, v97
	v_exp_f32_e32 v98, v98
	v_exp_f32_e32 v99, v99
	v_exp_f32_e32 v100, v100
	v_exp_f32_e32 v102, v102
	v_exp_f32_e32 v101, v101
	v_exp_f32_e32 v103, v103
	v_add_f32_e32 v96, 1.0, v96
	v_add_f32_e32 v97, 1.0, v97
	v_add_f32_e32 v98, 1.0, v98
	v_add_f32_e32 v99, 1.0, v99
	v_add_f32_e32 v100, 1.0, v100
	v_add_f32_e32 v102, 1.0, v102
	v_add_f32_e32 v101, 1.0, v101
	v_add_f32_e32 v103, 1.0, v103
	v_rcp_f32_e32 v96, v96
	v_rcp_f32_e32 v97, v97
	v_rcp_f32_e32 v98, v98
	v_rcp_f32_e32 v126, v99
	v_rcp_f32_e32 v127, v100
	v_rcp_f32_e32 v143, v102
	v_rcp_f32_e32 v101, v101
	v_rcp_f32_e32 v154, v103
	v_mul_f32_e32 v100, v108, v96
	v_mul_f32_e32 v103, v104, v97
	v_mul_f32_e32 v99, v109, v98
	v_mul_f32_e32 v102, v105, v126
	v_mul_f32_e32 v97, v110, v127
	v_mul_f32_e32 v96, v111, v143
	v_cvt_pk_bf16_f32 v104, v100, v99
	v_cvt_pk_bf16_f32 v105, v97, v96
	v_mul_f32_e32 v101, v106, v101
	v_mul_f32_e32 v98, v107, v154
	v_cvt_pk_bf16_f32 v106, v103, v102
	v_cvt_pk_bf16_f32 v107, v101, v98
	global_store_dwordx4 v[118:119], v[104:107], off
	v_mul_f32_e32 v124, 0x3d372713, v120
	v_mul_f32_e32 v125, 0x3d372713, v114
	v_mul_f32_e32 v105, 0x3d372713, v121
	v_mul_f32_e32 v105, v121, v105
	v_fma_f32 v105, v121, v105, v121
	v_mul_f32_e32 v105, 0x3f4c422a, v105
	v_mul_f32_e32 v105, 0xc038aa3b, v105
	v_exp_f32_e32 v105, v105
	v_mul_f32_e32 v124, v120, v124
	v_mul_f32_e32 v125, v114, v125
	v_fma_f32 v124, v120, v124, v120
	v_fma_f32 v125, v114, v125, v114
	v_mul_f32_e32 v124, 0x3f4c422a, v124
	v_mul_f32_e32 v125, 0x3f4c422a, v125
	v_mul_f32_e32 v124, 0xc038aa3b, v124
	v_mul_f32_e32 v125, 0xc038aa3b, v125
	v_add_f32_e32 v105, 1.0, v105
	v_exp_f32_e32 v124, v124
	v_exp_f32_e32 v104, v125
	v_rcp_f32_e32 v107, v105
	v_mul_f32_e32 v105, 0x3d372713, v115
	v_mul_f32_e32 v105, v115, v105
	v_fma_f32 v105, v115, v105, v115
	v_mul_f32_e32 v105, 0x3f4c422a, v105
	v_add_f32_e32 v124, 1.0, v124
	v_add_f32_e32 v104, 1.0, v104
	v_mul_f32_e32 v105, 0xc038aa3b, v105
	v_rcp_f32_e32 v106, v124
	v_rcp_f32_e32 v104, v104
	v_exp_f32_e32 v108, v105
	v_mul_f32_e32 v109, 0x3d372713, v122
	v_mul_f32_e32 v109, v122, v109
	v_mul_f32_e32 v110, 0x3d372713, v117
	v_mul_f32_e32 v105, v120, v106
	v_mul_f32_e32 v106, v114, v104
	v_mul_f32_e32 v104, v121, v107
	v_add_f32_e32 v107, 1.0, v108
	v_mul_f32_e32 v108, 0x3d372713, v116
	v_fma_f32 v109, v122, v109, v122
	v_mul_f32_e32 v110, v117, v110
	v_mul_f32_e32 v111, 0x3d372713, v123
	v_mul_f32_e32 v108, v116, v108
	v_mul_f32_e32 v109, 0x3f4c422a, v109
	v_fma_f32 v110, v117, v110, v117
	v_mul_f32_e32 v111, v123, v111
	v_fma_f32 v108, v116, v108, v116
	v_mul_f32_e32 v109, 0xc038aa3b, v109
	v_mul_f32_e32 v110, 0x3f4c422a, v110
	v_fma_f32 v111, v123, v111, v123
	v_mul_f32_e32 v108, 0x3f4c422a, v108
	v_exp_f32_e32 v109, v109
	v_mul_f32_e32 v110, 0xc038aa3b, v110
	v_mul_f32_e32 v111, 0x3f4c422a, v111
	v_mul_f32_e32 v108, 0xc038aa3b, v108
	v_exp_f32_e32 v110, v110
	v_mul_f32_e32 v111, 0xc038aa3b, v111
	v_exp_f32_e32 v108, v108
	v_exp_f32_e32 v111, v111
	v_rcp_f32_e32 v107, v107
	v_add_f32_e32 v109, 1.0, v109
	v_rcp_f32_e32 v114, v109
	v_add_f32_e32 v109, 1.0, v110
	v_add_f32_e32 v108, 1.0, v108
	v_rcp_f32_e32 v110, v109
	v_add_f32_e32 v109, 1.0, v111
	v_mul_f32_e32 v107, v115, v107
	v_rcp_f32_e32 v108, v108
	v_rcp_f32_e32 v115, v109
	v_cndmask_b32_e64 v120, 0, 1, s[26:27]
	v_mul_f32_e32 v111, v122, v114
	v_mul_f32_e32 v109, v116, v108
	v_mul_f32_e32 v108, v117, v110
	v_mul_f32_e32 v110, v123, v115
	v_cmp_ne_u32_e64 s[12:13], 1, v120
	v_cvt_pk_bf16_f32 v114, v105, v104
	v_cvt_pk_bf16_f32 v115, v109, v108
	v_cvt_pk_bf16_f32 v116, v106, v107
	v_cvt_pk_bf16_f32 v117, v111, v110
	global_store_dwordx4 v[118:119], v[114:117], off offset:256
	s_cbranch_vccnz .LBB0_608
	v_mul_f32_e32 v103, v103, v103
	v_fmac_f32_e32 v103, v100, v100
	v_mul_f32_e32 v100, v102, v102
	v_fmac_f32_e32 v100, v99, v99
	v_add_f32_e32 v99, v103, v100
	v_mul_f32_e32 v100, v101, v101
	v_fmac_f32_e32 v100, v97, v97
	v_mul_f32_e32 v98, v98, v98
	v_add_f32_e32 v97, v100, v99
	v_fmac_f32_e32 v98, v96, v96
	v_add_f32_e32 v96, v98, v97
	v_mul_f32_e32 v97, v106, v106
	v_fmac_f32_e32 v97, v105, v105
	v_add_f32_e32 v96, v97, v96
	v_mul_f32_e32 v97, v107, v107
	v_fmac_f32_e32 v97, v104, v104
	v_add_f32_e32 v96, v97, v96
	v_mul_f32_e32 v97, v111, v111
	v_fmac_f32_e32 v97, v109, v109
	v_add_f32_e32 v96, v97, v96
	v_mul_f32_e32 v97, v110, v110
	v_fmac_f32_e32 v97, v108, v108
	v_and_b32_e32 v98, 64, v153
	v_add_f32_e32 v96, v97, v96
	v_xor_b32_e32 v97, 16, v153
	v_add_u32_e32 v98, 64, v98
	v_cmp_lt_i32_e32 vcc, v97, v98
	s_nop 1
	v_cndmask_b32_e32 v97, v153, v97, vcc
	v_lshlrev_b32_e32 v97, 2, v97
	ds_bpermute_b32 v97, v97, v96
	s_waitcnt lgkmcnt(0)
	v_add_f32_e32 v96, v96, v97
	v_xor_b32_e32 v97, 32, v153
	v_cmp_lt_i32_e32 vcc, v97, v98
	s_nop 1
	v_cndmask_b32_e32 v97, v153, v97, vcc
	v_lshlrev_b32_e32 v97, 2, v97
	ds_bpermute_b32 v97, v97, v96
	s_and_saveexec_b64 s[0:1], s[8:9]
	s_cbranch_execz .LBB0_607
	v_lshl_add_u64 v[98:99], v[112:113], 2, s[4:5]
	s_waitcnt lgkmcnt(0)
	v_add_f32_e32 v96, v96, v97
	global_atomic_add_f32 v[98:99], v96, off

.LBB0_608:
	v_or_b32_e32 v96, 32, v142
	s_waitcnt lgkmcnt(0)
	v_ashrrev_i32_e32 v97, 31, v96
	v_lshl_add_u64 v[98:99], v[96:97], 2, s[14:15]
	s_nop 0
	v_lshlrev_b64 v[100:101], 13, v[96:97]
	v_lshl_add_u64 v[100:101], s[96:97], 0, v[100:101]
	v_lshl_add_u64 v[102:103], v[140:141], 1, v[100:101]
	s_and_b64 vcc, exec, s[12:13]
	s_nop 0
	v_fmamk_f32 v98, v181, 0x3a000000, v152
	v_rsq_f32_e32 v98, v98
	s_nop 0
	v_pk_mul_f32 v[94:95], v[94:95], v[98:99] op_sel_hi:[1,0]
	v_pk_mul_f32 v[92:93], v[92:93], v[98:99] op_sel_hi:[1,0]
	v_pk_mul_f32 v[88:89], v[88:89], v[98:99] op_sel_hi:[1,0]
	v_pk_mul_f32 v[90:91], v[90:91], v[98:99] op_sel_hi:[1,0]
	v_pk_mul_f32 v[100:101], v[86:87], v[98:99] op_sel_hi:[1,0]
	v_pk_mul_f32 v[104:105], v[84:85], v[98:99] op_sel_hi:[1,0]
	v_pk_mul_f32 v[106:107], v[82:83], v[98:99] op_sel_hi:[1,0]
	v_pk_mul_f32 v[98:99], v[80:81], v[98:99] op_sel_hi:[1,0]
	v_mul_f32_e32 v80, 0x3d372713, v92
	v_mul_f32_e32 v81, 0x3d372713, v88
	v_mul_f32_e32 v82, 0x3d372713, v93
	v_mul_f32_e32 v83, 0x3d372713, v89
	v_mul_f32_e32 v84, 0x3d372713, v94
	v_mul_f32_e32 v86, 0x3d372713, v95
	v_mul_f32_e32 v85, 0x3d372713, v90
	v_mul_f32_e32 v87, 0x3d372713, v91
	v_mul_f32_e32 v80, v92, v80
	v_mul_f32_e32 v81, v88, v81
	v_mul_f32_e32 v82, v93, v82
	v_mul_f32_e32 v83, v89, v83
	v_mul_f32_e32 v84, v94, v84
	v_mul_f32_e32 v86, v95, v86
	v_mul_f32_e32 v85, v90, v85
	v_mul_f32_e32 v87, v91, v87
	v_fma_f32 v80, v92, v80, v92
	v_fma_f32 v81, v88, v81, v88
	v_fma_f32 v82, v93, v82, v93
	v_fma_f32 v83, v89, v83, v89
	v_fma_f32 v84, v94, v84, v94
	v_fma_f32 v86, v95, v86, v95
	v_fma_f32 v85, v90, v85, v90
	v_fma_f32 v87, v91, v87, v91
	v_mul_f32_e32 v80, 0x3f4c422a, v80
	v_mul_f32_e32 v81, 0x3f4c422a, v81
	v_mul_f32_e32 v82, 0x3f4c422a, v82
	v_mul_f32_e32 v83, 0x3f4c422a, v83
	v_mul_f32_e32 v84, 0x3f4c422a, v84
	v_mul_f32_e32 v86, 0x3f4c422a, v86
	v_mul_f32_e32 v85, 0x3f4c422a, v85
	v_mul_f32_e32 v87, 0x3f4c422a, v87
	v_mul_f32_e32 v80, 0xc038aa3b, v80
	v_mul_f32_e32 v81, 0xc038aa3b, v81
	v_mul_f32_e32 v82, 0xc038aa3b, v82
	v_mul_f32_e32 v83, 0xc038aa3b, v83
	v_mul_f32_e32 v84, 0xc038aa3b, v84
	v_mul_f32_e32 v86, 0xc038aa3b, v86
	v_mul_f32_e32 v85, 0xc038aa3b, v85
	v_mul_f32_e32 v87, 0xc038aa3b, v87
	v_exp_f32_e32 v80, v80
	v_exp_f32_e32 v81, v81
	v_exp_f32_e32 v82, v82
	v_exp_f32_e32 v83, v83
	v_exp_f32_e32 v84, v84
	v_exp_f32_e32 v86, v86
	v_exp_f32_e32 v85, v85
	v_exp_f32_e32 v87, v87
	v_add_f32_e32 v80, 1.0, v80
	v_add_f32_e32 v81, 1.0, v81
	v_add_f32_e32 v82, 1.0, v82
	v_add_f32_e32 v83, 1.0, v83
	v_add_f32_e32 v84, 1.0, v84
	v_add_f32_e32 v86, 1.0, v86
	v_add_f32_e32 v85, 1.0, v85
	v_add_f32_e32 v87, 1.0, v87
	v_rcp_f32_e32 v80, v80
	v_rcp_f32_e32 v81, v81
	v_rcp_f32_e32 v82, v82
	v_rcp_f32_e32 v110, v83
	v_rcp_f32_e32 v111, v84
	v_rcp_f32_e32 v112, v86
	v_rcp_f32_e32 v85, v85
	v_rcp_f32_e32 v113, v87
	v_mul_f32_e32 v84, v92, v80
	v_mul_f32_e32 v87, v88, v81
	v_mul_f32_e32 v83, v93, v82
	v_mul_f32_e32 v86, v89, v110
	v_mul_f32_e32 v81, v94, v111
	v_mul_f32_e32 v80, v95, v112
	v_cvt_pk_bf16_f32 v88, v84, v83
	v_cvt_pk_bf16_f32 v89, v81, v80
	v_mul_f32_e32 v85, v90, v85
	v_mul_f32_e32 v82, v91, v113
	v_cvt_pk_bf16_f32 v90, v87, v86
	v_cvt_pk_bf16_f32 v91, v85, v82
	global_store_dwordx4 v[102:103], v[88:91], off
	v_mul_f32_e32 v108, 0x3d372713, v104
	v_mul_f32_e32 v109, 0x3d372713, v98
	v_mul_f32_e32 v89, 0x3d372713, v105
	v_mul_f32_e32 v89, v105, v89
	v_fma_f32 v89, v105, v89, v105
	v_mul_f32_e32 v89, 0x3f4c422a, v89
	v_mul_f32_e32 v89, 0xc038aa3b, v89
	v_exp_f32_e32 v89, v89
	v_mul_f32_e32 v108, v104, v108
	v_mul_f32_e32 v109, v98, v109
	v_fma_f32 v108, v104, v108, v104
	v_fma_f32 v109, v98, v109, v98
	v_mul_f32_e32 v108, 0x3f4c422a, v108
	v_mul_f32_e32 v109, 0x3f4c422a, v109
	v_mul_f32_e32 v108, 0xc038aa3b, v108
	v_mul_f32_e32 v109, 0xc038aa3b, v109
	v_add_f32_e32 v89, 1.0, v89
	v_exp_f32_e32 v108, v108
	v_exp_f32_e32 v88, v109
	v_rcp_f32_e32 v91, v89
	v_mul_f32_e32 v89, 0x3d372713, v99
	v_mul_f32_e32 v89, v99, v89
	v_fma_f32 v89, v99, v89, v99
	v_mul_f32_e32 v89, 0x3f4c422a, v89
	v_add_f32_e32 v108, 1.0, v108
	v_add_f32_e32 v88, 1.0, v88
	v_mul_f32_e32 v89, 0xc038aa3b, v89
	v_rcp_f32_e32 v90, v108
	v_rcp_f32_e32 v88, v88
	v_exp_f32_e32 v92, v89
	v_mul_f32_e32 v93, 0x3d372713, v106
	v_mul_f32_e32 v93, v106, v93
	v_mul_f32_e32 v94, 0x3d372713, v101
	v_mul_f32_e32 v89, v104, v90
	v_mul_f32_e32 v90, v98, v88
	v_mul_f32_e32 v88, v105, v91
	v_add_f32_e32 v91, 1.0, v92
	v_mul_f32_e32 v92, 0x3d372713, v100
	v_fma_f32 v93, v106, v93, v106
	v_mul_f32_e32 v94, v101, v94
	v_mul_f32_e32 v95, 0x3d372713, v107
	v_mul_f32_e32 v92, v100, v92
	v_mul_f32_e32 v93, 0x3f4c422a, v93
	v_fma_f32 v94, v101, v94, v101
	v_mul_f32_e32 v95, v107, v95
	v_fma_f32 v92, v100, v92, v100
	v_mul_f32_e32 v93, 0xc038aa3b, v93
	v_mul_f32_e32 v94, 0x3f4c422a, v94
	v_fma_f32 v95, v107, v95, v107
	v_mul_f32_e32 v92, 0x3f4c422a, v92
	v_exp_f32_e32 v93, v93
	v_mul_f32_e32 v94, 0xc038aa3b, v94
	v_mul_f32_e32 v95, 0x3f4c422a, v95
	v_mul_f32_e32 v92, 0xc038aa3b, v92
	v_exp_f32_e32 v94, v94
	v_mul_f32_e32 v95, 0xc038aa3b, v95
	v_exp_f32_e32 v92, v92
	v_exp_f32_e32 v95, v95
	v_rcp_f32_e32 v91, v91
	v_add_f32_e32 v93, 1.0, v93
	v_rcp_f32_e32 v98, v93
	v_add_f32_e32 v93, 1.0, v94
	v_add_f32_e32 v92, 1.0, v92
	v_rcp_f32_e32 v94, v93
	v_add_f32_e32 v93, 1.0, v95
	v_mul_f32_e32 v91, v99, v91
	v_rcp_f32_e32 v92, v92
	v_rcp_f32_e32 v99, v93
	v_mul_f32_e32 v95, v106, v98
	v_cvt_pk_bf16_f32 v98, v89, v88
	v_mul_f32_e32 v93, v100, v92
	v_mul_f32_e32 v92, v101, v94
	v_mul_f32_e32 v94, v107, v99
	v_cvt_pk_bf16_f32 v99, v93, v92
	v_cvt_pk_bf16_f32 v100, v90, v91
	v_cvt_pk_bf16_f32 v101, v95, v94
	global_store_dwordx4 v[102:103], v[98:101], off offset:256
	s_cbranch_vccnz .LBB0_612
	v_mul_f32_e32 v87, v87, v87
	v_fmac_f32_e32 v87, v84, v84
	v_mul_f32_e32 v84, v86, v86
	v_fmac_f32_e32 v84, v83, v83
	v_add_f32_e32 v83, v87, v84
	v_mul_f32_e32 v84, v85, v85
	v_fmac_f32_e32 v84, v81, v81
	v_mul_f32_e32 v82, v82, v82
	v_add_f32_e32 v81, v84, v83
	v_fmac_f32_e32 v82, v80, v80
	v_add_f32_e32 v80, v82, v81
	v_mul_f32_e32 v81, v90, v90
	v_fmac_f32_e32 v81, v89, v89
	v_add_f32_e32 v80, v81, v80
	v_mul_f32_e32 v81, v91, v91
	v_fmac_f32_e32 v81, v88, v88
	v_add_f32_e32 v80, v81, v80
	v_mul_f32_e32 v81, v95, v95
	v_fmac_f32_e32 v81, v93, v93
	v_add_f32_e32 v80, v81, v80
	v_mul_f32_e32 v81, v94, v94
	v_fmac_f32_e32 v81, v92, v92
	v_and_b32_e32 v82, 64, v153
	v_add_f32_e32 v80, v81, v80
	v_xor_b32_e32 v81, 16, v153
	v_add_u32_e32 v82, 64, v82
	v_cmp_lt_i32_e32 vcc, v81, v82
	s_nop 1
	v_cndmask_b32_e32 v81, v153, v81, vcc
	v_lshlrev_b32_e32 v81, 2, v81
	ds_bpermute_b32 v81, v81, v80
	s_waitcnt lgkmcnt(0)
	v_add_f32_e32 v80, v80, v81
	v_xor_b32_e32 v81, 32, v153
	v_cmp_lt_i32_e32 vcc, v81, v82
	s_nop 1
	v_cndmask_b32_e32 v81, v153, v81, vcc
	v_lshlrev_b32_e32 v81, 2, v81
	ds_bpermute_b32 v81, v81, v80
	s_and_saveexec_b64 s[0:1], s[8:9]
	s_cbranch_execz .LBB0_611
	v_lshl_add_u64 v[82:83], v[96:97], 2, s[4:5]
	s_waitcnt lgkmcnt(0)
	v_add_f32_e32 v80, v80, v81
	global_atomic_add_f32 v[82:83], v80, off

.LBB0_612:
	v_or_b32_e32 v80, 48, v142
	s_waitcnt lgkmcnt(0)
	v_ashrrev_i32_e32 v81, 31, v80
	v_lshl_add_u64 v[82:83], v[80:81], 2, s[14:15]
	s_nop 0
	v_lshlrev_b64 v[84:85], 13, v[80:81]
	v_lshl_add_u64 v[84:85], s[96:97], 0, v[84:85]
	v_lshl_add_u64 v[86:87], v[140:141], 1, v[84:85]
	s_and_b64 vcc, exec, s[12:13]
	s_nop 0
	v_fmamk_f32 v82, v182, 0x3a000000, v152
	v_rsq_f32_e32 v82, v82
	s_nop 0
	v_pk_mul_f32 v[78:79], v[78:79], v[82:83] op_sel_hi:[1,0]
	v_pk_mul_f32 v[76:77], v[76:77], v[82:83] op_sel_hi:[1,0]
	v_pk_mul_f32 v[72:73], v[72:73], v[82:83] op_sel_hi:[1,0]
	v_pk_mul_f32 v[74:75], v[74:75], v[82:83] op_sel_hi:[1,0]
	v_pk_mul_f32 v[84:85], v[70:71], v[82:83] op_sel_hi:[1,0]
	v_pk_mul_f32 v[88:89], v[68:69], v[82:83] op_sel_hi:[1,0]
	v_pk_mul_f32 v[90:91], v[66:67], v[82:83] op_sel_hi:[1,0]
	v_pk_mul_f32 v[82:83], v[64:65], v[82:83] op_sel_hi:[1,0]
	v_mul_f32_e32 v64, 0x3d372713, v76
	v_mul_f32_e32 v65, 0x3d372713, v72
	v_mul_f32_e32 v66, 0x3d372713, v77
	v_mul_f32_e32 v67, 0x3d372713, v73
	v_mul_f32_e32 v68, 0x3d372713, v78
	v_mul_f32_e32 v70, 0x3d372713, v79
	v_mul_f32_e32 v69, 0x3d372713, v74
	v_mul_f32_e32 v71, 0x3d372713, v75
	v_mul_f32_e32 v64, v76, v64
	v_mul_f32_e32 v65, v72, v65
	v_mul_f32_e32 v66, v77, v66
	v_mul_f32_e32 v67, v73, v67
	v_mul_f32_e32 v68, v78, v68
	v_mul_f32_e32 v70, v79, v70
	v_mul_f32_e32 v69, v74, v69
	v_mul_f32_e32 v71, v75, v71
	v_fma_f32 v64, v76, v64, v76
	v_fma_f32 v65, v72, v65, v72
	v_fma_f32 v66, v77, v66, v77
	v_fma_f32 v67, v73, v67, v73
	v_fma_f32 v68, v78, v68, v78
	v_fma_f32 v70, v79, v70, v79
	v_fma_f32 v69, v74, v69, v74
	v_fma_f32 v71, v75, v71, v75
	v_mul_f32_e32 v64, 0x3f4c422a, v64
	v_mul_f32_e32 v65, 0x3f4c422a, v65
	v_mul_f32_e32 v66, 0x3f4c422a, v66
	v_mul_f32_e32 v67, 0x3f4c422a, v67
	v_mul_f32_e32 v68, 0x3f4c422a, v68
	v_mul_f32_e32 v70, 0x3f4c422a, v70
	v_mul_f32_e32 v69, 0x3f4c422a, v69
	v_mul_f32_e32 v71, 0x3f4c422a, v71
	v_mul_f32_e32 v64, 0xc038aa3b, v64
	v_mul_f32_e32 v65, 0xc038aa3b, v65
	v_mul_f32_e32 v66, 0xc038aa3b, v66
	v_mul_f32_e32 v67, 0xc038aa3b, v67
	v_mul_f32_e32 v68, 0xc038aa3b, v68
	v_mul_f32_e32 v70, 0xc038aa3b, v70
	v_mul_f32_e32 v69, 0xc038aa3b, v69
	v_mul_f32_e32 v71, 0xc038aa3b, v71
	v_exp_f32_e32 v64, v64
	v_exp_f32_e32 v65, v65
	v_exp_f32_e32 v66, v66
	v_exp_f32_e32 v67, v67
	v_exp_f32_e32 v68, v68
	v_exp_f32_e32 v70, v70
	v_exp_f32_e32 v69, v69
	v_exp_f32_e32 v71, v71
	v_add_f32_e32 v64, 1.0, v64
	v_add_f32_e32 v65, 1.0, v65
	v_add_f32_e32 v66, 1.0, v66
	v_add_f32_e32 v67, 1.0, v67
	v_add_f32_e32 v68, 1.0, v68
	v_add_f32_e32 v70, 1.0, v70
	v_add_f32_e32 v69, 1.0, v69
	v_add_f32_e32 v71, 1.0, v71
	v_rcp_f32_e32 v64, v64
	v_rcp_f32_e32 v65, v65
	v_rcp_f32_e32 v66, v66
	v_rcp_f32_e32 v94, v67
	v_rcp_f32_e32 v95, v68
	v_rcp_f32_e32 v96, v70
	v_rcp_f32_e32 v69, v69
	v_rcp_f32_e32 v97, v71
	v_mul_f32_e32 v68, v76, v64
	v_mul_f32_e32 v71, v72, v65
	v_mul_f32_e32 v67, v77, v66
	v_mul_f32_e32 v70, v73, v94
	v_mul_f32_e32 v65, v78, v95
	v_mul_f32_e32 v64, v79, v96
	v_cvt_pk_bf16_f32 v72, v68, v67
	v_cvt_pk_bf16_f32 v73, v65, v64
	v_mul_f32_e32 v69, v74, v69
	v_mul_f32_e32 v66, v75, v97
	v_cvt_pk_bf16_f32 v74, v71, v70
	v_cvt_pk_bf16_f32 v75, v69, v66
	global_store_dwordx4 v[86:87], v[72:75], off
	v_mul_f32_e32 v92, 0x3d372713, v88
	v_mul_f32_e32 v93, 0x3d372713, v82
	v_mul_f32_e32 v73, 0x3d372713, v89
	v_mul_f32_e32 v73, v89, v73
	v_fma_f32 v73, v89, v73, v89
	v_mul_f32_e32 v73, 0x3f4c422a, v73
	v_mul_f32_e32 v73, 0xc038aa3b, v73
	v_exp_f32_e32 v73, v73
	v_mul_f32_e32 v92, v88, v92
	v_mul_f32_e32 v93, v82, v93
	v_fma_f32 v92, v88, v92, v88
	v_fma_f32 v93, v82, v93, v82
	v_mul_f32_e32 v92, 0x3f4c422a, v92
	v_mul_f32_e32 v93, 0x3f4c422a, v93
	v_mul_f32_e32 v92, 0xc038aa3b, v92
	v_mul_f32_e32 v93, 0xc038aa3b, v93
	v_add_f32_e32 v73, 1.0, v73
	v_exp_f32_e32 v92, v92
	v_exp_f32_e32 v72, v93
	v_rcp_f32_e32 v75, v73
	v_mul_f32_e32 v73, 0x3d372713, v83
	v_mul_f32_e32 v73, v83, v73
	v_fma_f32 v73, v83, v73, v83
	v_mul_f32_e32 v73, 0x3f4c422a, v73
	v_add_f32_e32 v92, 1.0, v92
	v_add_f32_e32 v72, 1.0, v72
	v_mul_f32_e32 v73, 0xc038aa3b, v73
	v_rcp_f32_e32 v74, v92
	v_rcp_f32_e32 v72, v72
	v_exp_f32_e32 v76, v73
	v_mul_f32_e32 v77, 0x3d372713, v90
	v_mul_f32_e32 v77, v90, v77
	v_mul_f32_e32 v78, 0x3d372713, v85
	v_mul_f32_e32 v73, v88, v74
	v_mul_f32_e32 v74, v82, v72
	v_mul_f32_e32 v72, v89, v75
	v_add_f32_e32 v75, 1.0, v76
	v_mul_f32_e32 v76, 0x3d372713, v84
	v_fma_f32 v77, v90, v77, v90
	v_mul_f32_e32 v78, v85, v78
	v_mul_f32_e32 v79, 0x3d372713, v91
	v_mul_f32_e32 v76, v84, v76
	v_mul_f32_e32 v77, 0x3f4c422a, v77
	v_fma_f32 v78, v85, v78, v85
	v_mul_f32_e32 v79, v91, v79
	v_fma_f32 v76, v84, v76, v84
	v_mul_f32_e32 v77, 0xc038aa3b, v77
	v_mul_f32_e32 v78, 0x3f4c422a, v78
	v_fma_f32 v79, v91, v79, v91
	v_mul_f32_e32 v76, 0x3f4c422a, v76
	v_exp_f32_e32 v77, v77
	v_mul_f32_e32 v78, 0xc038aa3b, v78
	v_mul_f32_e32 v79, 0x3f4c422a, v79
	v_mul_f32_e32 v76, 0xc038aa3b, v76
	v_exp_f32_e32 v78, v78
	v_mul_f32_e32 v79, 0xc038aa3b, v79
	v_exp_f32_e32 v76, v76
	v_exp_f32_e32 v79, v79
	v_rcp_f32_e32 v75, v75
	v_add_f32_e32 v77, 1.0, v77
	v_rcp_f32_e32 v82, v77
	v_add_f32_e32 v77, 1.0, v78
	v_add_f32_e32 v76, 1.0, v76
	v_rcp_f32_e32 v78, v77
	v_add_f32_e32 v77, 1.0, v79
	v_mul_f32_e32 v75, v83, v75
	v_rcp_f32_e32 v76, v76
	v_rcp_f32_e32 v83, v77
	v_mul_f32_e32 v79, v90, v82
	v_cvt_pk_bf16_f32 v82, v73, v72
	v_mul_f32_e32 v77, v84, v76
	v_mul_f32_e32 v76, v85, v78
	v_mul_f32_e32 v78, v91, v83
	v_cvt_pk_bf16_f32 v83, v77, v76
	v_cvt_pk_bf16_f32 v84, v74, v75
	v_cvt_pk_bf16_f32 v85, v79, v78
	global_store_dwordx4 v[86:87], v[82:85], off offset:256
	s_cbranch_vccnz .LBB0_616
	v_mul_f32_e32 v71, v71, v71
	v_fmac_f32_e32 v71, v68, v68
	v_mul_f32_e32 v68, v70, v70
	v_fmac_f32_e32 v68, v67, v67
	v_add_f32_e32 v67, v71, v68
	v_mul_f32_e32 v68, v69, v69
	v_fmac_f32_e32 v68, v65, v65
	v_mul_f32_e32 v66, v66, v66
	v_add_f32_e32 v65, v68, v67
	v_fmac_f32_e32 v66, v64, v64
	v_add_f32_e32 v64, v66, v65
	v_mul_f32_e32 v65, v74, v74
	v_fmac_f32_e32 v65, v73, v73
	v_add_f32_e32 v64, v65, v64
	v_mul_f32_e32 v65, v75, v75
	v_fmac_f32_e32 v65, v72, v72
	v_add_f32_e32 v64, v65, v64
	v_mul_f32_e32 v65, v79, v79
	v_fmac_f32_e32 v65, v77, v77
	v_add_f32_e32 v64, v65, v64
	v_mul_f32_e32 v65, v78, v78
	v_fmac_f32_e32 v65, v76, v76
	v_and_b32_e32 v66, 64, v153
	v_add_f32_e32 v64, v65, v64
	v_xor_b32_e32 v65, 16, v153
	v_add_u32_e32 v66, 64, v66
	v_cmp_lt_i32_e32 vcc, v65, v66
	s_nop 1
	v_cndmask_b32_e32 v65, v153, v65, vcc
	v_lshlrev_b32_e32 v65, 2, v65
	ds_bpermute_b32 v65, v65, v64
	s_waitcnt lgkmcnt(0)
	v_add_f32_e32 v64, v64, v65
	v_xor_b32_e32 v65, 32, v153
	v_cmp_lt_i32_e32 vcc, v65, v66
	s_nop 1
	v_cndmask_b32_e32 v65, v153, v65, vcc
	v_lshlrev_b32_e32 v65, 2, v65
	ds_bpermute_b32 v65, v65, v64
	s_and_saveexec_b64 s[0:1], s[8:9]
	s_cbranch_execz .LBB0_615
	v_lshl_add_u64 v[66:67], v[80:81], 2, s[4:5]
	s_waitcnt lgkmcnt(0)
	v_add_f32_e32 v64, v64, v65
	global_atomic_add_f32 v[66:67], v64, off

.LBB0_616:
	s_nop 0
	v_add_u32_e32 v64, 0x80, v142
	s_waitcnt lgkmcnt(0)
	v_ashrrev_i32_e32 v65, 31, v64
	v_lshlrev_b64 v[68:69], 13, v[64:65]
	v_lshl_add_u64 v[68:69], s[96:97], 0, v[68:69]
	v_lshl_add_u64 v[70:71], v[140:141], 1, v[68:69]
	s_and_b64 vcc, exec, s[12:13]
	s_nop 0
	v_fmamk_f32 v66, v183, 0x3a000000, v152
	v_rsq_f32_e32 v66, v66
	s_nop 0
	v_pk_mul_f32 v[62:63], v[62:63], v[66:67] op_sel_hi:[1,0]
	v_pk_mul_f32 v[60:61], v[60:61], v[66:67] op_sel_hi:[1,0]
	v_pk_mul_f32 v[56:57], v[56:57], v[66:67] op_sel_hi:[1,0]
	v_pk_mul_f32 v[58:59], v[58:59], v[66:67] op_sel_hi:[1,0]
	v_pk_mul_f32 v[68:69], v[54:55], v[66:67] op_sel_hi:[1,0]
	v_pk_mul_f32 v[72:73], v[52:53], v[66:67] op_sel_hi:[1,0]
	v_pk_mul_f32 v[74:75], v[50:51], v[66:67] op_sel_hi:[1,0]
	v_pk_mul_f32 v[66:67], v[48:49], v[66:67] op_sel_hi:[1,0]
	v_mul_f32_e32 v48, 0x3d372713, v60
	v_mul_f32_e32 v49, 0x3d372713, v56
	v_mul_f32_e32 v50, 0x3d372713, v61
	v_mul_f32_e32 v51, 0x3d372713, v57
	v_mul_f32_e32 v52, 0x3d372713, v62
	v_mul_f32_e32 v54, 0x3d372713, v63
	v_mul_f32_e32 v53, 0x3d372713, v58
	v_mul_f32_e32 v55, 0x3d372713, v59
	v_mul_f32_e32 v48, v60, v48
	v_mul_f32_e32 v49, v56, v49
	v_mul_f32_e32 v50, v61, v50
	v_mul_f32_e32 v51, v57, v51
	v_mul_f32_e32 v52, v62, v52
	v_mul_f32_e32 v54, v63, v54
	v_mul_f32_e32 v53, v58, v53
	v_mul_f32_e32 v55, v59, v55
	v_fma_f32 v48, v60, v48, v60
	v_fma_f32 v49, v56, v49, v56
	v_fma_f32 v50, v61, v50, v61
	v_fma_f32 v51, v57, v51, v57
	v_fma_f32 v52, v62, v52, v62
	v_fma_f32 v54, v63, v54, v63
	v_fma_f32 v53, v58, v53, v58
	v_fma_f32 v55, v59, v55, v59
	v_mul_f32_e32 v48, 0x3f4c422a, v48
	v_mul_f32_e32 v49, 0x3f4c422a, v49
	v_mul_f32_e32 v50, 0x3f4c422a, v50
	v_mul_f32_e32 v51, 0x3f4c422a, v51
	v_mul_f32_e32 v52, 0x3f4c422a, v52
	v_mul_f32_e32 v54, 0x3f4c422a, v54
	v_mul_f32_e32 v53, 0x3f4c422a, v53
	v_mul_f32_e32 v55, 0x3f4c422a, v55
	v_mul_f32_e32 v48, 0xc038aa3b, v48
	v_mul_f32_e32 v49, 0xc038aa3b, v49
	v_mul_f32_e32 v50, 0xc038aa3b, v50
	v_mul_f32_e32 v51, 0xc038aa3b, v51
	v_mul_f32_e32 v52, 0xc038aa3b, v52
	v_mul_f32_e32 v54, 0xc038aa3b, v54
	v_mul_f32_e32 v53, 0xc038aa3b, v53
	v_mul_f32_e32 v55, 0xc038aa3b, v55
	v_exp_f32_e32 v48, v48
	v_exp_f32_e32 v49, v49
	v_exp_f32_e32 v50, v50
	v_exp_f32_e32 v51, v51
	v_exp_f32_e32 v52, v52
	v_exp_f32_e32 v54, v54
	v_exp_f32_e32 v53, v53
	v_exp_f32_e32 v55, v55
	v_add_f32_e32 v48, 1.0, v48
	v_add_f32_e32 v49, 1.0, v49
	v_add_f32_e32 v50, 1.0, v50
	v_add_f32_e32 v51, 1.0, v51
	v_add_f32_e32 v52, 1.0, v52
	v_add_f32_e32 v54, 1.0, v54
	v_add_f32_e32 v53, 1.0, v53
	v_add_f32_e32 v55, 1.0, v55
	v_rcp_f32_e32 v48, v48
	v_rcp_f32_e32 v49, v49
	v_rcp_f32_e32 v50, v50
	v_rcp_f32_e32 v78, v51
	v_rcp_f32_e32 v79, v52
	v_rcp_f32_e32 v80, v54
	v_rcp_f32_e32 v53, v53
	v_rcp_f32_e32 v81, v55
	v_mul_f32_e32 v52, v60, v48
	v_mul_f32_e32 v55, v56, v49
	v_mul_f32_e32 v51, v61, v50
	v_mul_f32_e32 v54, v57, v78
	v_mul_f32_e32 v49, v62, v79
	v_mul_f32_e32 v48, v63, v80
	v_cvt_pk_bf16_f32 v56, v52, v51
	v_cvt_pk_bf16_f32 v57, v49, v48
	v_mul_f32_e32 v53, v58, v53
	v_mul_f32_e32 v50, v59, v81
	v_cvt_pk_bf16_f32 v58, v55, v54
	v_cvt_pk_bf16_f32 v59, v53, v50
	global_store_dwordx4 v[70:71], v[56:59], off
	v_mul_f32_e32 v76, 0x3d372713, v72
	v_mul_f32_e32 v77, 0x3d372713, v66
	v_mul_f32_e32 v57, 0x3d372713, v73
	v_mul_f32_e32 v57, v73, v57
	v_fma_f32 v57, v73, v57, v73
	v_mul_f32_e32 v57, 0x3f4c422a, v57
	v_mul_f32_e32 v57, 0xc038aa3b, v57
	v_exp_f32_e32 v57, v57
	v_mul_f32_e32 v76, v72, v76
	v_mul_f32_e32 v77, v66, v77
	v_fma_f32 v76, v72, v76, v72
	v_fma_f32 v77, v66, v77, v66
	v_mul_f32_e32 v76, 0x3f4c422a, v76
	v_mul_f32_e32 v56, 0x3f4c422a, v77
	v_mul_f32_e32 v76, 0xc038aa3b, v76
	v_mul_f32_e32 v56, 0xc038aa3b, v56
	v_add_f32_e32 v57, 1.0, v57
	v_exp_f32_e32 v76, v76
	v_exp_f32_e32 v56, v56
	v_rcp_f32_e32 v59, v57
	v_mul_f32_e32 v57, 0x3d372713, v67
	v_mul_f32_e32 v57, v67, v57
	v_fma_f32 v57, v67, v57, v67
	v_mul_f32_e32 v57, 0x3f4c422a, v57
	v_add_f32_e32 v76, 1.0, v76
	v_add_f32_e32 v56, 1.0, v56
	v_mul_f32_e32 v57, 0xc038aa3b, v57
	v_rcp_f32_e32 v58, v76
	v_rcp_f32_e32 v56, v56
	v_exp_f32_e32 v60, v57
	v_mul_f32_e32 v61, 0x3d372713, v74
	v_mul_f32_e32 v61, v74, v61
	v_mul_f32_e32 v62, 0x3d372713, v69
	v_mul_f32_e32 v57, v72, v58
	v_mul_f32_e32 v58, v66, v56
	v_mul_f32_e32 v56, v73, v59
	v_add_f32_e32 v59, 1.0, v60
	v_mul_f32_e32 v60, 0x3d372713, v68
	v_fma_f32 v61, v74, v61, v74
	v_mul_f32_e32 v62, v69, v62
	v_mul_f32_e32 v63, 0x3d372713, v75
	v_mul_f32_e32 v60, v68, v60
	v_mul_f32_e32 v61, 0x3f4c422a, v61
	v_fma_f32 v62, v69, v62, v69
	v_mul_f32_e32 v63, v75, v63
	v_fma_f32 v60, v68, v60, v68
	v_mul_f32_e32 v61, 0xc038aa3b, v61
	v_mul_f32_e32 v62, 0x3f4c422a, v62
	v_fma_f32 v63, v75, v63, v75
	v_mul_f32_e32 v60, 0x3f4c422a, v60
	v_exp_f32_e32 v61, v61
	v_mul_f32_e32 v62, 0xc038aa3b, v62
	v_mul_f32_e32 v63, 0x3f4c422a, v63
	v_mul_f32_e32 v60, 0xc038aa3b, v60
	v_exp_f32_e32 v62, v62
	v_mul_f32_e32 v63, 0xc038aa3b, v63
	v_exp_f32_e32 v60, v60
	v_exp_f32_e32 v63, v63
	v_rcp_f32_e32 v59, v59
	v_add_f32_e32 v61, 1.0, v61
	v_rcp_f32_e32 v66, v61
	v_add_f32_e32 v61, 1.0, v62
	v_add_f32_e32 v60, 1.0, v60
	v_rcp_f32_e32 v62, v61
	v_add_f32_e32 v61, 1.0, v63
	v_mul_f32_e32 v59, v67, v59
	v_rcp_f32_e32 v60, v60
	v_rcp_f32_e32 v67, v61
	v_mul_f32_e32 v63, v74, v66
	v_cvt_pk_bf16_f32 v66, v57, v56
	v_mul_f32_e32 v61, v68, v60
	v_mul_f32_e32 v60, v69, v62
	v_mul_f32_e32 v62, v75, v67
	v_cvt_pk_bf16_f32 v67, v61, v60
	v_cvt_pk_bf16_f32 v68, v58, v59
	v_cvt_pk_bf16_f32 v69, v63, v62
	global_store_dwordx4 v[70:71], v[66:69], off offset:256
	s_cbranch_vccnz .LBB0_620
	v_mul_f32_e32 v55, v55, v55
	v_fmac_f32_e32 v55, v52, v52
	v_mul_f32_e32 v52, v54, v54
	v_fmac_f32_e32 v52, v51, v51
	v_add_f32_e32 v51, v55, v52
	v_mul_f32_e32 v52, v53, v53
	v_fmac_f32_e32 v52, v49, v49
	v_mul_f32_e32 v50, v50, v50
	v_add_f32_e32 v49, v52, v51
	v_fmac_f32_e32 v50, v48, v48
	v_add_f32_e32 v48, v50, v49
	v_mul_f32_e32 v49, v58, v58
	v_fmac_f32_e32 v49, v57, v57
	v_add_f32_e32 v48, v49, v48
	v_mul_f32_e32 v49, v59, v59
	v_fmac_f32_e32 v49, v56, v56
	v_add_f32_e32 v48, v49, v48
	v_mul_f32_e32 v49, v63, v63
	v_fmac_f32_e32 v49, v61, v61
	v_add_f32_e32 v48, v49, v48
	v_mul_f32_e32 v49, v62, v62
	v_fmac_f32_e32 v49, v60, v60
	v_and_b32_e32 v50, 64, v153
	v_add_f32_e32 v48, v49, v48
	v_xor_b32_e32 v49, 16, v153
	v_add_u32_e32 v50, 64, v50
	v_cmp_lt_i32_e32 vcc, v49, v50
	s_nop 1
	v_cndmask_b32_e32 v49, v153, v49, vcc
	v_lshlrev_b32_e32 v49, 2, v49
	ds_bpermute_b32 v49, v49, v48
	s_waitcnt lgkmcnt(0)
	v_add_f32_e32 v48, v48, v49
	v_xor_b32_e32 v49, 32, v153
	v_cmp_lt_i32_e32 vcc, v49, v50
	s_nop 1
	v_cndmask_b32_e32 v49, v153, v49, vcc
	v_lshlrev_b32_e32 v49, 2, v49
	ds_bpermute_b32 v49, v49, v48
	s_and_saveexec_b64 s[0:1], s[8:9]
	s_cbranch_execz .LBB0_619
	v_lshl_add_u64 v[50:51], v[64:65], 2, s[4:5]
	s_waitcnt lgkmcnt(0)
	v_add_f32_e32 v48, v48, v49
	global_atomic_add_f32 v[50:51], v48, off

.LBB0_620:
	s_nop 0
	v_add_u32_e32 v48, 0x90, v142
	s_waitcnt lgkmcnt(0)
	v_ashrrev_i32_e32 v49, 31, v48
	v_lshlrev_b64 v[52:53], 13, v[48:49]
	v_lshl_add_u64 v[52:53], s[96:97], 0, v[52:53]
	v_lshl_add_u64 v[54:55], v[140:141], 1, v[52:53]
	s_and_b64 vcc, exec, s[12:13]
	s_nop 0
	v_fmamk_f32 v50, v184, 0x3a000000, v152
	v_rsq_f32_e32 v50, v50
	s_nop 0
	v_pk_mul_f32 v[46:47], v[46:47], v[50:51] op_sel_hi:[1,0]
	v_pk_mul_f32 v[44:45], v[44:45], v[50:51] op_sel_hi:[1,0]
	v_pk_mul_f32 v[40:41], v[40:41], v[50:51] op_sel_hi:[1,0]
	v_pk_mul_f32 v[42:43], v[42:43], v[50:51] op_sel_hi:[1,0]
	v_pk_mul_f32 v[52:53], v[38:39], v[50:51] op_sel_hi:[1,0]
	v_pk_mul_f32 v[56:57], v[36:37], v[50:51] op_sel_hi:[1,0]
	v_pk_mul_f32 v[58:59], v[34:35], v[50:51] op_sel_hi:[1,0]
	v_pk_mul_f32 v[50:51], v[32:33], v[50:51] op_sel_hi:[1,0]
	v_mul_f32_e32 v32, 0x3d372713, v44
	v_mul_f32_e32 v33, 0x3d372713, v40
	v_mul_f32_e32 v34, 0x3d372713, v45
	v_mul_f32_e32 v35, 0x3d372713, v41
	v_mul_f32_e32 v36, 0x3d372713, v46
	v_mul_f32_e32 v38, 0x3d372713, v47
	v_mul_f32_e32 v37, 0x3d372713, v42
	v_mul_f32_e32 v39, 0x3d372713, v43
	v_mul_f32_e32 v32, v44, v32
	v_mul_f32_e32 v33, v40, v33
	v_mul_f32_e32 v34, v45, v34
	v_mul_f32_e32 v35, v41, v35
	v_mul_f32_e32 v36, v46, v36
	v_mul_f32_e32 v38, v47, v38
	v_mul_f32_e32 v37, v42, v37
	v_mul_f32_e32 v39, v43, v39
	v_fma_f32 v32, v44, v32, v44
	v_fma_f32 v33, v40, v33, v40
	v_fma_f32 v34, v45, v34, v45
	v_fma_f32 v35, v41, v35, v41
	v_fma_f32 v36, v46, v36, v46
	v_fma_f32 v38, v47, v38, v47
	v_fma_f32 v37, v42, v37, v42
	v_fma_f32 v39, v43, v39, v43
	v_mul_f32_e32 v32, 0x3f4c422a, v32
	v_mul_f32_e32 v33, 0x3f4c422a, v33
	v_mul_f32_e32 v34, 0x3f4c422a, v34
	v_mul_f32_e32 v35, 0x3f4c422a, v35
	v_mul_f32_e32 v36, 0x3f4c422a, v36
	v_mul_f32_e32 v38, 0x3f4c422a, v38
	v_mul_f32_e32 v37, 0x3f4c422a, v37
	v_mul_f32_e32 v39, 0x3f4c422a, v39
	v_mul_f32_e32 v32, 0xc038aa3b, v32
	v_mul_f32_e32 v33, 0xc038aa3b, v33
	v_mul_f32_e32 v34, 0xc038aa3b, v34
	v_mul_f32_e32 v35, 0xc038aa3b, v35
	v_mul_f32_e32 v36, 0xc038aa3b, v36
	v_mul_f32_e32 v38, 0xc038aa3b, v38
	v_mul_f32_e32 v37, 0xc038aa3b, v37
	v_mul_f32_e32 v39, 0xc038aa3b, v39
	v_exp_f32_e32 v32, v32
	v_exp_f32_e32 v33, v33
	v_exp_f32_e32 v34, v34
	v_exp_f32_e32 v35, v35
	v_exp_f32_e32 v36, v36
	v_exp_f32_e32 v38, v38
	v_exp_f32_e32 v37, v37
	v_exp_f32_e32 v39, v39
	v_add_f32_e32 v32, 1.0, v32
	v_add_f32_e32 v33, 1.0, v33
	v_add_f32_e32 v34, 1.0, v34
	v_add_f32_e32 v35, 1.0, v35
	v_add_f32_e32 v36, 1.0, v36
	v_add_f32_e32 v38, 1.0, v38
	v_add_f32_e32 v37, 1.0, v37
	v_add_f32_e32 v39, 1.0, v39
	v_rcp_f32_e32 v32, v32
	v_rcp_f32_e32 v33, v33
	v_rcp_f32_e32 v34, v34
	v_rcp_f32_e32 v62, v35
	v_rcp_f32_e32 v63, v36
	v_rcp_f32_e32 v64, v38
	v_rcp_f32_e32 v37, v37
	v_rcp_f32_e32 v65, v39
	v_mul_f32_e32 v36, v44, v32
	v_mul_f32_e32 v39, v40, v33
	v_mul_f32_e32 v35, v45, v34
	v_mul_f32_e32 v38, v41, v62
	v_mul_f32_e32 v33, v46, v63
	v_mul_f32_e32 v32, v47, v64
	v_cvt_pk_bf16_f32 v40, v36, v35
	v_cvt_pk_bf16_f32 v41, v33, v32
	v_mul_f32_e32 v37, v42, v37
	v_mul_f32_e32 v34, v43, v65
	v_cvt_pk_bf16_f32 v42, v39, v38
	v_cvt_pk_bf16_f32 v43, v37, v34
	global_store_dwordx4 v[54:55], v[40:43], off
	v_mul_f32_e32 v60, 0x3d372713, v56
	v_mul_f32_e32 v61, 0x3d372713, v50
	v_mul_f32_e32 v41, 0x3d372713, v57
	v_mul_f32_e32 v41, v57, v41
	v_fma_f32 v41, v57, v41, v57
	v_mul_f32_e32 v41, 0x3f4c422a, v41
	v_mul_f32_e32 v41, 0xc038aa3b, v41
	v_exp_f32_e32 v41, v41
	v_mul_f32_e32 v60, v56, v60
	v_mul_f32_e32 v61, v50, v61
	v_fma_f32 v60, v56, v60, v56
	v_fma_f32 v61, v50, v61, v50
	v_mul_f32_e32 v60, 0x3f4c422a, v60
	v_mul_f32_e32 v40, 0x3f4c422a, v61
	v_mul_f32_e32 v60, 0xc038aa3b, v60
	v_mul_f32_e32 v40, 0xc038aa3b, v40
	v_add_f32_e32 v41, 1.0, v41
	v_exp_f32_e32 v60, v60
	v_exp_f32_e32 v40, v40
	v_rcp_f32_e32 v43, v41
	v_mul_f32_e32 v41, 0x3d372713, v51
	v_mul_f32_e32 v41, v51, v41
	v_fma_f32 v41, v51, v41, v51
	v_mul_f32_e32 v41, 0x3f4c422a, v41
	v_add_f32_e32 v60, 1.0, v60
	v_add_f32_e32 v40, 1.0, v40
	v_mul_f32_e32 v41, 0xc038aa3b, v41
	v_rcp_f32_e32 v42, v60
	v_rcp_f32_e32 v40, v40
	v_exp_f32_e32 v44, v41
	v_mul_f32_e32 v45, 0x3d372713, v58
	v_mul_f32_e32 v45, v58, v45
	v_mul_f32_e32 v46, 0x3d372713, v53
	v_mul_f32_e32 v41, v56, v42
	v_mul_f32_e32 v42, v50, v40
	v_mul_f32_e32 v40, v57, v43
	v_add_f32_e32 v43, 1.0, v44
	v_mul_f32_e32 v44, 0x3d372713, v52
	v_fma_f32 v45, v58, v45, v58
	v_mul_f32_e32 v46, v53, v46
	v_mul_f32_e32 v47, 0x3d372713, v59
	v_mul_f32_e32 v44, v52, v44
	v_mul_f32_e32 v45, 0x3f4c422a, v45
	v_fma_f32 v46, v53, v46, v53
	v_mul_f32_e32 v47, v59, v47
	v_fma_f32 v44, v52, v44, v52
	v_mul_f32_e32 v45, 0xc038aa3b, v45
	v_mul_f32_e32 v46, 0x3f4c422a, v46
	v_fma_f32 v47, v59, v47, v59
	v_mul_f32_e32 v44, 0x3f4c422a, v44
	v_exp_f32_e32 v45, v45
	v_mul_f32_e32 v46, 0xc038aa3b, v46
	v_mul_f32_e32 v47, 0x3f4c422a, v47
	v_mul_f32_e32 v44, 0xc038aa3b, v44
	v_exp_f32_e32 v46, v46
	v_mul_f32_e32 v47, 0xc038aa3b, v47
	v_exp_f32_e32 v44, v44
	v_exp_f32_e32 v47, v47
	v_rcp_f32_e32 v43, v43
	v_add_f32_e32 v45, 1.0, v45
	v_rcp_f32_e32 v50, v45
	v_add_f32_e32 v45, 1.0, v46
	v_add_f32_e32 v44, 1.0, v44
	v_rcp_f32_e32 v46, v45
	v_add_f32_e32 v45, 1.0, v47
	v_mul_f32_e32 v43, v51, v43
	v_rcp_f32_e32 v44, v44
	v_rcp_f32_e32 v51, v45
	v_mul_f32_e32 v47, v58, v50
	v_cvt_pk_bf16_f32 v50, v41, v40
	v_mul_f32_e32 v45, v52, v44
	v_mul_f32_e32 v44, v53, v46
	v_mul_f32_e32 v46, v59, v51
	v_cvt_pk_bf16_f32 v51, v45, v44
	v_cvt_pk_bf16_f32 v52, v42, v43
	v_cvt_pk_bf16_f32 v53, v47, v46
	global_store_dwordx4 v[54:55], v[50:53], off offset:256
	s_cbranch_vccnz .LBB0_624
	v_mul_f32_e32 v39, v39, v39
	v_fmac_f32_e32 v39, v36, v36
	v_mul_f32_e32 v36, v38, v38
	v_fmac_f32_e32 v36, v35, v35
	v_add_f32_e32 v35, v39, v36
	v_mul_f32_e32 v36, v37, v37
	v_fmac_f32_e32 v36, v33, v33
	v_mul_f32_e32 v34, v34, v34
	v_add_f32_e32 v33, v36, v35
	v_fmac_f32_e32 v34, v32, v32
	v_add_f32_e32 v32, v34, v33
	v_mul_f32_e32 v33, v42, v42
	v_fmac_f32_e32 v33, v41, v41
	v_add_f32_e32 v32, v33, v32
	v_mul_f32_e32 v33, v43, v43
	v_fmac_f32_e32 v33, v40, v40
	v_add_f32_e32 v32, v33, v32
	v_mul_f32_e32 v33, v47, v47
	v_fmac_f32_e32 v33, v45, v45
	v_add_f32_e32 v32, v33, v32
	v_mul_f32_e32 v33, v46, v46
	v_fmac_f32_e32 v33, v44, v44
	v_and_b32_e32 v34, 64, v153
	v_add_f32_e32 v32, v33, v32
	v_xor_b32_e32 v33, 16, v153
	v_add_u32_e32 v34, 64, v34
	v_cmp_lt_i32_e32 vcc, v33, v34
	s_nop 1
	v_cndmask_b32_e32 v33, v153, v33, vcc
	v_lshlrev_b32_e32 v33, 2, v33
	ds_bpermute_b32 v33, v33, v32
	s_waitcnt lgkmcnt(0)
	v_add_f32_e32 v32, v32, v33
	v_xor_b32_e32 v33, 32, v153
	v_cmp_lt_i32_e32 vcc, v33, v34
	s_nop 1
	v_cndmask_b32_e32 v33, v153, v33, vcc
	v_lshlrev_b32_e32 v33, 2, v33
	ds_bpermute_b32 v33, v33, v32
	s_and_saveexec_b64 s[0:1], s[8:9]
	s_cbranch_execz .LBB0_623
	v_lshl_add_u64 v[34:35], v[48:49], 2, s[4:5]
	s_waitcnt lgkmcnt(0)
	v_add_f32_e32 v32, v32, v33
	global_atomic_add_f32 v[34:35], v32, off

.LBB0_624:
	s_nop 0
	v_add_u32_e32 v32, 0xa0, v142
	s_waitcnt lgkmcnt(0)
	v_ashrrev_i32_e32 v33, 31, v32
	v_lshlrev_b64 v[36:37], 13, v[32:33]
	v_lshl_add_u64 v[36:37], s[96:97], 0, v[36:37]
	v_lshl_add_u64 v[38:39], v[140:141], 1, v[36:37]
	s_and_b64 vcc, exec, s[12:13]
	s_nop 0
	v_fmamk_f32 v34, v185, 0x3a000000, v152
	v_rsq_f32_e32 v34, v34
	s_nop 0
	v_pk_mul_f32 v[30:31], v[30:31], v[34:35] op_sel_hi:[1,0]
	v_pk_mul_f32 v[28:29], v[28:29], v[34:35] op_sel_hi:[1,0]
	v_pk_mul_f32 v[24:25], v[24:25], v[34:35] op_sel_hi:[1,0]
	v_pk_mul_f32 v[26:27], v[26:27], v[34:35] op_sel_hi:[1,0]
	v_pk_mul_f32 v[36:37], v[22:23], v[34:35] op_sel_hi:[1,0]
	v_pk_mul_f32 v[40:41], v[20:21], v[34:35] op_sel_hi:[1,0]
	v_pk_mul_f32 v[42:43], v[18:19], v[34:35] op_sel_hi:[1,0]
	v_pk_mul_f32 v[34:35], v[16:17], v[34:35] op_sel_hi:[1,0]
	v_mul_f32_e32 v16, 0x3d372713, v28
	v_mul_f32_e32 v17, 0x3d372713, v24
	v_mul_f32_e32 v18, 0x3d372713, v29
	v_mul_f32_e32 v19, 0x3d372713, v25
	v_mul_f32_e32 v20, 0x3d372713, v30
	v_mul_f32_e32 v22, 0x3d372713, v31
	v_mul_f32_e32 v21, 0x3d372713, v26
	v_mul_f32_e32 v23, 0x3d372713, v27
	v_mul_f32_e32 v16, v28, v16
	v_mul_f32_e32 v17, v24, v17
	v_mul_f32_e32 v18, v29, v18
	v_mul_f32_e32 v19, v25, v19
	v_mul_f32_e32 v20, v30, v20
	v_mul_f32_e32 v22, v31, v22
	v_mul_f32_e32 v21, v26, v21
	v_mul_f32_e32 v23, v27, v23
	v_fma_f32 v16, v28, v16, v28
	v_fma_f32 v17, v24, v17, v24
	v_fma_f32 v18, v29, v18, v29
	v_fma_f32 v19, v25, v19, v25
	v_fma_f32 v20, v30, v20, v30
	v_fma_f32 v22, v31, v22, v31
	v_fma_f32 v21, v26, v21, v26
	v_fma_f32 v23, v27, v23, v27
	v_mul_f32_e32 v16, 0x3f4c422a, v16
	v_mul_f32_e32 v17, 0x3f4c422a, v17
	v_mul_f32_e32 v18, 0x3f4c422a, v18
	v_mul_f32_e32 v19, 0x3f4c422a, v19
	v_mul_f32_e32 v20, 0x3f4c422a, v20
	v_mul_f32_e32 v22, 0x3f4c422a, v22
	v_mul_f32_e32 v21, 0x3f4c422a, v21
	v_mul_f32_e32 v23, 0x3f4c422a, v23
	v_mul_f32_e32 v16, 0xc038aa3b, v16
	v_mul_f32_e32 v17, 0xc038aa3b, v17
	v_mul_f32_e32 v18, 0xc038aa3b, v18
	v_mul_f32_e32 v19, 0xc038aa3b, v19
	v_mul_f32_e32 v20, 0xc038aa3b, v20
	v_mul_f32_e32 v22, 0xc038aa3b, v22
	v_mul_f32_e32 v21, 0xc038aa3b, v21
	v_mul_f32_e32 v23, 0xc038aa3b, v23
	v_exp_f32_e32 v16, v16
	v_exp_f32_e32 v17, v17
	v_exp_f32_e32 v18, v18
	v_exp_f32_e32 v19, v19
	v_exp_f32_e32 v20, v20
	v_exp_f32_e32 v22, v22
	v_exp_f32_e32 v21, v21
	v_exp_f32_e32 v23, v23
	v_add_f32_e32 v16, 1.0, v16
	v_add_f32_e32 v17, 1.0, v17
	v_add_f32_e32 v18, 1.0, v18
	v_add_f32_e32 v19, 1.0, v19
	v_add_f32_e32 v20, 1.0, v20
	v_add_f32_e32 v22, 1.0, v22
	v_add_f32_e32 v21, 1.0, v21
	v_add_f32_e32 v23, 1.0, v23
	v_rcp_f32_e32 v16, v16
	v_rcp_f32_e32 v17, v17
	v_rcp_f32_e32 v18, v18
	v_rcp_f32_e32 v46, v19
	v_rcp_f32_e32 v47, v20
	v_rcp_f32_e32 v48, v22
	v_rcp_f32_e32 v21, v21
	v_rcp_f32_e32 v49, v23
	v_mul_f32_e32 v20, v28, v16
	v_mul_f32_e32 v23, v24, v17
	v_mul_f32_e32 v19, v29, v18
	v_mul_f32_e32 v22, v25, v46
	v_mul_f32_e32 v17, v30, v47
	v_mul_f32_e32 v16, v31, v48
	v_cvt_pk_bf16_f32 v24, v20, v19
	v_cvt_pk_bf16_f32 v25, v17, v16
	v_mul_f32_e32 v21, v26, v21
	v_mul_f32_e32 v18, v27, v49
	v_cvt_pk_bf16_f32 v26, v23, v22
	v_cvt_pk_bf16_f32 v27, v21, v18
	global_store_dwordx4 v[38:39], v[24:27], off
	v_mul_f32_e32 v44, 0x3d372713, v40
	v_mul_f32_e32 v45, 0x3d372713, v34
	v_mul_f32_e32 v25, 0x3d372713, v41
	v_mul_f32_e32 v25, v41, v25
	v_fma_f32 v25, v41, v25, v41
	v_mul_f32_e32 v25, 0x3f4c422a, v25
	v_mul_f32_e32 v25, 0xc038aa3b, v25
	v_exp_f32_e32 v25, v25
	v_mul_f32_e32 v44, v40, v44
	v_mul_f32_e32 v45, v34, v45
	v_fma_f32 v44, v40, v44, v40
	v_fma_f32 v45, v34, v45, v34
	v_mul_f32_e32 v44, 0x3f4c422a, v44
	v_mul_f32_e32 v24, 0x3f4c422a, v45
	v_mul_f32_e32 v44, 0xc038aa3b, v44
	v_mul_f32_e32 v24, 0xc038aa3b, v24
	v_add_f32_e32 v25, 1.0, v25
	v_exp_f32_e32 v44, v44
	v_exp_f32_e32 v24, v24
	v_rcp_f32_e32 v27, v25
	v_mul_f32_e32 v25, 0x3d372713, v35
	v_mul_f32_e32 v25, v35, v25
	v_fma_f32 v25, v35, v25, v35
	v_mul_f32_e32 v25, 0x3f4c422a, v25
	v_add_f32_e32 v44, 1.0, v44
	v_add_f32_e32 v24, 1.0, v24
	v_mul_f32_e32 v25, 0xc038aa3b, v25
	v_rcp_f32_e32 v26, v44
	v_rcp_f32_e32 v24, v24
	v_exp_f32_e32 v28, v25
	v_mul_f32_e32 v29, 0x3d372713, v42
	v_mul_f32_e32 v29, v42, v29
	v_mul_f32_e32 v30, 0x3d372713, v37
	v_mul_f32_e32 v25, v40, v26
	v_mul_f32_e32 v26, v34, v24
	v_mul_f32_e32 v24, v41, v27
	v_add_f32_e32 v27, 1.0, v28
	v_mul_f32_e32 v28, 0x3d372713, v36
	v_fma_f32 v29, v42, v29, v42
	v_mul_f32_e32 v30, v37, v30
	v_mul_f32_e32 v31, 0x3d372713, v43
	v_mul_f32_e32 v28, v36, v28
	v_mul_f32_e32 v29, 0x3f4c422a, v29
	v_fma_f32 v30, v37, v30, v37
	v_mul_f32_e32 v31, v43, v31
	v_fma_f32 v28, v36, v28, v36
	v_mul_f32_e32 v29, 0xc038aa3b, v29
	v_mul_f32_e32 v30, 0x3f4c422a, v30
	v_fma_f32 v31, v43, v31, v43
	v_mul_f32_e32 v28, 0x3f4c422a, v28
	v_exp_f32_e32 v29, v29
	v_mul_f32_e32 v30, 0xc038aa3b, v30
	v_mul_f32_e32 v31, 0x3f4c422a, v31
	v_mul_f32_e32 v28, 0xc038aa3b, v28
	v_exp_f32_e32 v30, v30
	v_mul_f32_e32 v31, 0xc038aa3b, v31
	v_exp_f32_e32 v28, v28
	v_exp_f32_e32 v31, v31
	v_rcp_f32_e32 v27, v27
	v_add_f32_e32 v29, 1.0, v29
	v_rcp_f32_e32 v34, v29
	v_add_f32_e32 v29, 1.0, v30
	v_add_f32_e32 v28, 1.0, v28
	v_rcp_f32_e32 v30, v29
	v_add_f32_e32 v29, 1.0, v31
	v_mul_f32_e32 v27, v35, v27
	v_rcp_f32_e32 v28, v28
	v_rcp_f32_e32 v35, v29
	v_mul_f32_e32 v31, v42, v34
	v_cvt_pk_bf16_f32 v34, v25, v24
	v_mul_f32_e32 v29, v36, v28
	v_mul_f32_e32 v28, v37, v30
	v_mul_f32_e32 v30, v43, v35
	v_cvt_pk_bf16_f32 v35, v29, v28
	v_cvt_pk_bf16_f32 v36, v26, v27
	v_cvt_pk_bf16_f32 v37, v31, v30
	global_store_dwordx4 v[38:39], v[34:37], off offset:256
	s_cbranch_vccnz .LBB0_628
	v_mul_f32_e32 v23, v23, v23
	v_fmac_f32_e32 v23, v20, v20
	v_mul_f32_e32 v20, v22, v22
	v_fmac_f32_e32 v20, v19, v19
	v_add_f32_e32 v19, v23, v20
	v_mul_f32_e32 v20, v21, v21
	v_fmac_f32_e32 v20, v17, v17
	v_mul_f32_e32 v18, v18, v18
	v_add_f32_e32 v17, v20, v19
	v_fmac_f32_e32 v18, v16, v16
	v_add_f32_e32 v16, v18, v17
	v_mul_f32_e32 v17, v26, v26
	v_fmac_f32_e32 v17, v25, v25
	v_add_f32_e32 v16, v17, v16
	v_mul_f32_e32 v17, v27, v27
	v_fmac_f32_e32 v17, v24, v24
	v_add_f32_e32 v16, v17, v16
	v_mul_f32_e32 v17, v31, v31
	v_fmac_f32_e32 v17, v29, v29
	v_add_f32_e32 v16, v17, v16
	v_mul_f32_e32 v17, v30, v30
	v_fmac_f32_e32 v17, v28, v28
	v_and_b32_e32 v18, 64, v153
	v_add_f32_e32 v16, v17, v16
	v_xor_b32_e32 v17, 16, v153
	v_add_u32_e32 v18, 64, v18
	v_cmp_lt_i32_e32 vcc, v17, v18
	s_nop 1
	v_cndmask_b32_e32 v17, v153, v17, vcc
	v_lshlrev_b32_e32 v17, 2, v17
	ds_bpermute_b32 v17, v17, v16
	s_waitcnt lgkmcnt(0)
	v_add_f32_e32 v16, v16, v17
	v_xor_b32_e32 v17, 32, v153
	v_cmp_lt_i32_e32 vcc, v17, v18
	s_nop 1
	v_cndmask_b32_e32 v17, v153, v17, vcc
	v_lshlrev_b32_e32 v17, 2, v17
	ds_bpermute_b32 v17, v17, v16
	s_and_saveexec_b64 s[0:1], s[8:9]
	s_cbranch_execz .LBB0_627
	v_lshl_add_u64 v[18:19], v[32:33], 2, s[4:5]
	s_waitcnt lgkmcnt(0)
	v_add_f32_e32 v16, v16, v17
	global_atomic_add_f32 v[18:19], v16, off

.LBB0_628:
	s_nop 0
	v_add_u32_e32 v16, 0xb0, v142
	s_waitcnt lgkmcnt(0)
	v_ashrrev_i32_e32 v17, 31, v16
	v_lshlrev_b64 v[20:21], 13, v[16:17]
	v_lshl_add_u64 v[20:21], s[96:97], 0, v[20:21]
	v_lshl_add_u64 v[22:23], v[140:141], 1, v[20:21]
	s_and_b64 vcc, exec, s[12:13]
	s_nop 0
	v_fmamk_f32 v18, v186, 0x3a000000, v152
	v_rsq_f32_e32 v18, v18
	s_nop 0
	v_pk_mul_f32 v[14:15], v[14:15], v[18:19] op_sel_hi:[1,0]
	v_pk_mul_f32 v[12:13], v[12:13], v[18:19] op_sel_hi:[1,0]
	v_pk_mul_f32 v[8:9], v[8:9], v[18:19] op_sel_hi:[1,0]
	v_pk_mul_f32 v[10:11], v[10:11], v[18:19] op_sel_hi:[1,0]
	v_pk_mul_f32 v[20:21], v[6:7], v[18:19] op_sel_hi:[1,0]
	v_pk_mul_f32 v[24:25], v[4:5], v[18:19] op_sel_hi:[1,0]
	v_pk_mul_f32 v[26:27], v[2:3], v[18:19] op_sel_hi:[1,0]
	v_pk_mul_f32 v[18:19], v[0:1], v[18:19] op_sel_hi:[1,0]
	v_mul_f32_e32 v0, 0x3d372713, v12
	v_mul_f32_e32 v1, 0x3d372713, v8
	v_mul_f32_e32 v2, 0x3d372713, v13
	v_mul_f32_e32 v3, 0x3d372713, v9
	v_mul_f32_e32 v4, 0x3d372713, v14
	v_mul_f32_e32 v6, 0x3d372713, v15
	v_mul_f32_e32 v5, 0x3d372713, v10
	v_mul_f32_e32 v7, 0x3d372713, v11
	v_mul_f32_e32 v0, v12, v0
	v_mul_f32_e32 v1, v8, v1
	v_mul_f32_e32 v2, v13, v2
	v_mul_f32_e32 v3, v9, v3
	v_mul_f32_e32 v4, v14, v4
	v_mul_f32_e32 v6, v15, v6
	v_mul_f32_e32 v5, v10, v5
	v_mul_f32_e32 v7, v11, v7
	v_fma_f32 v0, v12, v0, v12
	v_fma_f32 v1, v8, v1, v8
	v_fma_f32 v2, v13, v2, v13
	v_fma_f32 v3, v9, v3, v9
	v_fma_f32 v4, v14, v4, v14
	v_fma_f32 v6, v15, v6, v15
	v_fma_f32 v5, v10, v5, v10
	v_fma_f32 v7, v11, v7, v11
	v_mul_f32_e32 v0, 0x3f4c422a, v0
	v_mul_f32_e32 v1, 0x3f4c422a, v1
	v_mul_f32_e32 v2, 0x3f4c422a, v2
	v_mul_f32_e32 v3, 0x3f4c422a, v3
	v_mul_f32_e32 v4, 0x3f4c422a, v4
	v_mul_f32_e32 v6, 0x3f4c422a, v6
	v_mul_f32_e32 v5, 0x3f4c422a, v5
	v_mul_f32_e32 v7, 0x3f4c422a, v7
	v_mul_f32_e32 v0, 0xc038aa3b, v0
	v_mul_f32_e32 v1, 0xc038aa3b, v1
	v_mul_f32_e32 v2, 0xc038aa3b, v2
	v_mul_f32_e32 v3, 0xc038aa3b, v3
	v_mul_f32_e32 v4, 0xc038aa3b, v4
	v_mul_f32_e32 v6, 0xc038aa3b, v6
	v_mul_f32_e32 v5, 0xc038aa3b, v5
	v_mul_f32_e32 v7, 0xc038aa3b, v7
	v_exp_f32_e32 v0, v0
	v_exp_f32_e32 v1, v1
	v_exp_f32_e32 v2, v2
	v_exp_f32_e32 v3, v3
	v_exp_f32_e32 v4, v4
	v_exp_f32_e32 v6, v6
	v_exp_f32_e32 v5, v5
	v_exp_f32_e32 v7, v7
	v_add_f32_e32 v0, 1.0, v0
	v_add_f32_e32 v1, 1.0, v1
	v_add_f32_e32 v2, 1.0, v2
	v_add_f32_e32 v3, 1.0, v3
	v_add_f32_e32 v4, 1.0, v4
	v_add_f32_e32 v6, 1.0, v6
	v_add_f32_e32 v5, 1.0, v5
	v_add_f32_e32 v7, 1.0, v7
	v_rcp_f32_e32 v0, v0
	v_rcp_f32_e32 v1, v1
	v_rcp_f32_e32 v2, v2
	v_rcp_f32_e32 v30, v3
	v_rcp_f32_e32 v31, v4
	v_rcp_f32_e32 v32, v6
	v_rcp_f32_e32 v5, v5
	v_rcp_f32_e32 v33, v7
	v_mul_f32_e32 v4, v12, v0
	v_mul_f32_e32 v7, v8, v1
	v_mul_f32_e32 v3, v13, v2
	v_mul_f32_e32 v6, v9, v30
	v_mul_f32_e32 v1, v14, v31
	v_mul_f32_e32 v0, v15, v32
	v_cvt_pk_bf16_f32 v8, v4, v3
	v_cvt_pk_bf16_f32 v9, v1, v0
	v_mul_f32_e32 v5, v10, v5
	v_mul_f32_e32 v2, v11, v33
	v_cvt_pk_bf16_f32 v10, v7, v6
	v_cvt_pk_bf16_f32 v11, v5, v2
	global_store_dwordx4 v[22:23], v[8:11], off
	v_mul_f32_e32 v28, 0x3d372713, v24
	v_mul_f32_e32 v29, 0x3d372713, v18
	v_mul_f32_e32 v9, 0x3d372713, v25
	v_mul_f32_e32 v9, v25, v9
	v_fma_f32 v9, v25, v9, v25
	v_mul_f32_e32 v9, 0x3f4c422a, v9
	v_mul_f32_e32 v9, 0xc038aa3b, v9
	v_exp_f32_e32 v9, v9
	v_mul_f32_e32 v28, v24, v28
	v_mul_f32_e32 v29, v18, v29
	v_fma_f32 v28, v24, v28, v24
	v_fma_f32 v29, v18, v29, v18
	v_mul_f32_e32 v28, 0x3f4c422a, v28
	v_mul_f32_e32 v8, 0x3f4c422a, v29
	v_mul_f32_e32 v28, 0xc038aa3b, v28
	v_mul_f32_e32 v8, 0xc038aa3b, v8
	v_add_f32_e32 v9, 1.0, v9
	v_exp_f32_e32 v28, v28
	v_exp_f32_e32 v8, v8
	v_rcp_f32_e32 v11, v9
	v_mul_f32_e32 v9, 0x3d372713, v19
	v_mul_f32_e32 v9, v19, v9
	v_fma_f32 v9, v19, v9, v19
	v_mul_f32_e32 v9, 0x3f4c422a, v9
	v_add_f32_e32 v28, 1.0, v28
	v_add_f32_e32 v8, 1.0, v8
	v_mul_f32_e32 v9, 0xc038aa3b, v9
	v_rcp_f32_e32 v10, v28
	v_rcp_f32_e32 v8, v8
	v_exp_f32_e32 v12, v9
	v_mul_f32_e32 v13, 0x3d372713, v26
	v_mul_f32_e32 v13, v26, v13
	v_mul_f32_e32 v14, 0x3d372713, v21
	v_mul_f32_e32 v9, v24, v10
	v_mul_f32_e32 v10, v18, v8
	v_mul_f32_e32 v8, v25, v11
	v_add_f32_e32 v11, 1.0, v12
	v_mul_f32_e32 v12, 0x3d372713, v20
	v_fma_f32 v13, v26, v13, v26
	v_mul_f32_e32 v14, v21, v14
	v_mul_f32_e32 v15, 0x3d372713, v27
	v_mul_f32_e32 v12, v20, v12
	v_mul_f32_e32 v13, 0x3f4c422a, v13
	v_fma_f32 v14, v21, v14, v21
	v_mul_f32_e32 v15, v27, v15
	v_fma_f32 v12, v20, v12, v20
	v_mul_f32_e32 v13, 0xc038aa3b, v13
	v_mul_f32_e32 v14, 0x3f4c422a, v14
	v_fma_f32 v15, v27, v15, v27
	v_mul_f32_e32 v12, 0x3f4c422a, v12
	v_exp_f32_e32 v13, v13
	v_mul_f32_e32 v14, 0xc038aa3b, v14
	v_mul_f32_e32 v15, 0x3f4c422a, v15
	v_mul_f32_e32 v12, 0xc038aa3b, v12
	v_exp_f32_e32 v14, v14
	v_mul_f32_e32 v15, 0xc038aa3b, v15
	v_exp_f32_e32 v12, v12
	v_exp_f32_e32 v15, v15
	v_rcp_f32_e32 v11, v11
	v_add_f32_e32 v13, 1.0, v13
	v_rcp_f32_e32 v18, v13
	v_add_f32_e32 v13, 1.0, v14
	v_add_f32_e32 v12, 1.0, v12
	v_rcp_f32_e32 v14, v13
	v_add_f32_e32 v13, 1.0, v15
	v_mul_f32_e32 v11, v19, v11
	v_rcp_f32_e32 v12, v12
	v_rcp_f32_e32 v19, v13
	v_mul_f32_e32 v15, v26, v18
	v_cvt_pk_bf16_f32 v18, v9, v8
	v_mul_f32_e32 v13, v20, v12
	v_mul_f32_e32 v12, v21, v14
	v_mul_f32_e32 v14, v27, v19
	v_cvt_pk_bf16_f32 v19, v13, v12
	v_cvt_pk_bf16_f32 v20, v10, v11
	v_cvt_pk_bf16_f32 v21, v15, v14
	global_store_dwordx4 v[22:23], v[18:21], off offset:256
	s_cbranch_vccnz .LBB0_591
	v_mul_f32_e32 v7, v7, v7
	v_fmac_f32_e32 v7, v4, v4
	v_mul_f32_e32 v4, v6, v6
	v_fmac_f32_e32 v4, v3, v3
	v_add_f32_e32 v3, v7, v4
	v_mul_f32_e32 v4, v5, v5
	v_fmac_f32_e32 v4, v1, v1
	v_mul_f32_e32 v2, v2, v2
	v_add_f32_e32 v1, v4, v3
	v_fmac_f32_e32 v2, v0, v0
	v_add_f32_e32 v0, v2, v1
	v_mul_f32_e32 v1, v10, v10
	v_fmac_f32_e32 v1, v9, v9
	v_add_f32_e32 v0, v1, v0
	v_mul_f32_e32 v1, v11, v11
	v_fmac_f32_e32 v1, v8, v8
	v_add_f32_e32 v0, v1, v0
	v_mul_f32_e32 v1, v15, v15
	v_fmac_f32_e32 v1, v13, v13
	v_add_f32_e32 v0, v1, v0
	v_mul_f32_e32 v1, v14, v14
	v_fmac_f32_e32 v1, v12, v12
	v_and_b32_e32 v2, 64, v153
	v_add_f32_e32 v0, v1, v0
	v_xor_b32_e32 v1, 16, v153
	v_add_u32_e32 v2, 64, v2
	v_cmp_lt_i32_e32 vcc, v1, v2
	s_nop 1
	v_cndmask_b32_e32 v1, v153, v1, vcc
	v_lshlrev_b32_e32 v1, 2, v1
	ds_bpermute_b32 v1, v1, v0
	s_waitcnt lgkmcnt(0)
	v_add_f32_e32 v0, v0, v1
	v_xor_b32_e32 v1, 32, v153
	v_cmp_lt_i32_e32 vcc, v1, v2
	s_nop 1
	v_cndmask_b32_e32 v1, v153, v1, vcc
	v_lshlrev_b32_e32 v1, 2, v1
	ds_bpermute_b32 v1, v1, v0
	s_and_saveexec_b64 s[0:1], s[8:9]
	s_cbranch_execz .LBB0_590
	v_lshl_add_u64 v[2:3], v[16:17], 2, s[4:5]
	s_waitcnt lgkmcnt(0)
	v_add_f32_e32 v0, v0, v1
	global_atomic_add_f32 v[2:3], v0, off
	s_branch .LBB0_590

.LBB0_760:
	ds_read_b128 v[140:143], v145
	v_xor_b32_e32 v161, 64, v145
	ds_read_b128 v[150:153], v161
	ds_read_b128 v[154:157], v145 offset:2048
	ds_read_b128 v[158:161], v161 offset:2048
	s_add_u32 s22, s20, 0xfff00080
	s_addc_u32 s23, s21, -1
	s_cmp_eq_u32 s45, 28
	s_cselect_b32 s25, s1, s23
	s_cselect_b32 s24, s9, s22
	s_cselect_b32 s23, s13, s44
	s_cselect_b32 s22, s15, s43
	v_lshl_add_u64 v[208:209], s[20:21], 0, v[132:133]
	s_add_i32 m0, s29, 0xc000
	ds_read_b128 v[176:179], v146
	v_xor_b32_e32 v207, 64, v146
	ds_read_b128 v[180:183], v207
	ds_read_b128 v[184:187], v146 offset:2048
	ds_read_b128 v[188:191], v207 offset:2048
	ds_read_b128 v[192:195], v146 offset:4096
	ds_read_b128 v[196:199], v207 offset:4096
	ds_read_b128 v[200:203], v146 offset:6144
	ds_read_b128 v[204:207], v207 offset:6144
	global_load_lds_dwordx4 v[208:209], off
	v_lshl_add_u64 v[208:209], s[20:21], 0, v[134:135]
	s_add_i32 m0, s29, 0xe000
	s_nop 0
	global_load_lds_dwordx4 v[208:209], off
	s_waitcnt lgkmcnt(8)
	s_barrier
	s_waitcnt lgkmcnt(0)
	s_setprio 1
	s_waitcnt lgkmcnt(0)
	v_mfma_f32_16x16x32_bf16 v[124:127], v[140:143], v[176:179], v[124:127]
	v_mfma_f32_16x16x32_bf16 v[120:123], v[154:157], v[176:179], v[120:123]
	v_mfma_f32_16x16x32_bf16 v[108:111], v[140:143], v[184:187], v[108:111]
	v_mfma_f32_16x16x32_bf16 v[104:107], v[154:157], v[184:187], v[104:107]
	v_mfma_f32_16x16x32_bf16 v[92:95], v[140:143], v[192:195], v[92:95]
	v_mfma_f32_16x16x32_bf16 v[88:91], v[154:157], v[192:195], v[88:91]
	v_mfma_f32_16x16x32_bf16 v[76:79], v[140:143], v[200:203], v[76:79]
	v_mfma_f32_16x16x32_bf16 v[72:75], v[154:157], v[200:203], v[72:75]
	v_mfma_f32_16x16x32_bf16 v[124:127], v[150:153], v[180:183], v[124:127]
	v_mfma_f32_16x16x32_bf16 v[120:123], v[158:161], v[180:183], v[120:123]
	v_mfma_f32_16x16x32_bf16 v[108:111], v[150:153], v[188:191], v[108:111]
	v_mfma_f32_16x16x32_bf16 v[104:107], v[158:161], v[188:191], v[104:107]
	v_mfma_f32_16x16x32_bf16 v[92:95], v[150:153], v[196:199], v[92:95]
	v_mfma_f32_16x16x32_bf16 v[88:91], v[158:161], v[196:199], v[88:91]
	v_mfma_f32_16x16x32_bf16 v[76:79], v[150:153], v[204:207], v[76:79]
	v_mfma_f32_16x16x32_bf16 v[72:75], v[158:161], v[204:207], v[72:75]
	s_setprio 0
	s_barrier
	s_add_i32 s46, s41, s28
	v_lshl_add_u64 v[216:217], s[22:23], 0, v[164:165]
	s_mov_b32 m0, s46
	ds_read_b128 v[208:211], v147
	v_xor_b32_e32 v243, 64, v147
	ds_read_b128 v[212:215], v243
	ds_read_b128 v[236:239], v147 offset:2048
	ds_read_b128 v[240:243], v243 offset:2048
	global_load_lds_dwordx4 v[216:217], off
	v_lshl_add_u64 v[234:235], s[22:23], 0, v[166:167]
	s_add_i32 m0, s46, 0x2000
	s_nop 0
	global_load_lds_dwordx4 v[234:235], off
	s_barrier
	s_waitcnt lgkmcnt(0)
	s_setprio 1
	s_waitcnt lgkmcnt(0)
	v_mfma_f32_16x16x32_bf16 v[116:119], v[208:211], v[176:179], v[116:119]
	v_mfma_f32_16x16x32_bf16 v[112:115], v[236:239], v[176:179], v[112:115]
	v_mfma_f32_16x16x32_bf16 v[100:103], v[208:211], v[184:187], v[100:103]
	v_mfma_f32_16x16x32_bf16 v[96:99], v[236:239], v[184:187], v[96:99]
	v_mfma_f32_16x16x32_bf16 v[84:87], v[208:211], v[192:195], v[84:87]
	v_mfma_f32_16x16x32_bf16 v[80:83], v[236:239], v[192:195], v[80:83]
	v_mfma_f32_16x16x32_bf16 v[68:71], v[208:211], v[200:203], v[68:71]
	v_mfma_f32_16x16x32_bf16 v[64:67], v[236:239], v[200:203], v[64:67]
	v_mfma_f32_16x16x32_bf16 v[116:119], v[212:215], v[180:183], v[116:119]
	v_mfma_f32_16x16x32_bf16 v[112:115], v[240:243], v[180:183], v[112:115]
	v_mfma_f32_16x16x32_bf16 v[100:103], v[212:215], v[188:191], v[100:103]
	v_mfma_f32_16x16x32_bf16 v[96:99], v[240:243], v[188:191], v[96:99]
	v_mfma_f32_16x16x32_bf16 v[84:87], v[212:215], v[196:199], v[84:87]
	v_mfma_f32_16x16x32_bf16 v[80:83], v[240:243], v[196:199], v[80:83]
	v_mfma_f32_16x16x32_bf16 v[68:71], v[212:215], v[204:207], v[68:71]
	v_mfma_f32_16x16x32_bf16 v[64:67], v[240:243], v[204:207], v[64:67]
	s_setprio 0
	s_mov_b32 m0, s29
	v_lshl_add_u64 v[244:245], s[24:25], 0, v[128:129]
	s_barrier
	ds_read_b128 v[176:179], v146 offset:16384
	v_xor_b32_e32 v207, 64, v146
	ds_read_b128 v[180:183], v207 offset:16384
	ds_read_b128 v[184:187], v146 offset:18432
	ds_read_b128 v[188:191], v207 offset:18432
	ds_read_b128 v[192:195], v146 offset:20480
	ds_read_b128 v[196:199], v207 offset:20480
	ds_read_b128 v[200:203], v146 offset:22528
	ds_read_b128 v[204:207], v207 offset:22528
	global_load_lds_dwordx4 v[244:245], off
	v_lshl_add_u64 v[246:247], s[24:25], 0, v[130:131]
	s_mov_b32 m0, s30
	s_nop 0
	global_load_lds_dwordx4 v[246:247], off
	s_barrier
	s_waitcnt lgkmcnt(0)
	s_setprio 1
	s_waitcnt lgkmcnt(0)
	v_mfma_f32_16x16x32_bf16 v[60:63], v[140:143], v[176:179], v[60:63]
	v_mfma_f32_16x16x32_bf16 v[56:59], v[154:157], v[176:179], v[56:59]
	v_mfma_f32_16x16x32_bf16 v[44:47], v[140:143], v[184:187], v[44:47]
	v_mfma_f32_16x16x32_bf16 v[40:43], v[154:157], v[184:187], v[40:43]
	v_mfma_f32_16x16x32_bf16 v[28:31], v[140:143], v[192:195], v[28:31]
	v_mfma_f32_16x16x32_bf16 v[24:27], v[154:157], v[192:195], v[24:27]
	v_mfma_f32_16x16x32_bf16 v[12:15], v[140:143], v[200:203], v[12:15]
	v_mfma_f32_16x16x32_bf16 v[8:11], v[154:157], v[200:203], v[8:11]
	v_mfma_f32_16x16x32_bf16 v[60:63], v[150:153], v[180:183], v[60:63]
	v_mfma_f32_16x16x32_bf16 v[56:59], v[158:161], v[180:183], v[56:59]
	v_mfma_f32_16x16x32_bf16 v[44:47], v[150:153], v[188:191], v[44:47]
	v_mfma_f32_16x16x32_bf16 v[40:43], v[158:161], v[188:191], v[40:43]
	v_mfma_f32_16x16x32_bf16 v[28:31], v[150:153], v[196:199], v[28:31]
	v_mfma_f32_16x16x32_bf16 v[24:27], v[158:161], v[196:199], v[24:27]
	v_mfma_f32_16x16x32_bf16 v[12:15], v[150:153], v[204:207], v[12:15]
	v_mfma_f32_16x16x32_bf16 v[8:11], v[158:161], v[204:207], v[8:11]
	s_setprio 0
	s_barrier
	s_add_u32 s46, s22, 0x80000
	s_addc_u32 s47, s23, 0
	s_add_i32 s48, s42, s28
	v_lshl_add_u64 v[140:141], s[46:47], 0, v[164:165]
	s_mov_b32 m0, s48
	s_nop 0
	global_load_lds_dwordx4 v[140:141], off
	v_lshl_add_u64 v[140:141], s[46:47], 0, v[166:167]
	s_add_i32 m0, s48, 0x2000
	s_nop 0
	global_load_lds_dwordx4 v[140:141], off
	s_waitcnt vmcnt(6)
	s_barrier
	s_setprio 1
	v_mfma_f32_16x16x32_bf16 v[52:55], v[208:211], v[176:179], v[52:55]
	v_mfma_f32_16x16x32_bf16 v[48:51], v[236:239], v[176:179], v[48:51]
	v_mfma_f32_16x16x32_bf16 v[36:39], v[208:211], v[184:187], v[36:39]
	v_mfma_f32_16x16x32_bf16 v[32:35], v[236:239], v[184:187], v[32:35]
	v_mfma_f32_16x16x32_bf16 v[20:23], v[208:211], v[192:195], v[20:23]
	v_mfma_f32_16x16x32_bf16 v[16:19], v[236:239], v[192:195], v[16:19]
	v_mfma_f32_16x16x32_bf16 v[4:7], v[208:211], v[200:203], v[4:7]
	v_mfma_f32_16x16x32_bf16 v[0:3], v[236:239], v[200:203], v[0:3]
	v_mfma_f32_16x16x32_bf16 v[52:55], v[212:215], v[180:183], v[52:55]
	v_mfma_f32_16x16x32_bf16 v[48:51], v[240:243], v[180:183], v[48:51]
	v_mfma_f32_16x16x32_bf16 v[36:39], v[212:215], v[188:191], v[36:39]
	v_mfma_f32_16x16x32_bf16 v[32:35], v[240:243], v[188:191], v[32:35]
	v_mfma_f32_16x16x32_bf16 v[20:23], v[212:215], v[196:199], v[20:23]
	v_mfma_f32_16x16x32_bf16 v[16:19], v[240:243], v[196:199], v[16:19]
	v_mfma_f32_16x16x32_bf16 v[4:7], v[212:215], v[204:207], v[4:7]
	v_mfma_f32_16x16x32_bf16 v[0:3], v[240:243], v[204:207], v[0:3]
	s_setprio 0
	s_add_i32 s46, 0, 0x18000
	v_add_u32_e32 v149, s46, v144
	s_barrier
	ds_read_b128 v[140:143], v149
	v_xor_b32_e32 v161, 64, v149
	ds_read_b128 v[150:153], v161
	ds_read_b128 v[154:157], v149 offset:2048
	ds_read_b128 v[158:161], v161 offset:2048
	s_add_u32 s24, s24, 0x100000
	s_addc_u32 s25, s25, 0
	s_mov_b32 m0, s31
	v_lshl_add_u64 v[208:209], s[24:25], 0, v[128:129]
	ds_read_b128 v[176:179], v146 offset:32768
	v_xor_b32_e32 v207, 64, v146
	ds_read_b128 v[180:183], v207 offset:32768
	ds_read_b128 v[184:187], v146 offset:34816
	ds_read_b128 v[188:191], v207 offset:34816
	ds_read_b128 v[192:195], v146 offset:36864
	ds_read_b128 v[196:199], v207 offset:36864
	ds_read_b128 v[200:203], v146 offset:38912
	ds_read_b128 v[204:207], v207 offset:38912
	global_load_lds_dwordx4 v[208:209], off
	v_lshl_add_u64 v[208:209], s[24:25], 0, v[130:131]
	s_mov_b32 m0, s33
	s_nop 0
	global_load_lds_dwordx4 v[208:209], off
	s_waitcnt lgkmcnt(8)
	s_barrier
	s_waitcnt lgkmcnt(0)
	s_setprio 1
	s_waitcnt lgkmcnt(0)
	v_mfma_f32_16x16x32_bf16 v[124:127], v[140:143], v[176:179], v[124:127]
	v_mfma_f32_16x16x32_bf16 v[120:123], v[154:157], v[176:179], v[120:123]
	v_mfma_f32_16x16x32_bf16 v[108:111], v[140:143], v[184:187], v[108:111]
	v_mfma_f32_16x16x32_bf16 v[104:107], v[154:157], v[184:187], v[104:107]
	v_mfma_f32_16x16x32_bf16 v[92:95], v[140:143], v[192:195], v[92:95]
	v_mfma_f32_16x16x32_bf16 v[88:91], v[154:157], v[192:195], v[88:91]
	v_mfma_f32_16x16x32_bf16 v[76:79], v[140:143], v[200:203], v[76:79]
	v_mfma_f32_16x16x32_bf16 v[72:75], v[154:157], v[200:203], v[72:75]
	v_mfma_f32_16x16x32_bf16 v[124:127], v[150:153], v[180:183], v[124:127]
	v_mfma_f32_16x16x32_bf16 v[120:123], v[158:161], v[180:183], v[120:123]
	v_mfma_f32_16x16x32_bf16 v[108:111], v[150:153], v[188:191], v[108:111]
	v_mfma_f32_16x16x32_bf16 v[104:107], v[158:161], v[188:191], v[104:107]
	v_mfma_f32_16x16x32_bf16 v[92:95], v[150:153], v[196:199], v[92:95]
	v_mfma_f32_16x16x32_bf16 v[88:91], v[158:161], v[196:199], v[88:91]
	v_mfma_f32_16x16x32_bf16 v[76:79], v[150:153], v[204:207], v[76:79]
	v_mfma_f32_16x16x32_bf16 v[72:75], v[158:161], v[204:207], v[72:75]
	s_setprio 0
	s_barrier
	s_add_i32 s24, 0, 0x1c000
	s_add_i32 s25, s46, s28
	v_add_u32_e32 v149, s24, v144
	v_lshl_add_u64 v[216:217], v[216:217], 0, s[10:11]
	s_mov_b32 m0, s25
	ds_read_b128 v[208:211], v149
	v_xor_b32_e32 v243, 64, v149
	ds_read_b128 v[212:215], v243
	ds_read_b128 v[236:239], v149 offset:2048
	ds_read_b128 v[240:243], v243 offset:2048
	global_load_lds_dwordx4 v[216:217], off
	v_lshl_add_u64 v[216:217], v[234:235], 0, s[10:11]
	s_add_i32 m0, s25, 0x2000
	s_nop 0
	global_load_lds_dwordx4 v[216:217], off
	s_barrier
	s_waitcnt lgkmcnt(0)
	s_setprio 1
	s_waitcnt lgkmcnt(0)
	v_mfma_f32_16x16x32_bf16 v[116:119], v[208:211], v[176:179], v[116:119]
	v_mfma_f32_16x16x32_bf16 v[112:115], v[236:239], v[176:179], v[112:115]
	v_mfma_f32_16x16x32_bf16 v[100:103], v[208:211], v[184:187], v[100:103]
	v_mfma_f32_16x16x32_bf16 v[96:99], v[236:239], v[184:187], v[96:99]
	v_mfma_f32_16x16x32_bf16 v[84:87], v[208:211], v[192:195], v[84:87]
	v_mfma_f32_16x16x32_bf16 v[80:83], v[236:239], v[192:195], v[80:83]
	v_mfma_f32_16x16x32_bf16 v[68:71], v[208:211], v[200:203], v[68:71]
	v_mfma_f32_16x16x32_bf16 v[64:67], v[236:239], v[200:203], v[64:67]
	v_mfma_f32_16x16x32_bf16 v[116:119], v[212:215], v[180:183], v[116:119]
	v_mfma_f32_16x16x32_bf16 v[112:115], v[240:243], v[180:183], v[112:115]
	v_mfma_f32_16x16x32_bf16 v[100:103], v[212:215], v[188:191], v[100:103]
	v_mfma_f32_16x16x32_bf16 v[96:99], v[240:243], v[188:191], v[96:99]
	v_mfma_f32_16x16x32_bf16 v[84:87], v[212:215], v[196:199], v[84:87]
	v_mfma_f32_16x16x32_bf16 v[80:83], v[240:243], v[196:199], v[80:83]
	v_mfma_f32_16x16x32_bf16 v[68:71], v[212:215], v[204:207], v[68:71]
	v_mfma_f32_16x16x32_bf16 v[64:67], v[240:243], v[204:207], v[64:67]
	s_setprio 0
	s_mov_b32 m0, s37
	v_lshl_add_u64 v[216:217], v[244:245], 0, s[10:11]
	s_barrier
	ds_read_b128 v[176:179], v146 offset:49152
	v_xor_b32_e32 v207, 64, v146
	ds_read_b128 v[180:183], v207 offset:49152
	ds_read_b128 v[184:187], v146 offset:51200
	ds_read_b128 v[188:191], v207 offset:51200
	ds_read_b128 v[192:195], v146 offset:53248
	ds_read_b128 v[196:199], v207 offset:53248
	ds_read_b128 v[200:203], v146 offset:55296
	ds_read_b128 v[204:207], v207 offset:55296
	global_load_lds_dwordx4 v[216:217], off
	v_lshl_add_u64 v[216:217], v[246:247], 0, s[10:11]
	s_mov_b32 m0, s38
	s_nop 0
	global_load_lds_dwordx4 v[216:217], off
	s_barrier
	s_waitcnt lgkmcnt(0)
	s_setprio 1
	s_waitcnt lgkmcnt(0)
	v_mfma_f32_16x16x32_bf16 v[60:63], v[140:143], v[176:179], v[60:63]
	v_mfma_f32_16x16x32_bf16 v[56:59], v[154:157], v[176:179], v[56:59]
	v_mfma_f32_16x16x32_bf16 v[44:47], v[140:143], v[184:187], v[44:47]
	v_mfma_f32_16x16x32_bf16 v[40:43], v[154:157], v[184:187], v[40:43]
	v_mfma_f32_16x16x32_bf16 v[28:31], v[140:143], v[192:195], v[28:31]
	v_mfma_f32_16x16x32_bf16 v[24:27], v[154:157], v[192:195], v[24:27]
	v_mfma_f32_16x16x32_bf16 v[12:15], v[140:143], v[200:203], v[12:15]
	v_mfma_f32_16x16x32_bf16 v[8:11], v[154:157], v[200:203], v[8:11]
	v_mfma_f32_16x16x32_bf16 v[60:63], v[150:153], v[180:183], v[60:63]
	v_mfma_f32_16x16x32_bf16 v[56:59], v[158:161], v[180:183], v[56:59]
	v_mfma_f32_16x16x32_bf16 v[44:47], v[150:153], v[188:191], v[44:47]
	v_mfma_f32_16x16x32_bf16 v[40:43], v[158:161], v[188:191], v[40:43]
	v_mfma_f32_16x16x32_bf16 v[28:31], v[150:153], v[196:199], v[28:31]
	v_mfma_f32_16x16x32_bf16 v[24:27], v[158:161], v[196:199], v[24:27]
	v_mfma_f32_16x16x32_bf16 v[12:15], v[150:153], v[204:207], v[12:15]
	v_mfma_f32_16x16x32_bf16 v[8:11], v[158:161], v[204:207], v[8:11]
	s_setprio 0
	s_barrier
	s_add_u32 s22, s22, 0x80080
	s_addc_u32 s23, s23, 0
	s_add_i32 s24, s24, s28
	v_lshl_add_u64 v[140:141], s[22:23], 0, v[164:165]
	s_mov_b32 m0, s24
	s_nop 0
	global_load_lds_dwordx4 v[140:141], off
	v_lshl_add_u64 v[140:141], s[22:23], 0, v[166:167]
	s_add_i32 m0, s24, 0x2000
	s_nop 0
	global_load_lds_dwordx4 v[140:141], off
	s_waitcnt vmcnt(6)
	s_barrier
	s_setprio 1
	v_mfma_f32_16x16x32_bf16 v[52:55], v[208:211], v[176:179], v[52:55]
	v_mfma_f32_16x16x32_bf16 v[48:51], v[236:239], v[176:179], v[48:51]
	v_mfma_f32_16x16x32_bf16 v[36:39], v[208:211], v[184:187], v[36:39]
	v_mfma_f32_16x16x32_bf16 v[32:35], v[236:239], v[184:187], v[32:35]
	v_mfma_f32_16x16x32_bf16 v[20:23], v[208:211], v[192:195], v[20:23]
	v_mfma_f32_16x16x32_bf16 v[16:19], v[236:239], v[192:195], v[16:19]
	v_mfma_f32_16x16x32_bf16 v[4:7], v[208:211], v[200:203], v[4:7]
	v_mfma_f32_16x16x32_bf16 v[0:3], v[236:239], v[200:203], v[0:3]
	v_mfma_f32_16x16x32_bf16 v[52:55], v[212:215], v[180:183], v[52:55]
	v_mfma_f32_16x16x32_bf16 v[48:51], v[240:243], v[180:183], v[48:51]
	v_mfma_f32_16x16x32_bf16 v[36:39], v[212:215], v[188:191], v[36:39]
	v_mfma_f32_16x16x32_bf16 v[32:35], v[240:243], v[188:191], v[32:35]
	v_mfma_f32_16x16x32_bf16 v[20:23], v[212:215], v[196:199], v[20:23]
	v_mfma_f32_16x16x32_bf16 v[16:19], v[240:243], v[196:199], v[16:19]
	v_mfma_f32_16x16x32_bf16 v[4:7], v[212:215], v[204:207], v[4:7]
	v_mfma_f32_16x16x32_bf16 v[0:3], v[240:243], v[204:207], v[0:3]
	s_setprio 0
	s_add_i32 s45, s45, 2
	s_add_u32 s20, s20, 0x100
	s_addc_u32 s21, s21, 0
	s_add_u32 s43, s43, 0x100
	s_addc_u32 s44, s44, 0
	s_cmp_gt_u32 s45, 29
	s_barrier
	s_cbranch_scc0 .LBB0_760
	v_lshl_add_u32 v217, s8, 8, v163
	v_add_u32_e32 v217, s35, v217
	v_lshlrev_b32_e32 v208, 2, v217
	v_lshl_add_u32 v214, v225, 3, s36
	v_lshl_add_u32 v214, s0, 8, v214
	v_lshl_add_u32 v209, v217, 11, v214
	v_lshlrev_b32_e32 v209, 1, v209
	v_lshlrev_b32_e32 v210, 1, v209
	v_lshl_add_u32 v217, v225, 4, v163
	v_xor_b32_e32 v215, 16, v217
	v_lshlrev_b32_e32 v215, 2, v215
	v_xor_b32_e32 v216, 32, v217
	v_lshlrev_b32_e32 v216, 2, v216
	v_add_u32_e32 v211, 0x0, v209
	global_load_dwordx4 v[176:179], v211, s[80:81]
	global_load_dwordx4 v[180:183], v211, s[80:81] offset:256
	v_add_u32_e32 v211, 0x10000, v209
	global_load_dwordx4 v[192:195], v211, s[80:81]
	global_load_dwordx4 v[196:199], v211, s[80:81] offset:256
	s_waitcnt vmcnt(2)
	v_lshlrev_b32_e32 v184, 16, v176
	v_and_b32_e32 v185, 0xffff0000, v176
	v_lshlrev_b32_e32 v186, 16, v177
	v_and_b32_e32 v187, 0xffff0000, v177
	v_lshlrev_b32_e32 v188, 16, v178
	v_and_b32_e32 v189, 0xffff0000, v178
	v_lshlrev_b32_e32 v190, 16, v179
	v_and_b32_e32 v191, 0xffff0000, v179
	v_pk_add_f32 v[124:125], v[124:125], v[184:185]
	v_pk_add_f32 v[126:127], v[126:127], v[186:187]
	v_pk_add_f32 v[120:121], v[120:121], v[188:189]
	v_pk_add_f32 v[122:123], v[122:123], v[190:191]
	v_mul_f32_e32 v213, v124, v124
	v_fmac_f32_e32 v213, v125, v125
	v_fmac_f32_e32 v213, v126, v126
	v_fmac_f32_e32 v213, v127, v127
	v_fmac_f32_e32 v213, v120, v120
	v_fmac_f32_e32 v213, v121, v121
	v_fmac_f32_e32 v213, v122, v122
	v_fmac_f32_e32 v213, v123, v123
	v_cvt_pk_bf16_f32 v176, v124, v125
	v_cvt_pk_bf16_f32 v177, v126, v127
	v_cvt_pk_bf16_f32 v178, v120, v121
	v_cvt_pk_bf16_f32 v179, v122, v123
	v_add_u32_e32 v217, 0x0, v209
	global_store_dwordx4 v217, v[176:179], s[80:81]
	v_lshlrev_b32_e32 v184, 16, v180
	v_and_b32_e32 v185, 0xffff0000, v180
	v_lshlrev_b32_e32 v186, 16, v181
	v_and_b32_e32 v187, 0xffff0000, v181
	v_lshlrev_b32_e32 v188, 16, v182
	v_and_b32_e32 v189, 0xffff0000, v182
	v_lshlrev_b32_e32 v190, 16, v183
	v_and_b32_e32 v191, 0xffff0000, v183
	v_pk_add_f32 v[116:117], v[116:117], v[184:185]
	v_pk_add_f32 v[118:119], v[118:119], v[186:187]
	v_pk_add_f32 v[112:113], v[112:113], v[188:189]
	v_pk_add_f32 v[114:115], v[114:115], v[190:191]
	v_fmac_f32_e32 v213, v116, v116
	v_fmac_f32_e32 v213, v117, v117
	v_fmac_f32_e32 v213, v118, v118
	v_fmac_f32_e32 v213, v119, v119
	v_fmac_f32_e32 v213, v112, v112
	v_fmac_f32_e32 v213, v113, v113
	v_fmac_f32_e32 v213, v114, v114
	v_fmac_f32_e32 v213, v115, v115
	v_cvt_pk_bf16_f32 v180, v116, v117
	v_cvt_pk_bf16_f32 v181, v118, v119
	v_cvt_pk_bf16_f32 v182, v112, v113
	v_cvt_pk_bf16_f32 v183, v114, v115
	global_store_dwordx4 v217, v[180:183], s[80:81] offset:256
	ds_bpermute_b32 v214, v215, v213
	s_waitcnt lgkmcnt(0)
	v_add_f32_e32 v213, v213, v214
	ds_bpermute_b32 v214, v216, v213
	s_waitcnt lgkmcnt(0)
	v_add_f32_e32 v213, v213, v214
	s_mov_b64 exec, 0xffff
	global_atomic_add_f32 v208, v213, s[4:5]
	s_mov_b64 exec, -1
	v_add_u32_e32 v211, 0x20000, v209
	global_load_dwordx4 v[176:179], v211, s[80:81]
	global_load_dwordx4 v[180:183], v211, s[80:81] offset:256
	s_waitcnt vmcnt(5)
	v_lshlrev_b32_e32 v200, 16, v192
	v_and_b32_e32 v201, 0xffff0000, v192
	v_lshlrev_b32_e32 v202, 16, v193
	v_and_b32_e32 v203, 0xffff0000, v193
	v_lshlrev_b32_e32 v204, 16, v194
	v_and_b32_e32 v205, 0xffff0000, v194
	v_lshlrev_b32_e32 v206, 16, v195
	v_and_b32_e32 v207, 0xffff0000, v195
	v_pk_add_f32 v[108:109], v[108:109], v[200:201]
	v_pk_add_f32 v[110:111], v[110:111], v[202:203]
	v_pk_add_f32 v[104:105], v[104:105], v[204:205]
	v_pk_add_f32 v[106:107], v[106:107], v[206:207]
	v_mul_f32_e32 v213, v108, v108
	v_fmac_f32_e32 v213, v109, v109
	v_fmac_f32_e32 v213, v110, v110
	v_fmac_f32_e32 v213, v111, v111
	v_fmac_f32_e32 v213, v104, v104
	v_fmac_f32_e32 v213, v105, v105
	v_fmac_f32_e32 v213, v106, v106
	v_fmac_f32_e32 v213, v107, v107
	v_cvt_pk_bf16_f32 v192, v108, v109
	v_cvt_pk_bf16_f32 v193, v110, v111
	v_cvt_pk_bf16_f32 v194, v104, v105
	v_cvt_pk_bf16_f32 v195, v106, v107
	v_add_u32_e32 v217, 0x10000, v209
	global_store_dwordx4 v217, v[192:195], s[80:81]
	v_lshlrev_b32_e32 v200, 16, v196
	v_and_b32_e32 v201, 0xffff0000, v196
	v_lshlrev_b32_e32 v202, 16, v197
	v_and_b32_e32 v203, 0xffff0000, v197
	v_lshlrev_b32_e32 v204, 16, v198
	v_and_b32_e32 v205, 0xffff0000, v198
	v_lshlrev_b32_e32 v206, 16, v199
	v_and_b32_e32 v207, 0xffff0000, v199
	v_pk_add_f32 v[100:101], v[100:101], v[200:201]
	v_pk_add_f32 v[102:103], v[102:103], v[202:203]
	v_pk_add_f32 v[96:97], v[96:97], v[204:205]
	v_pk_add_f32 v[98:99], v[98:99], v[206:207]
	v_fmac_f32_e32 v213, v100, v100
	v_fmac_f32_e32 v213, v101, v101
	v_fmac_f32_e32 v213, v102, v102
	v_fmac_f32_e32 v213, v103, v103
	v_fmac_f32_e32 v213, v96, v96
	v_fmac_f32_e32 v213, v97, v97
	v_fmac_f32_e32 v213, v98, v98
	v_fmac_f32_e32 v213, v99, v99
	v_cvt_pk_bf16_f32 v196, v100, v101
	v_cvt_pk_bf16_f32 v197, v102, v103
	v_cvt_pk_bf16_f32 v198, v96, v97
	v_cvt_pk_bf16_f32 v199, v98, v99
	global_store_dwordx4 v217, v[196:199], s[80:81] offset:256
	ds_bpermute_b32 v214, v215, v213
	s_waitcnt lgkmcnt(0)
	v_add_f32_e32 v213, v213, v214
	ds_bpermute_b32 v214, v216, v213
	s_waitcnt lgkmcnt(0)
	v_add_f32_e32 v213, v213, v214
	s_mov_b64 exec, 0xffff
	global_atomic_add_f32 v208, v213, s[4:5] offset:64
	s_mov_b64 exec, -1
	v_add_u32_e32 v211, 0x30000, v209
	global_load_dwordx4 v[192:195], v211, s[80:81]
	global_load_dwordx4 v[196:199], v211, s[80:81] offset:256
	s_waitcnt vmcnt(5)
	v_lshlrev_b32_e32 v184, 16, v176
	v_and_b32_e32 v185, 0xffff0000, v176
	v_lshlrev_b32_e32 v186, 16, v177
	v_and_b32_e32 v187, 0xffff0000, v177
	v_lshlrev_b32_e32 v188, 16, v178
	v_and_b32_e32 v189, 0xffff0000, v178
	v_lshlrev_b32_e32 v190, 16, v179
	v_and_b32_e32 v191, 0xffff0000, v179
	v_pk_add_f32 v[92:93], v[92:93], v[184:185]
	v_pk_add_f32 v[94:95], v[94:95], v[186:187]
	v_pk_add_f32 v[88:89], v[88:89], v[188:189]
	v_pk_add_f32 v[90:91], v[90:91], v[190:191]
	v_mul_f32_e32 v213, v92, v92
	v_fmac_f32_e32 v213, v93, v93
	v_fmac_f32_e32 v213, v94, v94
	v_fmac_f32_e32 v213, v95, v95
	v_fmac_f32_e32 v213, v88, v88
	v_fmac_f32_e32 v213, v89, v89
	v_fmac_f32_e32 v213, v90, v90
	v_fmac_f32_e32 v213, v91, v91
	v_cvt_pk_bf16_f32 v176, v92, v93
	v_cvt_pk_bf16_f32 v177, v94, v95
	v_cvt_pk_bf16_f32 v178, v88, v89
	v_cvt_pk_bf16_f32 v179, v90, v91
	v_add_u32_e32 v217, 0x20000, v209
	global_store_dwordx4 v217, v[176:179], s[80:81]
	v_lshlrev_b32_e32 v184, 16, v180
	v_and_b32_e32 v185, 0xffff0000, v180
	v_lshlrev_b32_e32 v186, 16, v181
	v_and_b32_e32 v187, 0xffff0000, v181
	v_lshlrev_b32_e32 v188, 16, v182
	v_and_b32_e32 v189, 0xffff0000, v182
	v_lshlrev_b32_e32 v190, 16, v183
	v_and_b32_e32 v191, 0xffff0000, v183
	v_pk_add_f32 v[84:85], v[84:85], v[184:185]
	v_pk_add_f32 v[86:87], v[86:87], v[186:187]
	v_pk_add_f32 v[80:81], v[80:81], v[188:189]
	v_pk_add_f32 v[82:83], v[82:83], v[190:191]
	v_fmac_f32_e32 v213, v84, v84
	v_fmac_f32_e32 v213, v85, v85
	v_fmac_f32_e32 v213, v86, v86
	v_fmac_f32_e32 v213, v87, v87
	v_fmac_f32_e32 v213, v80, v80
	v_fmac_f32_e32 v213, v81, v81
	v_fmac_f32_e32 v213, v82, v82
	v_fmac_f32_e32 v213, v83, v83
	v_cvt_pk_bf16_f32 v180, v84, v85
	v_cvt_pk_bf16_f32 v181, v86, v87
	v_cvt_pk_bf16_f32 v182, v80, v81
	v_cvt_pk_bf16_f32 v183, v82, v83
	global_store_dwordx4 v217, v[180:183], s[80:81] offset:256
	ds_bpermute_b32 v214, v215, v213
	s_waitcnt lgkmcnt(0)
	v_add_f32_e32 v213, v213, v214
	ds_bpermute_b32 v214, v216, v213
	s_waitcnt lgkmcnt(0)
	v_add_f32_e32 v213, v213, v214
	s_mov_b64 exec, 0xffff
	global_atomic_add_f32 v208, v213, s[4:5] offset:128
	s_mov_b64 exec, -1
	v_add_u32_e32 v211, 0x80000, v209
	global_load_dwordx4 v[176:179], v211, s[80:81]
	global_load_dwordx4 v[180:183], v211, s[80:81] offset:256
	s_waitcnt vmcnt(5)
	v_lshlrev_b32_e32 v200, 16, v192
	v_and_b32_e32 v201, 0xffff0000, v192
	v_lshlrev_b32_e32 v202, 16, v193
	v_and_b32_e32 v203, 0xffff0000, v193
	v_lshlrev_b32_e32 v204, 16, v194
	v_and_b32_e32 v205, 0xffff0000, v194
	v_lshlrev_b32_e32 v206, 16, v195
	v_and_b32_e32 v207, 0xffff0000, v195
	v_pk_add_f32 v[76:77], v[76:77], v[200:201]
	v_pk_add_f32 v[78:79], v[78:79], v[202:203]
	v_pk_add_f32 v[72:73], v[72:73], v[204:205]
	v_pk_add_f32 v[74:75], v[74:75], v[206:207]
	v_mul_f32_e32 v213, v76, v76
	v_fmac_f32_e32 v213, v77, v77
	v_fmac_f32_e32 v213, v78, v78
	v_fmac_f32_e32 v213, v79, v79
	v_fmac_f32_e32 v213, v72, v72
	v_fmac_f32_e32 v213, v73, v73
	v_fmac_f32_e32 v213, v74, v74
	v_fmac_f32_e32 v213, v75, v75
	v_cvt_pk_bf16_f32 v192, v76, v77
	v_cvt_pk_bf16_f32 v193, v78, v79
	v_cvt_pk_bf16_f32 v194, v72, v73
	v_cvt_pk_bf16_f32 v195, v74, v75
	v_add_u32_e32 v217, 0x30000, v209
	global_store_dwordx4 v217, v[192:195], s[80:81]
	v_lshlrev_b32_e32 v200, 16, v196
	v_and_b32_e32 v201, 0xffff0000, v196
	v_lshlrev_b32_e32 v202, 16, v197
	v_and_b32_e32 v203, 0xffff0000, v197
	v_lshlrev_b32_e32 v204, 16, v198
	v_and_b32_e32 v205, 0xffff0000, v198
	v_lshlrev_b32_e32 v206, 16, v199
	v_and_b32_e32 v207, 0xffff0000, v199
	v_pk_add_f32 v[68:69], v[68:69], v[200:201]
	v_pk_add_f32 v[70:71], v[70:71], v[202:203]
	v_pk_add_f32 v[64:65], v[64:65], v[204:205]
	v_pk_add_f32 v[66:67], v[66:67], v[206:207]
	v_fmac_f32_e32 v213, v68, v68
	v_fmac_f32_e32 v213, v69, v69
	v_fmac_f32_e32 v213, v70, v70
	v_fmac_f32_e32 v213, v71, v71
	v_fmac_f32_e32 v213, v64, v64
	v_fmac_f32_e32 v213, v65, v65
	v_fmac_f32_e32 v213, v66, v66
	v_fmac_f32_e32 v213, v67, v67
	v_cvt_pk_bf16_f32 v196, v68, v69
	v_cvt_pk_bf16_f32 v197, v70, v71
	v_cvt_pk_bf16_f32 v198, v64, v65
	v_cvt_pk_bf16_f32 v199, v66, v67
	global_store_dwordx4 v217, v[196:199], s[80:81] offset:256
	ds_bpermute_b32 v214, v215, v213
	s_waitcnt lgkmcnt(0)
	v_add_f32_e32 v213, v213, v214
	ds_bpermute_b32 v214, v216, v213
	s_waitcnt lgkmcnt(0)
	v_add_f32_e32 v213, v213, v214
	s_mov_b64 exec, 0xffff
	global_atomic_add_f32 v208, v213, s[4:5] offset:192
	s_mov_b64 exec, -1
	v_add_u32_e32 v211, 0x90000, v209
	global_load_dwordx4 v[192:195], v211, s[80:81]
	global_load_dwordx4 v[196:199], v211, s[80:81] offset:256
	s_waitcnt vmcnt(5)
	v_lshlrev_b32_e32 v184, 16, v176
	v_and_b32_e32 v185, 0xffff0000, v176
	v_lshlrev_b32_e32 v186, 16, v177
	v_and_b32_e32 v187, 0xffff0000, v177
	v_lshlrev_b32_e32 v188, 16, v178
	v_and_b32_e32 v189, 0xffff0000, v178
	v_lshlrev_b32_e32 v190, 16, v179
	v_and_b32_e32 v191, 0xffff0000, v179
	v_pk_add_f32 v[60:61], v[60:61], v[184:185]
	v_pk_add_f32 v[62:63], v[62:63], v[186:187]
	v_pk_add_f32 v[56:57], v[56:57], v[188:189]
	v_pk_add_f32 v[58:59], v[58:59], v[190:191]
	v_mul_f32_e32 v213, v60, v60
	v_fmac_f32_e32 v213, v61, v61
	v_fmac_f32_e32 v213, v62, v62
	v_fmac_f32_e32 v213, v63, v63
	v_fmac_f32_e32 v213, v56, v56
	v_fmac_f32_e32 v213, v57, v57
	v_fmac_f32_e32 v213, v58, v58
	v_fmac_f32_e32 v213, v59, v59
	v_cvt_pk_bf16_f32 v176, v60, v61
	v_cvt_pk_bf16_f32 v177, v62, v63
	v_cvt_pk_bf16_f32 v178, v56, v57
	v_cvt_pk_bf16_f32 v179, v58, v59
	v_add_u32_e32 v217, 0x80000, v209
	global_store_dwordx4 v217, v[176:179], s[80:81]
	v_lshlrev_b32_e32 v184, 16, v180
	v_and_b32_e32 v185, 0xffff0000, v180
	v_lshlrev_b32_e32 v186, 16, v181
	v_and_b32_e32 v187, 0xffff0000, v181
	v_lshlrev_b32_e32 v188, 16, v182
	v_and_b32_e32 v189, 0xffff0000, v182
	v_lshlrev_b32_e32 v190, 16, v183
	v_and_b32_e32 v191, 0xffff0000, v183
	v_pk_add_f32 v[52:53], v[52:53], v[184:185]
	v_pk_add_f32 v[54:55], v[54:55], v[186:187]
	v_pk_add_f32 v[48:49], v[48:49], v[188:189]
	v_pk_add_f32 v[50:51], v[50:51], v[190:191]
	v_fmac_f32_e32 v213, v52, v52
	v_fmac_f32_e32 v213, v53, v53
	v_fmac_f32_e32 v213, v54, v54
	v_fmac_f32_e32 v213, v55, v55
	v_fmac_f32_e32 v213, v48, v48
	v_fmac_f32_e32 v213, v49, v49
	v_fmac_f32_e32 v213, v50, v50
	v_fmac_f32_e32 v213, v51, v51
	v_cvt_pk_bf16_f32 v180, v52, v53
	v_cvt_pk_bf16_f32 v181, v54, v55
	v_cvt_pk_bf16_f32 v182, v48, v49
	v_cvt_pk_bf16_f32 v183, v50, v51
	global_store_dwordx4 v217, v[180:183], s[80:81] offset:256
	ds_bpermute_b32 v214, v215, v213
	s_waitcnt lgkmcnt(0)
	v_add_f32_e32 v213, v213, v214
	ds_bpermute_b32 v214, v216, v213
	s_waitcnt lgkmcnt(0)
	v_add_f32_e32 v213, v213, v214
	s_mov_b64 exec, 0xffff
	global_atomic_add_f32 v208, v213, s[4:5] offset:512
	s_mov_b64 exec, -1
	v_add_u32_e32 v211, 0xa0000, v209
	global_load_dwordx4 v[176:179], v211, s[80:81]
	global_load_dwordx4 v[180:183], v211, s[80:81] offset:256
	s_waitcnt vmcnt(5)
	v_lshlrev_b32_e32 v200, 16, v192
	v_and_b32_e32 v201, 0xffff0000, v192
	v_lshlrev_b32_e32 v202, 16, v193
	v_and_b32_e32 v203, 0xffff0000, v193
	v_lshlrev_b32_e32 v204, 16, v194
	v_and_b32_e32 v205, 0xffff0000, v194
	v_lshlrev_b32_e32 v206, 16, v195
	v_and_b32_e32 v207, 0xffff0000, v195
	v_pk_add_f32 v[44:45], v[44:45], v[200:201]
	v_pk_add_f32 v[46:47], v[46:47], v[202:203]
	v_pk_add_f32 v[40:41], v[40:41], v[204:205]
	v_pk_add_f32 v[42:43], v[42:43], v[206:207]
	v_mul_f32_e32 v213, v44, v44
	v_fmac_f32_e32 v213, v45, v45
	v_fmac_f32_e32 v213, v46, v46
	v_fmac_f32_e32 v213, v47, v47
	v_fmac_f32_e32 v213, v40, v40
	v_fmac_f32_e32 v213, v41, v41
	v_fmac_f32_e32 v213, v42, v42
	v_fmac_f32_e32 v213, v43, v43
	v_cvt_pk_bf16_f32 v192, v44, v45
	v_cvt_pk_bf16_f32 v193, v46, v47
	v_cvt_pk_bf16_f32 v194, v40, v41
	v_cvt_pk_bf16_f32 v195, v42, v43
	v_add_u32_e32 v217, 0x90000, v209
	global_store_dwordx4 v217, v[192:195], s[80:81]
	v_lshlrev_b32_e32 v200, 16, v196
	v_and_b32_e32 v201, 0xffff0000, v196
	v_lshlrev_b32_e32 v202, 16, v197
	v_and_b32_e32 v203, 0xffff0000, v197
	v_lshlrev_b32_e32 v204, 16, v198
	v_and_b32_e32 v205, 0xffff0000, v198
	v_lshlrev_b32_e32 v206, 16, v199
	v_and_b32_e32 v207, 0xffff0000, v199
	v_pk_add_f32 v[36:37], v[36:37], v[200:201]
	v_pk_add_f32 v[38:39], v[38:39], v[202:203]
	v_pk_add_f32 v[32:33], v[32:33], v[204:205]
	v_pk_add_f32 v[34:35], v[34:35], v[206:207]
	v_fmac_f32_e32 v213, v36, v36
	v_fmac_f32_e32 v213, v37, v37
	v_fmac_f32_e32 v213, v38, v38
	v_fmac_f32_e32 v213, v39, v39
	v_fmac_f32_e32 v213, v32, v32
	v_fmac_f32_e32 v213, v33, v33
	v_fmac_f32_e32 v213, v34, v34
	v_fmac_f32_e32 v213, v35, v35
	v_cvt_pk_bf16_f32 v196, v36, v37
	v_cvt_pk_bf16_f32 v197, v38, v39
	v_cvt_pk_bf16_f32 v198, v32, v33
	v_cvt_pk_bf16_f32 v199, v34, v35
	global_store_dwordx4 v217, v[196:199], s[80:81] offset:256
	ds_bpermute_b32 v214, v215, v213
	s_waitcnt lgkmcnt(0)
	v_add_f32_e32 v213, v213, v214
	ds_bpermute_b32 v214, v216, v213
	s_waitcnt lgkmcnt(0)
	v_add_f32_e32 v213, v213, v214
	s_mov_b64 exec, 0xffff
	global_atomic_add_f32 v208, v213, s[4:5] offset:576
	s_mov_b64 exec, -1
	v_add_u32_e32 v211, 0xb0000, v209
	global_load_dwordx4 v[192:195], v211, s[80:81]
	global_load_dwordx4 v[196:199], v211, s[80:81] offset:256
	s_waitcnt vmcnt(5)
	v_lshlrev_b32_e32 v184, 16, v176
	v_and_b32_e32 v185, 0xffff0000, v176
	v_lshlrev_b32_e32 v186, 16, v177
	v_and_b32_e32 v187, 0xffff0000, v177
	v_lshlrev_b32_e32 v188, 16, v178
	v_and_b32_e32 v189, 0xffff0000, v178
	v_lshlrev_b32_e32 v190, 16, v179
	v_and_b32_e32 v191, 0xffff0000, v179
	v_pk_add_f32 v[28:29], v[28:29], v[184:185]
	v_pk_add_f32 v[30:31], v[30:31], v[186:187]
	v_pk_add_f32 v[24:25], v[24:25], v[188:189]
	v_pk_add_f32 v[26:27], v[26:27], v[190:191]
	v_mul_f32_e32 v213, v28, v28
	v_fmac_f32_e32 v213, v29, v29
	v_fmac_f32_e32 v213, v30, v30
	v_fmac_f32_e32 v213, v31, v31
	v_fmac_f32_e32 v213, v24, v24
	v_fmac_f32_e32 v213, v25, v25
	v_fmac_f32_e32 v213, v26, v26
	v_fmac_f32_e32 v213, v27, v27
	v_cvt_pk_bf16_f32 v176, v28, v29
	v_cvt_pk_bf16_f32 v177, v30, v31
	v_cvt_pk_bf16_f32 v178, v24, v25
	v_cvt_pk_bf16_f32 v179, v26, v27
	v_add_u32_e32 v217, 0xa0000, v209
	global_store_dwordx4 v217, v[176:179], s[80:81]
	v_lshlrev_b32_e32 v184, 16, v180
	v_and_b32_e32 v185, 0xffff0000, v180
	v_lshlrev_b32_e32 v186, 16, v181
	v_and_b32_e32 v187, 0xffff0000, v181
	v_lshlrev_b32_e32 v188, 16, v182
	v_and_b32_e32 v189, 0xffff0000, v182
	v_lshlrev_b32_e32 v190, 16, v183
	v_and_b32_e32 v191, 0xffff0000, v183
	v_pk_add_f32 v[20:21], v[20:21], v[184:185]
	v_pk_add_f32 v[22:23], v[22:23], v[186:187]
	v_pk_add_f32 v[16:17], v[16:17], v[188:189]
	v_pk_add_f32 v[18:19], v[18:19], v[190:191]
	v_fmac_f32_e32 v213, v20, v20
	v_fmac_f32_e32 v213, v21, v21
	v_fmac_f32_e32 v213, v22, v22
	v_fmac_f32_e32 v213, v23, v23
	v_fmac_f32_e32 v213, v16, v16
	v_fmac_f32_e32 v213, v17, v17
	v_fmac_f32_e32 v213, v18, v18
	v_fmac_f32_e32 v213, v19, v19
	v_cvt_pk_bf16_f32 v180, v20, v21
	v_cvt_pk_bf16_f32 v181, v22, v23
	v_cvt_pk_bf16_f32 v182, v16, v17
	v_cvt_pk_bf16_f32 v183, v18, v19
	global_store_dwordx4 v217, v[180:183], s[80:81] offset:256
	ds_bpermute_b32 v214, v215, v213
	s_waitcnt lgkmcnt(0)
	v_add_f32_e32 v213, v213, v214
	ds_bpermute_b32 v214, v216, v213
	s_waitcnt lgkmcnt(0)
	v_add_f32_e32 v213, v213, v214
	s_mov_b64 exec, 0xffff
	global_atomic_add_f32 v208, v213, s[4:5] offset:640
	s_mov_b64 exec, -1
	s_waitcnt vmcnt(3)
	v_lshlrev_b32_e32 v200, 16, v192
	v_and_b32_e32 v201, 0xffff0000, v192
	v_lshlrev_b32_e32 v202, 16, v193
	v_and_b32_e32 v203, 0xffff0000, v193
	v_lshlrev_b32_e32 v204, 16, v194
	v_and_b32_e32 v205, 0xffff0000, v194
	v_lshlrev_b32_e32 v206, 16, v195
	v_and_b32_e32 v207, 0xffff0000, v195
	v_pk_add_f32 v[12:13], v[12:13], v[200:201]
	v_pk_add_f32 v[14:15], v[14:15], v[202:203]
	v_pk_add_f32 v[8:9], v[8:9], v[204:205]
	v_pk_add_f32 v[10:11], v[10:11], v[206:207]
	v_mul_f32_e32 v213, v12, v12
	v_fmac_f32_e32 v213, v13, v13
	v_fmac_f32_e32 v213, v14, v14
	v_fmac_f32_e32 v213, v15, v15
	v_fmac_f32_e32 v213, v8, v8
	v_fmac_f32_e32 v213, v9, v9
	v_fmac_f32_e32 v213, v10, v10
	v_fmac_f32_e32 v213, v11, v11
	v_cvt_pk_bf16_f32 v192, v12, v13
	v_cvt_pk_bf16_f32 v193, v14, v15
	v_cvt_pk_bf16_f32 v194, v8, v9
	v_cvt_pk_bf16_f32 v195, v10, v11
	v_add_u32_e32 v217, 0xb0000, v209
	global_store_dwordx4 v217, v[192:195], s[80:81]
	v_lshlrev_b32_e32 v200, 16, v196
	v_and_b32_e32 v201, 0xffff0000, v196
	v_lshlrev_b32_e32 v202, 16, v197
	v_and_b32_e32 v203, 0xffff0000, v197
	v_lshlrev_b32_e32 v204, 16, v198
	v_and_b32_e32 v205, 0xffff0000, v198
	v_lshlrev_b32_e32 v206, 16, v199
	v_and_b32_e32 v207, 0xffff0000, v199
	v_pk_add_f32 v[4:5], v[4:5], v[200:201]
	v_pk_add_f32 v[6:7], v[6:7], v[202:203]
	v_pk_add_f32 v[0:1], v[0:1], v[204:205]
	v_pk_add_f32 v[2:3], v[2:3], v[206:207]
	v_fmac_f32_e32 v213, v4, v4
	v_fmac_f32_e32 v213, v5, v5
	v_fmac_f32_e32 v213, v6, v6
	v_fmac_f32_e32 v213, v7, v7
	v_fmac_f32_e32 v213, v0, v0
	v_fmac_f32_e32 v213, v1, v1
	v_fmac_f32_e32 v213, v2, v2
	v_fmac_f32_e32 v213, v3, v3
	v_cvt_pk_bf16_f32 v196, v4, v5
	v_cvt_pk_bf16_f32 v197, v6, v7
	v_cvt_pk_bf16_f32 v198, v0, v1
	v_cvt_pk_bf16_f32 v199, v2, v3
	global_store_dwordx4 v217, v[196:199], s[80:81] offset:256
	ds_bpermute_b32 v214, v215, v213
	s_waitcnt lgkmcnt(0)
	v_add_f32_e32 v213, v213, v214
	ds_bpermute_b32 v214, v216, v213
	s_waitcnt lgkmcnt(0)
	v_add_f32_e32 v213, v213, v214
	s_mov_b64 exec, 0xffff
	global_atomic_add_f32 v208, v213, s[4:5] offset:704
	s_mov_b64 exec, -1
	s_branch .LBB0_752

.LBB0_985:
	ds_read_b128 v[136:139], v141
	v_xor_b32_e32 v157, 64, v141
	ds_read_b128 v[146:149], v157
	ds_read_b128 v[150:153], v141 offset:2048
	ds_read_b128 v[154:157], v157 offset:2048
	s_add_u32 s14, s0, 0xffea0080
	s_addc_u32 s15, s1, -1
	s_cmpk_eq_i32 s41, 0x54
	s_cselect_b32 s17, s5, s15
	s_cselect_b32 s16, s4, s14
	s_cselect_b32 s15, s7, s40
	s_cselect_b32 s14, s6, s39
	v_lshl_add_u64 v[200:201], s[0:1], 0, v[128:129]
	s_add_i32 m0, s21, 0xc000
	ds_read_b128 v[158:161], v142
	v_xor_b32_e32 v199, 64, v142
	ds_read_b128 v[164:167], v199
	ds_read_b128 v[176:179], v142 offset:2048
	ds_read_b128 v[180:183], v199 offset:2048
	ds_read_b128 v[184:187], v142 offset:4096
	ds_read_b128 v[188:191], v199 offset:4096
	ds_read_b128 v[192:195], v142 offset:6144
	ds_read_b128 v[196:199], v199 offset:6144
	global_load_lds_dwordx4 v[200:201], off
	v_lshl_add_u64 v[200:201], s[0:1], 0, v[130:131]
	s_add_i32 m0, s21, 0xe000
	s_nop 0
	global_load_lds_dwordx4 v[200:201], off
	s_waitcnt lgkmcnt(8)
	s_barrier
	s_waitcnt lgkmcnt(0)
	s_setprio 1
	s_waitcnt lgkmcnt(0)
	v_mfma_f32_16x16x32_bf16 v[124:127], v[136:139], v[158:161], v[124:127]
	v_mfma_f32_16x16x32_bf16 v[120:123], v[150:153], v[158:161], v[120:123]
	v_mfma_f32_16x16x32_bf16 v[108:111], v[136:139], v[176:179], v[108:111]
	v_mfma_f32_16x16x32_bf16 v[104:107], v[150:153], v[176:179], v[104:107]
	v_mfma_f32_16x16x32_bf16 v[92:95], v[136:139], v[184:187], v[92:95]
	v_mfma_f32_16x16x32_bf16 v[88:91], v[150:153], v[184:187], v[88:91]
	v_mfma_f32_16x16x32_bf16 v[76:79], v[136:139], v[192:195], v[76:79]
	v_mfma_f32_16x16x32_bf16 v[72:75], v[150:153], v[192:195], v[72:75]
	v_mfma_f32_16x16x32_bf16 v[124:127], v[146:149], v[164:167], v[124:127]
	v_mfma_f32_16x16x32_bf16 v[120:123], v[154:157], v[164:167], v[120:123]
	v_mfma_f32_16x16x32_bf16 v[108:111], v[146:149], v[180:183], v[108:111]
	v_mfma_f32_16x16x32_bf16 v[104:107], v[154:157], v[180:183], v[104:107]
	v_mfma_f32_16x16x32_bf16 v[92:95], v[146:149], v[188:191], v[92:95]
	v_mfma_f32_16x16x32_bf16 v[88:91], v[154:157], v[188:191], v[88:91]
	v_mfma_f32_16x16x32_bf16 v[76:79], v[146:149], v[196:199], v[76:79]
	v_mfma_f32_16x16x32_bf16 v[72:75], v[154:157], v[196:199], v[72:75]
	s_setprio 0
	s_barrier
	s_add_i32 s42, s33, s20
	v_lshl_add_u64 v[216:217], s[14:15], 0, v[170:171]
	s_mov_b32 m0, s42
	ds_read_b128 v[200:203], v143
	v_xor_b32_e32 v215, 64, v143
	ds_read_b128 v[204:207], v215
	ds_read_b128 v[208:211], v143 offset:2048
	ds_read_b128 v[212:215], v215 offset:2048
	global_load_lds_dwordx4 v[216:217], off
	v_lshl_add_u64 v[218:219], s[14:15], 0, v[174:175]
	s_add_i32 m0, s42, 0x2000
	s_nop 0
	global_load_lds_dwordx4 v[218:219], off
	s_barrier
	s_waitcnt lgkmcnt(0)
	s_setprio 1
	s_waitcnt lgkmcnt(0)
	v_mfma_f32_16x16x32_bf16 v[116:119], v[200:203], v[158:161], v[116:119]
	v_mfma_f32_16x16x32_bf16 v[112:115], v[208:211], v[158:161], v[112:115]
	v_mfma_f32_16x16x32_bf16 v[100:103], v[200:203], v[176:179], v[100:103]
	v_mfma_f32_16x16x32_bf16 v[96:99], v[208:211], v[176:179], v[96:99]
	v_mfma_f32_16x16x32_bf16 v[84:87], v[200:203], v[184:187], v[84:87]
	v_mfma_f32_16x16x32_bf16 v[80:83], v[208:211], v[184:187], v[80:83]
	v_mfma_f32_16x16x32_bf16 v[68:71], v[200:203], v[192:195], v[68:71]
	v_mfma_f32_16x16x32_bf16 v[64:67], v[208:211], v[192:195], v[64:67]
	v_mfma_f32_16x16x32_bf16 v[116:119], v[204:207], v[164:167], v[116:119]
	v_mfma_f32_16x16x32_bf16 v[112:115], v[212:215], v[164:167], v[112:115]
	v_mfma_f32_16x16x32_bf16 v[100:103], v[204:207], v[180:183], v[100:103]
	v_mfma_f32_16x16x32_bf16 v[96:99], v[212:215], v[180:183], v[96:99]
	v_mfma_f32_16x16x32_bf16 v[84:87], v[204:207], v[188:191], v[84:87]
	v_mfma_f32_16x16x32_bf16 v[80:83], v[212:215], v[188:191], v[80:83]
	v_mfma_f32_16x16x32_bf16 v[68:71], v[204:207], v[196:199], v[68:71]
	v_mfma_f32_16x16x32_bf16 v[64:67], v[212:215], v[196:199], v[64:67]
	s_setprio 0
	s_mov_b32 m0, s21
	v_lshl_add_u64 v[220:221], s[16:17], 0, v[168:169]
	s_barrier
	ds_read_b128 v[158:161], v142 offset:16384
	v_xor_b32_e32 v199, 64, v142
	ds_read_b128 v[164:167], v199 offset:16384
	ds_read_b128 v[176:179], v142 offset:18432
	ds_read_b128 v[180:183], v199 offset:18432
	ds_read_b128 v[184:187], v142 offset:20480
	ds_read_b128 v[188:191], v199 offset:20480
	ds_read_b128 v[192:195], v142 offset:22528
	ds_read_b128 v[196:199], v199 offset:22528
	global_load_lds_dwordx4 v[220:221], off
	v_lshl_add_u64 v[222:223], s[16:17], 0, v[172:173]
	s_mov_b32 m0, s22
	s_nop 0
	global_load_lds_dwordx4 v[222:223], off
	s_barrier
	s_waitcnt lgkmcnt(0)
	s_setprio 1
	s_waitcnt lgkmcnt(0)
	v_mfma_f32_16x16x32_bf16 v[60:63], v[136:139], v[158:161], v[60:63]
	v_mfma_f32_16x16x32_bf16 v[56:59], v[150:153], v[158:161], v[56:59]
	v_mfma_f32_16x16x32_bf16 v[44:47], v[136:139], v[176:179], v[44:47]
	v_mfma_f32_16x16x32_bf16 v[40:43], v[150:153], v[176:179], v[40:43]
	v_mfma_f32_16x16x32_bf16 v[28:31], v[136:139], v[184:187], v[28:31]
	v_mfma_f32_16x16x32_bf16 v[24:27], v[150:153], v[184:187], v[24:27]
	v_mfma_f32_16x16x32_bf16 v[12:15], v[136:139], v[192:195], v[12:15]
	v_mfma_f32_16x16x32_bf16 v[8:11], v[150:153], v[192:195], v[8:11]
	v_mfma_f32_16x16x32_bf16 v[60:63], v[146:149], v[164:167], v[60:63]
	v_mfma_f32_16x16x32_bf16 v[56:59], v[154:157], v[164:167], v[56:59]
	v_mfma_f32_16x16x32_bf16 v[44:47], v[146:149], v[180:183], v[44:47]
	v_mfma_f32_16x16x32_bf16 v[40:43], v[154:157], v[180:183], v[40:43]
	v_mfma_f32_16x16x32_bf16 v[28:31], v[146:149], v[188:191], v[28:31]
	v_mfma_f32_16x16x32_bf16 v[24:27], v[154:157], v[188:191], v[24:27]
	v_mfma_f32_16x16x32_bf16 v[12:15], v[146:149], v[196:199], v[12:15]
	v_mfma_f32_16x16x32_bf16 v[8:11], v[154:157], v[196:199], v[8:11]
	s_setprio 0
	s_barrier
	s_add_u32 s42, s14, 0x160000
	s_addc_u32 s43, s15, 0
	s_add_i32 s44, s34, s20
	v_lshl_add_u64 v[136:137], s[42:43], 0, v[170:171]
	s_mov_b32 m0, s44
	s_nop 0
	global_load_lds_dwordx4 v[136:137], off
	v_lshl_add_u64 v[136:137], s[42:43], 0, v[174:175]
	s_add_i32 m0, s44, 0x2000
	s_nop 0
	global_load_lds_dwordx4 v[136:137], off
	s_waitcnt vmcnt(6)
	s_barrier
	s_setprio 1
	v_mfma_f32_16x16x32_bf16 v[52:55], v[200:203], v[158:161], v[52:55]
	v_mfma_f32_16x16x32_bf16 v[48:51], v[208:211], v[158:161], v[48:51]
	v_mfma_f32_16x16x32_bf16 v[36:39], v[200:203], v[176:179], v[36:39]
	v_mfma_f32_16x16x32_bf16 v[32:35], v[208:211], v[176:179], v[32:35]
	v_mfma_f32_16x16x32_bf16 v[20:23], v[200:203], v[184:187], v[20:23]
	v_mfma_f32_16x16x32_bf16 v[16:19], v[208:211], v[184:187], v[16:19]
	v_mfma_f32_16x16x32_bf16 v[4:7], v[200:203], v[192:195], v[4:7]
	v_mfma_f32_16x16x32_bf16 v[0:3], v[208:211], v[192:195], v[0:3]
	v_mfma_f32_16x16x32_bf16 v[52:55], v[204:207], v[164:167], v[52:55]
	v_mfma_f32_16x16x32_bf16 v[48:51], v[212:215], v[164:167], v[48:51]
	v_mfma_f32_16x16x32_bf16 v[36:39], v[204:207], v[180:183], v[36:39]
	v_mfma_f32_16x16x32_bf16 v[32:35], v[212:215], v[180:183], v[32:35]
	v_mfma_f32_16x16x32_bf16 v[20:23], v[204:207], v[188:191], v[20:23]
	v_mfma_f32_16x16x32_bf16 v[16:19], v[212:215], v[188:191], v[16:19]
	v_mfma_f32_16x16x32_bf16 v[4:7], v[204:207], v[196:199], v[4:7]
	v_mfma_f32_16x16x32_bf16 v[0:3], v[212:215], v[196:199], v[0:3]
	s_setprio 0
	s_add_i32 s42, 0, 0x18000
	v_add_u32_e32 v145, s42, v140
	s_barrier
	ds_read_b128 v[136:139], v145
	v_xor_b32_e32 v157, 64, v145
	ds_read_b128 v[146:149], v157
	ds_read_b128 v[150:153], v145 offset:2048
	ds_read_b128 v[154:157], v157 offset:2048
	s_add_u32 s16, s16, 0x160000
	s_addc_u32 s17, s17, 0
	s_mov_b32 m0, s23
	v_lshl_add_u64 v[200:201], s[16:17], 0, v[168:169]
	ds_read_b128 v[158:161], v142 offset:32768
	v_xor_b32_e32 v199, 64, v142
	ds_read_b128 v[164:167], v199 offset:32768
	ds_read_b128 v[176:179], v142 offset:34816
	ds_read_b128 v[180:183], v199 offset:34816
	ds_read_b128 v[184:187], v142 offset:36864
	ds_read_b128 v[188:191], v199 offset:36864
	ds_read_b128 v[192:195], v142 offset:38912
	ds_read_b128 v[196:199], v199 offset:38912
	global_load_lds_dwordx4 v[200:201], off
	v_lshl_add_u64 v[200:201], s[16:17], 0, v[172:173]
	s_mov_b32 m0, s24
	s_nop 0
	global_load_lds_dwordx4 v[200:201], off
	s_waitcnt lgkmcnt(8)
	s_barrier
	s_waitcnt lgkmcnt(0)
	s_setprio 1
	s_waitcnt lgkmcnt(0)
	v_mfma_f32_16x16x32_bf16 v[124:127], v[136:139], v[158:161], v[124:127]
	v_mfma_f32_16x16x32_bf16 v[120:123], v[150:153], v[158:161], v[120:123]
	v_mfma_f32_16x16x32_bf16 v[108:111], v[136:139], v[176:179], v[108:111]
	v_mfma_f32_16x16x32_bf16 v[104:107], v[150:153], v[176:179], v[104:107]
	v_mfma_f32_16x16x32_bf16 v[92:95], v[136:139], v[184:187], v[92:95]
	v_mfma_f32_16x16x32_bf16 v[88:91], v[150:153], v[184:187], v[88:91]
	v_mfma_f32_16x16x32_bf16 v[76:79], v[136:139], v[192:195], v[76:79]
	v_mfma_f32_16x16x32_bf16 v[72:75], v[150:153], v[192:195], v[72:75]
	v_mfma_f32_16x16x32_bf16 v[124:127], v[146:149], v[164:167], v[124:127]
	v_mfma_f32_16x16x32_bf16 v[120:123], v[154:157], v[164:167], v[120:123]
	v_mfma_f32_16x16x32_bf16 v[108:111], v[146:149], v[180:183], v[108:111]
	v_mfma_f32_16x16x32_bf16 v[104:107], v[154:157], v[180:183], v[104:107]
	v_mfma_f32_16x16x32_bf16 v[92:95], v[146:149], v[188:191], v[92:95]
	v_mfma_f32_16x16x32_bf16 v[88:91], v[154:157], v[188:191], v[88:91]
	v_mfma_f32_16x16x32_bf16 v[76:79], v[146:149], v[196:199], v[76:79]
	v_mfma_f32_16x16x32_bf16 v[72:75], v[154:157], v[196:199], v[72:75]
	s_setprio 0
	s_barrier
	s_add_i32 s16, 0, 0x1c000
	s_add_i32 s17, s42, s20
	v_add_u32_e32 v145, s16, v140
	v_lshl_add_u64 v[216:217], v[216:217], 0, s[12:13]
	s_mov_b32 m0, s17
	ds_read_b128 v[200:203], v145
	v_xor_b32_e32 v215, 64, v145
	ds_read_b128 v[204:207], v215
	ds_read_b128 v[208:211], v145 offset:2048
	ds_read_b128 v[212:215], v215 offset:2048
	global_load_lds_dwordx4 v[216:217], off
	v_lshl_add_u64 v[216:217], v[218:219], 0, s[12:13]
	s_add_i32 m0, s17, 0x2000
	s_nop 0
	global_load_lds_dwordx4 v[216:217], off
	s_barrier
	s_waitcnt lgkmcnt(0)
	s_setprio 1
	s_waitcnt lgkmcnt(0)
	v_mfma_f32_16x16x32_bf16 v[116:119], v[200:203], v[158:161], v[116:119]
	v_mfma_f32_16x16x32_bf16 v[112:115], v[208:211], v[158:161], v[112:115]
	v_mfma_f32_16x16x32_bf16 v[100:103], v[200:203], v[176:179], v[100:103]
	v_mfma_f32_16x16x32_bf16 v[96:99], v[208:211], v[176:179], v[96:99]
	v_mfma_f32_16x16x32_bf16 v[84:87], v[200:203], v[184:187], v[84:87]
	v_mfma_f32_16x16x32_bf16 v[80:83], v[208:211], v[184:187], v[80:83]
	v_mfma_f32_16x16x32_bf16 v[68:71], v[200:203], v[192:195], v[68:71]
	v_mfma_f32_16x16x32_bf16 v[64:67], v[208:211], v[192:195], v[64:67]
	v_mfma_f32_16x16x32_bf16 v[116:119], v[204:207], v[164:167], v[116:119]
	v_mfma_f32_16x16x32_bf16 v[112:115], v[212:215], v[164:167], v[112:115]
	v_mfma_f32_16x16x32_bf16 v[100:103], v[204:207], v[180:183], v[100:103]
	v_mfma_f32_16x16x32_bf16 v[96:99], v[212:215], v[180:183], v[96:99]
	v_mfma_f32_16x16x32_bf16 v[84:87], v[204:207], v[188:191], v[84:87]
	v_mfma_f32_16x16x32_bf16 v[80:83], v[212:215], v[188:191], v[80:83]
	v_mfma_f32_16x16x32_bf16 v[68:71], v[204:207], v[196:199], v[68:71]
	v_mfma_f32_16x16x32_bf16 v[64:67], v[212:215], v[196:199], v[64:67]
	s_setprio 0
	s_mov_b32 m0, s28
	v_lshl_add_u64 v[216:217], v[220:221], 0, s[12:13]
	s_barrier
	ds_read_b128 v[158:161], v142 offset:49152
	v_xor_b32_e32 v199, 64, v142
	ds_read_b128 v[164:167], v199 offset:49152
	ds_read_b128 v[176:179], v142 offset:51200
	ds_read_b128 v[180:183], v199 offset:51200
	ds_read_b128 v[184:187], v142 offset:53248
	ds_read_b128 v[188:191], v199 offset:53248
	ds_read_b128 v[192:195], v142 offset:55296
	ds_read_b128 v[196:199], v199 offset:55296
	global_load_lds_dwordx4 v[216:217], off
	v_lshl_add_u64 v[216:217], v[222:223], 0, s[12:13]
	s_mov_b32 m0, s29
	s_nop 0
	global_load_lds_dwordx4 v[216:217], off
	s_barrier
	s_waitcnt lgkmcnt(0)
	s_setprio 1
	s_waitcnt lgkmcnt(0)
	v_mfma_f32_16x16x32_bf16 v[60:63], v[136:139], v[158:161], v[60:63]
	v_mfma_f32_16x16x32_bf16 v[56:59], v[150:153], v[158:161], v[56:59]
	v_mfma_f32_16x16x32_bf16 v[44:47], v[136:139], v[176:179], v[44:47]
	v_mfma_f32_16x16x32_bf16 v[40:43], v[150:153], v[176:179], v[40:43]
	v_mfma_f32_16x16x32_bf16 v[28:31], v[136:139], v[184:187], v[28:31]
	v_mfma_f32_16x16x32_bf16 v[24:27], v[150:153], v[184:187], v[24:27]
	v_mfma_f32_16x16x32_bf16 v[12:15], v[136:139], v[192:195], v[12:15]
	v_mfma_f32_16x16x32_bf16 v[8:11], v[150:153], v[192:195], v[8:11]
	v_mfma_f32_16x16x32_bf16 v[60:63], v[146:149], v[164:167], v[60:63]
	v_mfma_f32_16x16x32_bf16 v[56:59], v[154:157], v[164:167], v[56:59]
	v_mfma_f32_16x16x32_bf16 v[44:47], v[146:149], v[180:183], v[44:47]
	v_mfma_f32_16x16x32_bf16 v[40:43], v[154:157], v[180:183], v[40:43]
	v_mfma_f32_16x16x32_bf16 v[28:31], v[146:149], v[188:191], v[28:31]
	v_mfma_f32_16x16x32_bf16 v[24:27], v[154:157], v[188:191], v[24:27]
	v_mfma_f32_16x16x32_bf16 v[12:15], v[146:149], v[196:199], v[12:15]
	v_mfma_f32_16x16x32_bf16 v[8:11], v[154:157], v[196:199], v[8:11]
	s_setprio 0
	s_barrier
	s_add_u32 s14, s14, 0x160080
	s_addc_u32 s15, s15, 0
	s_add_i32 s16, s16, s20
	v_lshl_add_u64 v[136:137], s[14:15], 0, v[170:171]
	s_mov_b32 m0, s16
	s_nop 0
	global_load_lds_dwordx4 v[136:137], off
	v_lshl_add_u64 v[136:137], s[14:15], 0, v[174:175]
	s_add_i32 m0, s16, 0x2000
	s_nop 0
	global_load_lds_dwordx4 v[136:137], off
	s_waitcnt vmcnt(6)
	s_barrier
	s_setprio 1
	v_mfma_f32_16x16x32_bf16 v[52:55], v[200:203], v[158:161], v[52:55]
	v_mfma_f32_16x16x32_bf16 v[48:51], v[208:211], v[158:161], v[48:51]
	v_mfma_f32_16x16x32_bf16 v[36:39], v[200:203], v[176:179], v[36:39]
	v_mfma_f32_16x16x32_bf16 v[32:35], v[208:211], v[176:179], v[32:35]
	v_mfma_f32_16x16x32_bf16 v[20:23], v[200:203], v[184:187], v[20:23]
	v_mfma_f32_16x16x32_bf16 v[16:19], v[208:211], v[184:187], v[16:19]
	v_mfma_f32_16x16x32_bf16 v[4:7], v[200:203], v[192:195], v[4:7]
	v_mfma_f32_16x16x32_bf16 v[0:3], v[208:211], v[192:195], v[0:3]
	v_mfma_f32_16x16x32_bf16 v[52:55], v[204:207], v[164:167], v[52:55]
	v_mfma_f32_16x16x32_bf16 v[48:51], v[212:215], v[164:167], v[48:51]
	v_mfma_f32_16x16x32_bf16 v[36:39], v[204:207], v[180:183], v[36:39]
	v_mfma_f32_16x16x32_bf16 v[32:35], v[212:215], v[180:183], v[32:35]
	v_mfma_f32_16x16x32_bf16 v[20:23], v[204:207], v[188:191], v[20:23]
	v_mfma_f32_16x16x32_bf16 v[16:19], v[212:215], v[188:191], v[16:19]
	v_mfma_f32_16x16x32_bf16 v[4:7], v[204:207], v[196:199], v[4:7]
	v_mfma_f32_16x16x32_bf16 v[0:3], v[212:215], v[196:199], v[0:3]
	s_setprio 0
	s_add_i32 s41, s41, 2
	s_add_u32 s0, s0, 0x100
	s_addc_u32 s1, s1, 0
	s_add_u32 s39, s39, 0x100
	s_addc_u32 s40, s40, 0
	s_cmpk_gt_u32 s41, 0x55
	s_barrier
	s_cbranch_scc0 .LBB0_985
	v_lshl_add_u32 v217, s38, 8, v163
	v_add_u32_e32 v217, s26, v217
	v_lshlrev_b32_e32 v208, 2, v217
	v_lshl_add_u32 v214, v225, 3, s27
	v_lshl_add_u32 v214, s37, 8, v214
	v_lshl_add_u32 v209, v217, 11, v214
	v_lshlrev_b32_e32 v209, 1, v209
	v_lshlrev_b32_e32 v210, 1, v209
	v_lshl_add_u32 v217, v225, 4, v163
	v_xor_b32_e32 v215, 16, v217
	v_lshlrev_b32_e32 v215, 2, v215
	v_xor_b32_e32 v216, 32, v217
	v_lshlrev_b32_e32 v216, 2, v216
	v_add_u32_e32 v211, 0x0, v209
	global_load_dwordx4 v[176:179], v211, s[80:81]
	global_load_dwordx4 v[180:183], v211, s[80:81] offset:256
	v_add_u32_e32 v211, 0x10000, v209
	global_load_dwordx4 v[192:195], v211, s[80:81]
	global_load_dwordx4 v[196:199], v211, s[80:81] offset:256
	s_waitcnt vmcnt(2)
	v_lshlrev_b32_e32 v184, 16, v176
	v_and_b32_e32 v185, 0xffff0000, v176
	v_lshlrev_b32_e32 v186, 16, v177
	v_and_b32_e32 v187, 0xffff0000, v177
	v_lshlrev_b32_e32 v188, 16, v178
	v_and_b32_e32 v189, 0xffff0000, v178
	v_lshlrev_b32_e32 v190, 16, v179
	v_and_b32_e32 v191, 0xffff0000, v179
	v_pk_add_f32 v[124:125], v[124:125], v[184:185]
	v_pk_add_f32 v[126:127], v[126:127], v[186:187]
	v_pk_add_f32 v[120:121], v[120:121], v[188:189]
	v_pk_add_f32 v[122:123], v[122:123], v[190:191]
	v_mul_f32_e32 v213, v124, v124
	v_fmac_f32_e32 v213, v125, v125
	v_fmac_f32_e32 v213, v126, v126
	v_fmac_f32_e32 v213, v127, v127
	v_fmac_f32_e32 v213, v120, v120
	v_fmac_f32_e32 v213, v121, v121
	v_fmac_f32_e32 v213, v122, v122
	v_fmac_f32_e32 v213, v123, v123
	v_add_u32_e32 v212, 0x0, v210
	global_store_dwordx4 v212, v[124:127], s[90:91]
	global_store_dwordx4 v212, v[120:123], s[90:91] offset:16
	v_lshlrev_b32_e32 v184, 16, v180
	v_and_b32_e32 v185, 0xffff0000, v180
	v_lshlrev_b32_e32 v186, 16, v181
	v_and_b32_e32 v187, 0xffff0000, v181
	v_lshlrev_b32_e32 v188, 16, v182
	v_and_b32_e32 v189, 0xffff0000, v182
	v_lshlrev_b32_e32 v190, 16, v183
	v_and_b32_e32 v191, 0xffff0000, v183
	v_pk_add_f32 v[116:117], v[116:117], v[184:185]
	v_pk_add_f32 v[118:119], v[118:119], v[186:187]
	v_pk_add_f32 v[112:113], v[112:113], v[188:189]
	v_pk_add_f32 v[114:115], v[114:115], v[190:191]
	v_fmac_f32_e32 v213, v116, v116
	v_fmac_f32_e32 v213, v117, v117
	v_fmac_f32_e32 v213, v118, v118
	v_fmac_f32_e32 v213, v119, v119
	v_fmac_f32_e32 v213, v112, v112
	v_fmac_f32_e32 v213, v113, v113
	v_fmac_f32_e32 v213, v114, v114
	v_fmac_f32_e32 v213, v115, v115
	global_store_dwordx4 v212, v[116:119], s[90:91] offset:512
	global_store_dwordx4 v212, v[112:115], s[90:91] offset:528
	ds_bpermute_b32 v214, v215, v213
	s_waitcnt lgkmcnt(0)
	v_add_f32_e32 v213, v213, v214
	ds_bpermute_b32 v214, v216, v213
	s_waitcnt lgkmcnt(0)
	v_add_f32_e32 v213, v213, v214
	s_mov_b64 exec, 0xffff
	global_atomic_add_f32 v208, v213, s[10:11]
	s_mov_b64 exec, -1
	v_add_u32_e32 v211, 0x20000, v209
	global_load_dwordx4 v[176:179], v211, s[80:81]
	global_load_dwordx4 v[180:183], v211, s[80:81] offset:256
	s_waitcnt vmcnt(7)
	v_lshlrev_b32_e32 v200, 16, v192
	v_and_b32_e32 v201, 0xffff0000, v192
	v_lshlrev_b32_e32 v202, 16, v193
	v_and_b32_e32 v203, 0xffff0000, v193
	v_lshlrev_b32_e32 v204, 16, v194
	v_and_b32_e32 v205, 0xffff0000, v194
	v_lshlrev_b32_e32 v206, 16, v195
	v_and_b32_e32 v207, 0xffff0000, v195
	v_pk_add_f32 v[108:109], v[108:109], v[200:201]
	v_pk_add_f32 v[110:111], v[110:111], v[202:203]
	v_pk_add_f32 v[104:105], v[104:105], v[204:205]
	v_pk_add_f32 v[106:107], v[106:107], v[206:207]
	v_mul_f32_e32 v213, v108, v108
	v_fmac_f32_e32 v213, v109, v109
	v_fmac_f32_e32 v213, v110, v110
	v_fmac_f32_e32 v213, v111, v111
	v_fmac_f32_e32 v213, v104, v104
	v_fmac_f32_e32 v213, v105, v105
	v_fmac_f32_e32 v213, v106, v106
	v_fmac_f32_e32 v213, v107, v107
	v_add_u32_e32 v212, 0x20000, v210
	global_store_dwordx4 v212, v[108:111], s[90:91]
	global_store_dwordx4 v212, v[104:107], s[90:91] offset:16
	v_lshlrev_b32_e32 v200, 16, v196
	v_and_b32_e32 v201, 0xffff0000, v196
	v_lshlrev_b32_e32 v202, 16, v197
	v_and_b32_e32 v203, 0xffff0000, v197
	v_lshlrev_b32_e32 v204, 16, v198
	v_and_b32_e32 v205, 0xffff0000, v198
	v_lshlrev_b32_e32 v206, 16, v199
	v_and_b32_e32 v207, 0xffff0000, v199
	v_pk_add_f32 v[100:101], v[100:101], v[200:201]
	v_pk_add_f32 v[102:103], v[102:103], v[202:203]
	v_pk_add_f32 v[96:97], v[96:97], v[204:205]
	v_pk_add_f32 v[98:99], v[98:99], v[206:207]
	v_fmac_f32_e32 v213, v100, v100
	v_fmac_f32_e32 v213, v101, v101
	v_fmac_f32_e32 v213, v102, v102
	v_fmac_f32_e32 v213, v103, v103
	v_fmac_f32_e32 v213, v96, v96
	v_fmac_f32_e32 v213, v97, v97
	v_fmac_f32_e32 v213, v98, v98
	v_fmac_f32_e32 v213, v99, v99
	global_store_dwordx4 v212, v[100:103], s[90:91] offset:512
	global_store_dwordx4 v212, v[96:99], s[90:91] offset:528
	ds_bpermute_b32 v214, v215, v213
	s_waitcnt lgkmcnt(0)
	v_add_f32_e32 v213, v213, v214
	ds_bpermute_b32 v214, v216, v213
	s_waitcnt lgkmcnt(0)
	v_add_f32_e32 v213, v213, v214
	s_mov_b64 exec, 0xffff
	global_atomic_add_f32 v208, v213, s[10:11] offset:64
	s_mov_b64 exec, -1
	v_add_u32_e32 v211, 0x30000, v209
	global_load_dwordx4 v[192:195], v211, s[80:81]
	global_load_dwordx4 v[196:199], v211, s[80:81] offset:256
	s_waitcnt vmcnt(7)
	v_lshlrev_b32_e32 v184, 16, v176
	v_and_b32_e32 v185, 0xffff0000, v176
	v_lshlrev_b32_e32 v186, 16, v177
	v_and_b32_e32 v187, 0xffff0000, v177
	v_lshlrev_b32_e32 v188, 16, v178
	v_and_b32_e32 v189, 0xffff0000, v178
	v_lshlrev_b32_e32 v190, 16, v179
	v_and_b32_e32 v191, 0xffff0000, v179
	v_pk_add_f32 v[92:93], v[92:93], v[184:185]
	v_pk_add_f32 v[94:95], v[94:95], v[186:187]
	v_pk_add_f32 v[88:89], v[88:89], v[188:189]
	v_pk_add_f32 v[90:91], v[90:91], v[190:191]
	v_mul_f32_e32 v213, v92, v92
	v_fmac_f32_e32 v213, v93, v93
	v_fmac_f32_e32 v213, v94, v94
	v_fmac_f32_e32 v213, v95, v95
	v_fmac_f32_e32 v213, v88, v88
	v_fmac_f32_e32 v213, v89, v89
	v_fmac_f32_e32 v213, v90, v90
	v_fmac_f32_e32 v213, v91, v91
	v_add_u32_e32 v212, 0x40000, v210
	global_store_dwordx4 v212, v[92:95], s[90:91]
	global_store_dwordx4 v212, v[88:91], s[90:91] offset:16
	v_lshlrev_b32_e32 v184, 16, v180
	v_and_b32_e32 v185, 0xffff0000, v180
	v_lshlrev_b32_e32 v186, 16, v181
	v_and_b32_e32 v187, 0xffff0000, v181
	v_lshlrev_b32_e32 v188, 16, v182
	v_and_b32_e32 v189, 0xffff0000, v182
	v_lshlrev_b32_e32 v190, 16, v183
	v_and_b32_e32 v191, 0xffff0000, v183
	v_pk_add_f32 v[84:85], v[84:85], v[184:185]
	v_pk_add_f32 v[86:87], v[86:87], v[186:187]
	v_pk_add_f32 v[80:81], v[80:81], v[188:189]
	v_pk_add_f32 v[82:83], v[82:83], v[190:191]
	v_fmac_f32_e32 v213, v84, v84
	v_fmac_f32_e32 v213, v85, v85
	v_fmac_f32_e32 v213, v86, v86
	v_fmac_f32_e32 v213, v87, v87
	v_fmac_f32_e32 v213, v80, v80
	v_fmac_f32_e32 v213, v81, v81
	v_fmac_f32_e32 v213, v82, v82
	v_fmac_f32_e32 v213, v83, v83
	global_store_dwordx4 v212, v[84:87], s[90:91] offset:512
	global_store_dwordx4 v212, v[80:83], s[90:91] offset:528
	ds_bpermute_b32 v214, v215, v213
	s_waitcnt lgkmcnt(0)
	v_add_f32_e32 v213, v213, v214
	ds_bpermute_b32 v214, v216, v213
	s_waitcnt lgkmcnt(0)
	v_add_f32_e32 v213, v213, v214
	s_mov_b64 exec, 0xffff
	global_atomic_add_f32 v208, v213, s[10:11] offset:128
	s_mov_b64 exec, -1
	v_add_u32_e32 v211, 0x80000, v209
	global_load_dwordx4 v[176:179], v211, s[80:81]
	global_load_dwordx4 v[180:183], v211, s[80:81] offset:256
	s_waitcnt vmcnt(7)
	v_lshlrev_b32_e32 v200, 16, v192
	v_and_b32_e32 v201, 0xffff0000, v192
	v_lshlrev_b32_e32 v202, 16, v193
	v_and_b32_e32 v203, 0xffff0000, v193
	v_lshlrev_b32_e32 v204, 16, v194
	v_and_b32_e32 v205, 0xffff0000, v194
	v_lshlrev_b32_e32 v206, 16, v195
	v_and_b32_e32 v207, 0xffff0000, v195
	v_pk_add_f32 v[76:77], v[76:77], v[200:201]
	v_pk_add_f32 v[78:79], v[78:79], v[202:203]
	v_pk_add_f32 v[72:73], v[72:73], v[204:205]
	v_pk_add_f32 v[74:75], v[74:75], v[206:207]
	v_mul_f32_e32 v213, v76, v76
	v_fmac_f32_e32 v213, v77, v77
	v_fmac_f32_e32 v213, v78, v78
	v_fmac_f32_e32 v213, v79, v79
	v_fmac_f32_e32 v213, v72, v72
	v_fmac_f32_e32 v213, v73, v73
	v_fmac_f32_e32 v213, v74, v74
	v_fmac_f32_e32 v213, v75, v75
	v_add_u32_e32 v212, 0x60000, v210
	global_store_dwordx4 v212, v[76:79], s[90:91]
	global_store_dwordx4 v212, v[72:75], s[90:91] offset:16
	v_lshlrev_b32_e32 v200, 16, v196
	v_and_b32_e32 v201, 0xffff0000, v196
	v_lshlrev_b32_e32 v202, 16, v197
	v_and_b32_e32 v203, 0xffff0000, v197
	v_lshlrev_b32_e32 v204, 16, v198
	v_and_b32_e32 v205, 0xffff0000, v198
	v_lshlrev_b32_e32 v206, 16, v199
	v_and_b32_e32 v207, 0xffff0000, v199
	v_pk_add_f32 v[68:69], v[68:69], v[200:201]
	v_pk_add_f32 v[70:71], v[70:71], v[202:203]
	v_pk_add_f32 v[64:65], v[64:65], v[204:205]
	v_pk_add_f32 v[66:67], v[66:67], v[206:207]
	v_fmac_f32_e32 v213, v68, v68
	v_fmac_f32_e32 v213, v69, v69
	v_fmac_f32_e32 v213, v70, v70
	v_fmac_f32_e32 v213, v71, v71
	v_fmac_f32_e32 v213, v64, v64
	v_fmac_f32_e32 v213, v65, v65
	v_fmac_f32_e32 v213, v66, v66
	v_fmac_f32_e32 v213, v67, v67
	global_store_dwordx4 v212, v[68:71], s[90:91] offset:512
	global_store_dwordx4 v212, v[64:67], s[90:91] offset:528
	ds_bpermute_b32 v214, v215, v213
	s_waitcnt lgkmcnt(0)
	v_add_f32_e32 v213, v213, v214
	ds_bpermute_b32 v214, v216, v213
	s_waitcnt lgkmcnt(0)
	v_add_f32_e32 v213, v213, v214
	s_mov_b64 exec, 0xffff
	global_atomic_add_f32 v208, v213, s[10:11] offset:192
	s_mov_b64 exec, -1
	v_add_u32_e32 v211, 0x90000, v209
	global_load_dwordx4 v[192:195], v211, s[80:81]
	global_load_dwordx4 v[196:199], v211, s[80:81] offset:256
	s_waitcnt vmcnt(7)
	v_lshlrev_b32_e32 v184, 16, v176
	v_and_b32_e32 v185, 0xffff0000, v176
	v_lshlrev_b32_e32 v186, 16, v177
	v_and_b32_e32 v187, 0xffff0000, v177
	v_lshlrev_b32_e32 v188, 16, v178
	v_and_b32_e32 v189, 0xffff0000, v178
	v_lshlrev_b32_e32 v190, 16, v179
	v_and_b32_e32 v191, 0xffff0000, v179
	v_pk_add_f32 v[60:61], v[60:61], v[184:185]
	v_pk_add_f32 v[62:63], v[62:63], v[186:187]
	v_pk_add_f32 v[56:57], v[56:57], v[188:189]
	v_pk_add_f32 v[58:59], v[58:59], v[190:191]
	v_mul_f32_e32 v213, v60, v60
	v_fmac_f32_e32 v213, v61, v61
	v_fmac_f32_e32 v213, v62, v62
	v_fmac_f32_e32 v213, v63, v63
	v_fmac_f32_e32 v213, v56, v56
	v_fmac_f32_e32 v213, v57, v57
	v_fmac_f32_e32 v213, v58, v58
	v_fmac_f32_e32 v213, v59, v59
	v_add_u32_e32 v212, 0x100000, v210
	global_store_dwordx4 v212, v[60:63], s[90:91]
	global_store_dwordx4 v212, v[56:59], s[90:91] offset:16
	v_lshlrev_b32_e32 v184, 16, v180
	v_and_b32_e32 v185, 0xffff0000, v180
	v_lshlrev_b32_e32 v186, 16, v181
	v_and_b32_e32 v187, 0xffff0000, v181
	v_lshlrev_b32_e32 v188, 16, v182
	v_and_b32_e32 v189, 0xffff0000, v182
	v_lshlrev_b32_e32 v190, 16, v183
	v_and_b32_e32 v191, 0xffff0000, v183
	v_pk_add_f32 v[52:53], v[52:53], v[184:185]
	v_pk_add_f32 v[54:55], v[54:55], v[186:187]
	v_pk_add_f32 v[48:49], v[48:49], v[188:189]
	v_pk_add_f32 v[50:51], v[50:51], v[190:191]
	v_fmac_f32_e32 v213, v52, v52
	v_fmac_f32_e32 v213, v53, v53
	v_fmac_f32_e32 v213, v54, v54
	v_fmac_f32_e32 v213, v55, v55
	v_fmac_f32_e32 v213, v48, v48
	v_fmac_f32_e32 v213, v49, v49
	v_fmac_f32_e32 v213, v50, v50
	v_fmac_f32_e32 v213, v51, v51
	global_store_dwordx4 v212, v[52:55], s[90:91] offset:512
	global_store_dwordx4 v212, v[48:51], s[90:91] offset:528
	ds_bpermute_b32 v214, v215, v213
	s_waitcnt lgkmcnt(0)
	v_add_f32_e32 v213, v213, v214
	ds_bpermute_b32 v214, v216, v213
	s_waitcnt lgkmcnt(0)
	v_add_f32_e32 v213, v213, v214
	s_mov_b64 exec, 0xffff
	global_atomic_add_f32 v208, v213, s[10:11] offset:512
	s_mov_b64 exec, -1
	v_add_u32_e32 v211, 0xa0000, v209
	global_load_dwordx4 v[176:179], v211, s[80:81]
	global_load_dwordx4 v[180:183], v211, s[80:81] offset:256
	s_waitcnt vmcnt(7)
	v_lshlrev_b32_e32 v200, 16, v192
	v_and_b32_e32 v201, 0xffff0000, v192
	v_lshlrev_b32_e32 v202, 16, v193
	v_and_b32_e32 v203, 0xffff0000, v193
	v_lshlrev_b32_e32 v204, 16, v194
	v_and_b32_e32 v205, 0xffff0000, v194
	v_lshlrev_b32_e32 v206, 16, v195
	v_and_b32_e32 v207, 0xffff0000, v195
	v_pk_add_f32 v[44:45], v[44:45], v[200:201]
	v_pk_add_f32 v[46:47], v[46:47], v[202:203]
	v_pk_add_f32 v[40:41], v[40:41], v[204:205]
	v_pk_add_f32 v[42:43], v[42:43], v[206:207]
	v_mul_f32_e32 v213, v44, v44
	v_fmac_f32_e32 v213, v45, v45
	v_fmac_f32_e32 v213, v46, v46
	v_fmac_f32_e32 v213, v47, v47
	v_fmac_f32_e32 v213, v40, v40
	v_fmac_f32_e32 v213, v41, v41
	v_fmac_f32_e32 v213, v42, v42
	v_fmac_f32_e32 v213, v43, v43
	v_add_u32_e32 v212, 0x120000, v210
	global_store_dwordx4 v212, v[44:47], s[90:91]
	global_store_dwordx4 v212, v[40:43], s[90:91] offset:16
	v_lshlrev_b32_e32 v200, 16, v196
	v_and_b32_e32 v201, 0xffff0000, v196
	v_lshlrev_b32_e32 v202, 16, v197
	v_and_b32_e32 v203, 0xffff0000, v197
	v_lshlrev_b32_e32 v204, 16, v198
	v_and_b32_e32 v205, 0xffff0000, v198
	v_lshlrev_b32_e32 v206, 16, v199
	v_and_b32_e32 v207, 0xffff0000, v199
	v_pk_add_f32 v[36:37], v[36:37], v[200:201]
	v_pk_add_f32 v[38:39], v[38:39], v[202:203]
	v_pk_add_f32 v[32:33], v[32:33], v[204:205]
	v_pk_add_f32 v[34:35], v[34:35], v[206:207]
	v_fmac_f32_e32 v213, v36, v36
	v_fmac_f32_e32 v213, v37, v37
	v_fmac_f32_e32 v213, v38, v38
	v_fmac_f32_e32 v213, v39, v39
	v_fmac_f32_e32 v213, v32, v32
	v_fmac_f32_e32 v213, v33, v33
	v_fmac_f32_e32 v213, v34, v34
	v_fmac_f32_e32 v213, v35, v35
	global_store_dwordx4 v212, v[36:39], s[90:91] offset:512
	global_store_dwordx4 v212, v[32:35], s[90:91] offset:528
	ds_bpermute_b32 v214, v215, v213
	s_waitcnt lgkmcnt(0)
	v_add_f32_e32 v213, v213, v214
	ds_bpermute_b32 v214, v216, v213
	s_waitcnt lgkmcnt(0)
	v_add_f32_e32 v213, v213, v214
	s_mov_b64 exec, 0xffff
	global_atomic_add_f32 v208, v213, s[10:11] offset:576
	s_mov_b64 exec, -1
	v_add_u32_e32 v211, 0xb0000, v209
	global_load_dwordx4 v[192:195], v211, s[80:81]
	global_load_dwordx4 v[196:199], v211, s[80:81] offset:256
	s_waitcnt vmcnt(7)
	v_lshlrev_b32_e32 v184, 16, v176
	v_and_b32_e32 v185, 0xffff0000, v176
	v_lshlrev_b32_e32 v186, 16, v177
	v_and_b32_e32 v187, 0xffff0000, v177
	v_lshlrev_b32_e32 v188, 16, v178
	v_and_b32_e32 v189, 0xffff0000, v178
	v_lshlrev_b32_e32 v190, 16, v179
	v_and_b32_e32 v191, 0xffff0000, v179
	v_pk_add_f32 v[28:29], v[28:29], v[184:185]
	v_pk_add_f32 v[30:31], v[30:31], v[186:187]
	v_pk_add_f32 v[24:25], v[24:25], v[188:189]
	v_pk_add_f32 v[26:27], v[26:27], v[190:191]
	v_mul_f32_e32 v213, v28, v28
	v_fmac_f32_e32 v213, v29, v29
	v_fmac_f32_e32 v213, v30, v30
	v_fmac_f32_e32 v213, v31, v31
	v_fmac_f32_e32 v213, v24, v24
	v_fmac_f32_e32 v213, v25, v25
	v_fmac_f32_e32 v213, v26, v26
	v_fmac_f32_e32 v213, v27, v27
	v_add_u32_e32 v212, 0x140000, v210
	global_store_dwordx4 v212, v[28:31], s[90:91]
	global_store_dwordx4 v212, v[24:27], s[90:91] offset:16
	v_lshlrev_b32_e32 v184, 16, v180
	v_and_b32_e32 v185, 0xffff0000, v180
	v_lshlrev_b32_e32 v186, 16, v181
	v_and_b32_e32 v187, 0xffff0000, v181
	v_lshlrev_b32_e32 v188, 16, v182
	v_and_b32_e32 v189, 0xffff0000, v182
	v_lshlrev_b32_e32 v190, 16, v183
	v_and_b32_e32 v191, 0xffff0000, v183
	v_pk_add_f32 v[20:21], v[20:21], v[184:185]
	v_pk_add_f32 v[22:23], v[22:23], v[186:187]
	v_pk_add_f32 v[16:17], v[16:17], v[188:189]
	v_pk_add_f32 v[18:19], v[18:19], v[190:191]
	v_fmac_f32_e32 v213, v20, v20
	v_fmac_f32_e32 v213, v21, v21
	v_fmac_f32_e32 v213, v22, v22
	v_fmac_f32_e32 v213, v23, v23
	v_fmac_f32_e32 v213, v16, v16
	v_fmac_f32_e32 v213, v17, v17
	v_fmac_f32_e32 v213, v18, v18
	v_fmac_f32_e32 v213, v19, v19
	global_store_dwordx4 v212, v[20:23], s[90:91] offset:512
	global_store_dwordx4 v212, v[16:19], s[90:91] offset:528
	ds_bpermute_b32 v214, v215, v213
	s_waitcnt lgkmcnt(0)
	v_add_f32_e32 v213, v213, v214
	ds_bpermute_b32 v214, v216, v213
	s_waitcnt lgkmcnt(0)
	v_add_f32_e32 v213, v213, v214
	s_mov_b64 exec, 0xffff
	global_atomic_add_f32 v208, v213, s[10:11] offset:640
	s_mov_b64 exec, -1
	s_waitcnt vmcnt(5)
	v_lshlrev_b32_e32 v200, 16, v192
	v_and_b32_e32 v201, 0xffff0000, v192
	v_lshlrev_b32_e32 v202, 16, v193
	v_and_b32_e32 v203, 0xffff0000, v193
	v_lshlrev_b32_e32 v204, 16, v194
	v_and_b32_e32 v205, 0xffff0000, v194
	v_lshlrev_b32_e32 v206, 16, v195
	v_and_b32_e32 v207, 0xffff0000, v195
	v_pk_add_f32 v[12:13], v[12:13], v[200:201]
	v_pk_add_f32 v[14:15], v[14:15], v[202:203]
	v_pk_add_f32 v[8:9], v[8:9], v[204:205]
	v_pk_add_f32 v[10:11], v[10:11], v[206:207]
	v_mul_f32_e32 v213, v12, v12
	v_fmac_f32_e32 v213, v13, v13
	v_fmac_f32_e32 v213, v14, v14
	v_fmac_f32_e32 v213, v15, v15
	v_fmac_f32_e32 v213, v8, v8
	v_fmac_f32_e32 v213, v9, v9
	v_fmac_f32_e32 v213, v10, v10
	v_fmac_f32_e32 v213, v11, v11
	v_add_u32_e32 v212, 0x160000, v210
	global_store_dwordx4 v212, v[12:15], s[90:91]
	global_store_dwordx4 v212, v[8:11], s[90:91] offset:16
	v_lshlrev_b32_e32 v200, 16, v196
	v_and_b32_e32 v201, 0xffff0000, v196
	v_lshlrev_b32_e32 v202, 16, v197
	v_and_b32_e32 v203, 0xffff0000, v197
	v_lshlrev_b32_e32 v204, 16, v198
	v_and_b32_e32 v205, 0xffff0000, v198
	v_lshlrev_b32_e32 v206, 16, v199
	v_and_b32_e32 v207, 0xffff0000, v199
	v_pk_add_f32 v[4:5], v[4:5], v[200:201]
	v_pk_add_f32 v[6:7], v[6:7], v[202:203]
	v_pk_add_f32 v[0:1], v[0:1], v[204:205]
	v_pk_add_f32 v[2:3], v[2:3], v[206:207]
	v_fmac_f32_e32 v213, v4, v4
	v_fmac_f32_e32 v213, v5, v5
	v_fmac_f32_e32 v213, v6, v6
	v_fmac_f32_e32 v213, v7, v7
	v_fmac_f32_e32 v213, v0, v0
	v_fmac_f32_e32 v213, v1, v1
	v_fmac_f32_e32 v213, v2, v2
	v_fmac_f32_e32 v213, v3, v3
	global_store_dwordx4 v212, v[4:7], s[90:91] offset:512
	global_store_dwordx4 v212, v[0:3], s[90:91] offset:528
	ds_bpermute_b32 v214, v215, v213
	s_waitcnt lgkmcnt(0)
	v_add_f32_e32 v213, v213, v214
	ds_bpermute_b32 v214, v216, v213
	s_waitcnt lgkmcnt(0)
	v_add_f32_e32 v213, v213, v214
	s_mov_b64 exec, 0xffff
	global_atomic_add_f32 v208, v213, s[10:11] offset:704
	s_mov_b64 exec, -1
	s_branch .LBB0_973
